# ffn2_moe main loop hand-scheduled (loads two k-tiles ahead, LDS reads one k-step ahead of the MFMAs)
# speedup vs baseline: 1.2569x; 1.0087x over previous
; DI int otid512() { int t = threadIdx.x; asm volatile("" : "+v"(t)); return t; }
; template <bool GATHER>
; DI void gemm256_main(const h16* __restrict__ A, int lda, const int* __restrict__ idx, int m0,
;                      const h16* __restrict__ B, int ldb, int n0, int K, h16* lds, f16v (&acc)[4][2]) {
;   const int tid = otid512(), lane = tid & 63, wv = tid >> 6, wm = wv >> 2, wn = wv & 3;
;   const int lr = tid >> 1, lc = (tid & 1) * 32;
;   unsigned ao = (unsigned)(GATHER ? idx[m0 + lr] : (m0 + lr)) * (unsigned)lda + lc;
;   unsigned bo = (unsigned)(n0 + lr) * (unsigned)ldb + lc;
;   const h16* ap = A; const h16* bp = B;
;     ...
;   u4v ra[4], rb[4];
;   const int nk = K >> 6;
;   __syncthreads();
; #pragma unroll
;   for (int i = 0; i < 4; ++i) { ra[i] = *(const u4v*)(AP_ + 8 * i); rb[i] = *(const u4v*)(BP_ + 8 * i); }
;   ao += 64; bo += 64;
; #pragma unroll
;   for (int i = 0; i < 4; ++i) { *(u4v*)&lds[lr * LDH + lc + 8 * i] = ra[i]; *(u4v*)&lds[(256 + lr) * LDH + lc + 8 * i] = rb[i]; }
; #pragma unroll
;   for (int i = 0; i < 4; ++i) { ra[i] = *(const u4v*)(AP_ + 8 * i); rb[i] = *(const u4v*)(BP_ + 8 * i); }
;   ao += 64; bo += 64;
;   __syncthreads();
;   for (int kt = 0; kt < nk; ++kt) {
;     const h16* As = lds + (kt & 1) * (512 * LDH);
;     const h16* Bs = As + 256 * LDH;
;     h16* Wn = lds + ((kt & 1) ^ 1) * (512 * LDH);
;     if (kt + 1 < nk) {
; #pragma unroll
;       for (int i = 0; i < 4; ++i) { *(u4v*)&Wn[lr * LDH + lc + 8 * i] = ra[i]; *(u4v*)&Wn[(256 + lr) * LDH + lc + 8 * i] = rb[i]; }
;     }
;     if (kt + 2 < nk) {
; #pragma unroll
;       for (int i = 0; i < 4; ++i) { ra[i] = *(const u4v*)(AP_ + 8 * i); rb[i] = *(const u4v*)(BP_ + 8 * i); }
;       ao += 64; bo += 64;
;     }
; #pragma unroll
;     for (int ks = 0; ks < 4; ++ks) {
;       h8v af[4], bf[2];
; #pragma unroll
;       for (int i = 0; i < 4; ++i) af[i] = *(const h8v*)&As[(wm * 128 + i * 32 + (lane & 31)) * LDH + ks * 16 + 8 * (lane >> 5)];
; #pragma unroll
; DI void phase_ffn2_moe(const Params& p, int bid, int nb, h16* lds) {
;     ...
;   for (int u = bid; u < ntl; u += nb) {
;     const int mt = u >> 2, m0 = mt * 256, n0 = (u & 3) * 256;
;     int e = 0;
; #pragma unroll
;     for (int i = 1; i < 8; ++i) if (m0 >= ps[i]) e = i;
;     f16v acc[4][2]; acc256_zero(acc);
;     gemm256_main<false>(H, 1408, nullptr, m0, w2 + (size_t)e * 1024 * 1408, 1408, n0, 1408, lds, acc);
.LBB0_1571:
	s_lshl_b32 s5, s4, 6
	s_and_b32 s6, s5, 0xffffff00
	s_lshl_b32 s5, s4, 8
	s_and_b32 s5, s5, 0x300
	s_cmp_lt_i32 s6, s2
	s_cselect_b32 s7, 0, 0x160000
	s_cmp_lt_i32 s6, s3
	s_cselect_b32 s7, s7, 0x2c0000
	v_mov_b32_e32 v2, s7
	v_cmp_lt_i32_e32 vcc, s6, v1
	v_mov_b32_e32 v3, v0
	v_readlane_b32 s8, v254, 44
	v_cndmask_b32_e32 v2, v211, v2, vcc
	v_cmp_lt_i32_e32 vcc, s6, v171
	v_readlane_b32 s9, v254, 45
	v_mov_b32_e32 v13, v180
	v_cndmask_b32_e32 v2, v212, v2, vcc
	v_cmp_lt_i32_e32 vcc, s6, v176
	s_movk_i32 s7, 0x580
	v_ashrrev_i32_e32 v52, 1, v13
	v_cndmask_b32_e32 v2, v213, v2, vcc
	v_cmp_lt_i32_e32 vcc, s6, v177
	v_mov_b32_e32 v47, v0
	v_mov_b32_e32 v49, v0
	v_cndmask_b32_e32 v2, v206, v2, vcc
	v_cmp_lt_i32_e32 vcc, s6, v178
	v_mov_b32_e32 v53, v0
	v_mul_lo_u32 v55, v52, s33
	v_cndmask_b32_e32 v2, v214, v2, vcc
	v_lshlrev_b64 v[2:3], 1, v[2:3]
	v_lshl_add_u64 v[162:163], s[8:9], 0, v[2:3]
	v_lshlrev_b32_e32 v2, 5, v13
	v_and_b32_e32 v54, 32, v2
	v_add_u32_e32 v2, s6, v52
	v_mul_lo_u32 v2, v2, s7
	v_or_b32_e32 v46, v2, v54
	v_add_u32_e32 v2, s5, v52
	v_mul_lo_u32 v2, v2, s7
	v_or_b32_e32 v48, v2, v54
	v_lshl_add_u64 v[2:3], v[46:47], 1, s[0:1]
	v_and_b32_e32 v47, 31, v13
	v_and_or_b32 v47, v52, s56, v47
	v_or_b32_e32 v52, 64, v46
	v_lshl_add_u64 v[50:51], v[48:49], 1, v[162:163]
	v_mul_lo_u32 v215, v47, s33
	v_add_u32_e32 v174, 0x80, v46
	v_lshl_add_u64 v[46:47], v[52:53], 1, s[0:1]
	s_barrier
	v_readlane_b32 s16, v252, 3
	v_readlane_b32 s22, v252, 9
	v_readlane_b32 s17, v252, 4
	v_readlane_b32 s18, v252, 5
	v_readlane_b32 s19, v252, 6
	v_readlane_b32 s20, v252, 7
	v_readlane_b32 s21, v252, 8
	v_readlane_b32 s23, v252, 10
	s_nop 1
	s_add_i32 s4, s4, s22
	v_cmp_lt_i32_e32 vcc, s4, v179
	s_and_b64 vcc, exec, vcc
	v_mov_b32_e32 v164, v2
	v_mov_b32_e32 v165, v3
	v_mov_b32_e32 v192, v50
	v_mov_b32_e32 v193, v51
	v_lshrrev_b32_e32 v214, 1, v180
	v_and_b32_e32 v248, 1, v180
	v_mul_u32_u24_e32 v214, 0x90, v214
	v_lshl_add_u32 v163, v248, 6, v214
	v_add_u32_e32 v163, 16, v163
	v_add_u32_e32 v175, 0x12000, v163
	v_lshrrev_b32_e32 v214, 8, v180
	v_and_b32_e32 v249, 31, v180
	v_lshl_or_b32 v214, v214, 7, v249
	v_mul_u32_u24_e32 v214, 0x90, v214
	v_bfe_u32 v248, v180, 5, 1
	v_lshl_add_u32 v214, v248, 4, v214
	v_add_u32_e32 v194, 16, v214
	v_add_u32_e32 v199, 0x12000, v194
	v_bfe_u32 v214, v180, 6, 2
	v_lshl_or_b32 v214, v214, 6, v249
	v_mul_u32_u24_e32 v214, 0x90, v214
	v_lshl_add_u32 v214, v248, 4, v214
	v_add_u32_e32 v212, 0x9010, v214
	v_add_u32_e32 v213, 0x12000, v212
	global_load_dwordx4 v[130:133], v[164:165], off offset:0
	global_load_dwordx4 v[134:137], v[164:165], off offset:16
	global_load_dwordx4 v[138:141], v[164:165], off offset:32
	global_load_dwordx4 v[142:145], v[164:165], off offset:48
	global_load_dwordx4 v[146:149], v[192:193], off offset:0
	global_load_dwordx4 v[150:153], v[192:193], off offset:16
	global_load_dwordx4 v[154:157], v[192:193], off offset:32
	global_load_dwordx4 v[158:161], v[192:193], off offset:48
	s_waitcnt vmcnt(0)
	ds_write_b128 v163, v[130:133]
	ds_write_b128 v163, v[134:137] offset:16
	ds_write_b128 v163, v[138:141] offset:32
	ds_write_b128 v163, v[142:145] offset:48
	ds_write_b128 v163, v[146:149] offset:36864
	ds_write_b128 v163, v[150:153] offset:36880
	ds_write_b128 v163, v[154:157] offset:36896
	ds_write_b128 v163, v[158:161] offset:36912
	global_load_dwordx4 v[130:133], v[164:165], off offset:128
	global_load_dwordx4 v[134:137], v[164:165], off offset:144
	global_load_dwordx4 v[138:141], v[164:165], off offset:160
	global_load_dwordx4 v[142:145], v[164:165], off offset:176
	global_load_dwordx4 v[146:149], v[192:193], off offset:128
	global_load_dwordx4 v[150:153], v[192:193], off offset:144
	global_load_dwordx4 v[154:157], v[192:193], off offset:160
	global_load_dwordx4 v[158:161], v[192:193], off offset:176
	s_waitcnt lgkmcnt(0)
	s_barrier
	ds_read_b128 v[232:235], v212
	ds_read_b128 v[188:191], v194
	ds_read_b128 v[236:239], v212 offset:4608
	ds_read_b128 v[200:203], v194 offset:4608
	ds_read_b128 v[204:207], v194 offset:9216
	ds_read_b128 v[208:211], v194 offset:13824
	ds_read_b128 v[240:243], v212 offset:32
	ds_read_b128 v[216:219], v194 offset:32
	ds_read_b128 v[244:247], v212 offset:4640
	ds_read_b128 v[220:223], v194 offset:4640
	ds_read_b128 v[224:227], v194 offset:9248
	ds_read_b128 v[228:231], v194 offset:13856
	s_waitcnt vmcnt(4)
	ds_write_b128 v175, v[130:133]
	ds_write_b128 v175, v[134:137] offset:16
	ds_write_b128 v175, v[138:141] offset:32
	ds_write_b128 v175, v[142:145] offset:48
	global_load_dwordx4 v[130:133], v[164:165], off offset:256
	global_load_dwordx4 v[134:137], v[164:165], off offset:272
	global_load_dwordx4 v[138:141], v[164:165], off offset:288
	global_load_dwordx4 v[142:145], v[164:165], off offset:304
	s_waitcnt lgkmcnt(14)
	v_mfma_f32_32x32x16_f16 v[114:129], v[232:235], v[188:191], 0
	s_waitcnt lgkmcnt(13)
	v_mfma_f32_32x32x16_f16 v[98:113], v[236:239], v[188:191], 0
	s_waitcnt lgkmcnt(12)
	v_mfma_f32_32x32x16_f16 v[82:97], v[232:235], v[200:203], 0
	v_mfma_f32_32x32x16_f16 v[66:81], v[236:239], v[200:203], 0
	s_waitcnt lgkmcnt(11)
	v_mfma_f32_32x32x16_f16 v[50:65], v[232:235], v[204:207], 0
	v_mfma_f32_32x32x16_f16 v[34:49], v[236:239], v[204:207], 0
	s_waitcnt lgkmcnt(10)
	v_mfma_f32_32x32x16_f16 v[18:33], v[232:235], v[208:211], 0
	v_mfma_f32_32x32x16_f16 v[2:17], v[236:239], v[208:211], 0
	ds_read_b128 v[232:235], v212 offset:64
	ds_read_b128 v[188:191], v194 offset:64
	ds_read_b128 v[236:239], v212 offset:4672
	ds_read_b128 v[200:203], v194 offset:4672
	ds_read_b128 v[204:207], v194 offset:9280
	ds_read_b128 v[208:211], v194 offset:13888
	s_waitcnt vmcnt(4)
; DI f16v mfma32(h8v a, h8v b, f16v c) { return __builtin_amdgcn_mfma_f32_32x32x16_f16(a, b, c, 0, 0, 0); }
; template <bool GATHER>
; DI void gemm256_main(const h16* __restrict__ A, int lda, const int* __restrict__ idx, int m0,
;                      const h16* __restrict__ B, int ldb, int n0, int K, h16* lds, f16v (&acc)[4][2]) {
;     ...
;   for (int kt = 0; kt < nk; ++kt) {
;     const h16* As = lds + (kt & 1) * (512 * LDH);
;     const h16* Bs = As + 256 * LDH;
;     h16* Wn = lds + ((kt & 1) ^ 1) * (512 * LDH);
;     if (kt + 1 < nk) {
; #pragma unroll
;       for (int i = 0; i < 4; ++i) { *(u4v*)&Wn[lr * LDH + lc + 8 * i] = ra[i]; *(u4v*)&Wn[(256 + lr) * LDH + lc + 8 * i] = rb[i]; }
;     }
;     if (kt + 2 < nk) {
; #pragma unroll
;       for (int i = 0; i < 4; ++i) { ra[i] = *(const u4v*)(AP_ + 8 * i); rb[i] = *(const u4v*)(BP_ + 8 * i); }
;       ao += 64; bo += 64;
;     }
; #pragma unroll
;     for (int ks = 0; ks < 4; ++ks) {
;       h8v af[4], bf[2];
; #pragma unroll
;       for (int i = 0; i < 4; ++i) af[i] = *(const h8v*)&As[(wm * 128 + i * 32 + (lane & 31)) * LDH + ks * 16 + 8 * (lane >> 5)];
; #pragma unroll
;       for (int j = 0; j < 2; ++j) bf[j] = *(const h8v*)&Bs[(wn * 64 + j * 32 + (lane & 31)) * LDH + ks * 16 + 8 * (lane >> 5)];
; #pragma unroll
;       for (int i = 0; i < 4; ++i)
; #pragma unroll
;         for (int j = 0; j < 2; ++j) acc[i][j] = mfma32(bf[j], af[i], acc[i][j]);
;     }
;     __syncthreads();
;   }
	ds_write_b128 v175, v[146:149] offset:36864
	ds_write_b128 v175, v[150:153] offset:36880
	ds_write_b128 v175, v[154:157] offset:36896
	ds_write_b128 v175, v[158:161] offset:36912
	global_load_dwordx4 v[146:149], v[192:193], off offset:256
	global_load_dwordx4 v[150:153], v[192:193], off offset:272
	global_load_dwordx4 v[154:157], v[192:193], off offset:288
	global_load_dwordx4 v[158:161], v[192:193], off offset:304
	s_waitcnt lgkmcnt(15)
	v_mfma_f32_32x32x16_f16 v[114:129], v[240:243], v[216:219], v[114:129]
	s_waitcnt lgkmcnt(15)
	v_mfma_f32_32x32x16_f16 v[98:113], v[244:247], v[216:219], v[98:113]
	s_waitcnt lgkmcnt(15)
	v_mfma_f32_32x32x16_f16 v[82:97], v[240:243], v[220:223], v[82:97]
	v_mfma_f32_32x32x16_f16 v[66:81], v[244:247], v[220:223], v[66:81]
	s_waitcnt lgkmcnt(15)
	v_mfma_f32_32x32x16_f16 v[50:65], v[240:243], v[224:227], v[50:65]
	v_mfma_f32_32x32x16_f16 v[34:49], v[244:247], v[224:227], v[34:49]
	s_waitcnt lgkmcnt(14)
	v_mfma_f32_32x32x16_f16 v[18:33], v[240:243], v[228:231], v[18:33]
	v_mfma_f32_32x32x16_f16 v[2:17], v[244:247], v[228:231], v[2:17]
	ds_read_b128 v[240:243], v212 offset:96
	ds_read_b128 v[216:219], v194 offset:96
	ds_read_b128 v[244:247], v212 offset:4704
	ds_read_b128 v[220:223], v194 offset:4704
	ds_read_b128 v[224:227], v194 offset:9312
	ds_read_b128 v[228:231], v194 offset:13920
	s_waitcnt lgkmcnt(14)
	v_mfma_f32_32x32x16_f16 v[114:129], v[232:235], v[188:191], v[114:129]
	s_waitcnt lgkmcnt(13)
	v_mfma_f32_32x32x16_f16 v[98:113], v[236:239], v[188:191], v[98:113]
	s_waitcnt lgkmcnt(12)
	v_mfma_f32_32x32x16_f16 v[82:97], v[232:235], v[200:203], v[82:97]
	v_mfma_f32_32x32x16_f16 v[66:81], v[236:239], v[200:203], v[66:81]
	s_waitcnt lgkmcnt(11)
	v_mfma_f32_32x32x16_f16 v[50:65], v[232:235], v[204:207], v[50:65]
	v_mfma_f32_32x32x16_f16 v[34:49], v[236:239], v[204:207], v[34:49]
	s_waitcnt lgkmcnt(10)
	v_mfma_f32_32x32x16_f16 v[18:33], v[232:235], v[208:211], v[18:33]
	v_mfma_f32_32x32x16_f16 v[2:17], v[236:239], v[208:211], v[2:17]
	s_waitcnt lgkmcnt(0)
	s_barrier
	ds_read_b128 v[232:235], v213
	ds_read_b128 v[188:191], v199
	ds_read_b128 v[236:239], v213 offset:4608
	ds_read_b128 v[200:203], v199 offset:4608
	ds_read_b128 v[204:207], v199 offset:9216
	ds_read_b128 v[208:211], v199 offset:13824
	v_mfma_f32_32x32x16_f16 v[114:129], v[240:243], v[216:219], v[114:129]
	v_mfma_f32_32x32x16_f16 v[98:113], v[244:247], v[216:219], v[98:113]
	v_mfma_f32_32x32x16_f16 v[82:97], v[240:243], v[220:223], v[82:97]
	v_mfma_f32_32x32x16_f16 v[66:81], v[244:247], v[220:223], v[66:81]
	v_mfma_f32_32x32x16_f16 v[50:65], v[240:243], v[224:227], v[50:65]
	v_mfma_f32_32x32x16_f16 v[34:49], v[244:247], v[224:227], v[34:49]
	v_mfma_f32_32x32x16_f16 v[18:33], v[240:243], v[228:231], v[18:33]
	v_mfma_f32_32x32x16_f16 v[2:17], v[244:247], v[228:231], v[2:17]
	ds_read_b128 v[240:243], v213 offset:32
	ds_read_b128 v[216:219], v199 offset:32
	ds_read_b128 v[244:247], v213 offset:4640
	ds_read_b128 v[220:223], v199 offset:4640
	ds_read_b128 v[224:227], v199 offset:9248
	ds_read_b128 v[228:231], v199 offset:13856
	s_waitcnt vmcnt(4)
	ds_write_b128 v163, v[130:133]
	ds_write_b128 v163, v[134:137] offset:16
	ds_write_b128 v163, v[138:141] offset:32
	ds_write_b128 v163, v[142:145] offset:48
	global_load_dwordx4 v[130:133], v[164:165], off offset:384
	global_load_dwordx4 v[134:137], v[164:165], off offset:400
	global_load_dwordx4 v[138:141], v[164:165], off offset:416
	global_load_dwordx4 v[142:145], v[164:165], off offset:432
	s_waitcnt lgkmcnt(14)
	v_mfma_f32_32x32x16_f16 v[114:129], v[232:235], v[188:191], v[114:129]
	s_waitcnt lgkmcnt(13)
	v_mfma_f32_32x32x16_f16 v[98:113], v[236:239], v[188:191], v[98:113]
	s_waitcnt lgkmcnt(12)
	v_mfma_f32_32x32x16_f16 v[82:97], v[232:235], v[200:203], v[82:97]
	v_mfma_f32_32x32x16_f16 v[66:81], v[236:239], v[200:203], v[66:81]
	s_waitcnt lgkmcnt(11)
	v_mfma_f32_32x32x16_f16 v[50:65], v[232:235], v[204:207], v[50:65]
	v_mfma_f32_32x32x16_f16 v[34:49], v[236:239], v[204:207], v[34:49]
	s_waitcnt lgkmcnt(10)
	v_mfma_f32_32x32x16_f16 v[18:33], v[232:235], v[208:211], v[18:33]
	v_mfma_f32_32x32x16_f16 v[2:17], v[236:239], v[208:211], v[2:17]
	ds_read_b128 v[232:235], v213 offset:64
	ds_read_b128 v[188:191], v199 offset:64
	ds_read_b128 v[236:239], v213 offset:4672
	ds_read_b128 v[200:203], v199 offset:4672
	ds_read_b128 v[204:207], v199 offset:9280
	ds_read_b128 v[208:211], v199 offset:13888
	s_waitcnt vmcnt(4)
	ds_write_b128 v163, v[146:149] offset:36864
	ds_write_b128 v163, v[150:153] offset:36880
	ds_write_b128 v163, v[154:157] offset:36896
	ds_write_b128 v163, v[158:161] offset:36912
	global_load_dwordx4 v[146:149], v[192:193], off offset:384
	global_load_dwordx4 v[150:153], v[192:193], off offset:400
	global_load_dwordx4 v[154:157], v[192:193], off offset:416
	global_load_dwordx4 v[158:161], v[192:193], off offset:432
	s_waitcnt lgkmcnt(15)
	v_mfma_f32_32x32x16_f16 v[114:129], v[240:243], v[216:219], v[114:129]
	s_waitcnt lgkmcnt(15)
	v_mfma_f32_32x32x16_f16 v[98:113], v[244:247], v[216:219], v[98:113]
	s_waitcnt lgkmcnt(15)
	v_mfma_f32_32x32x16_f16 v[82:97], v[240:243], v[220:223], v[82:97]
	v_mfma_f32_32x32x16_f16 v[66:81], v[244:247], v[220:223], v[66:81]
	s_waitcnt lgkmcnt(15)
	v_mfma_f32_32x32x16_f16 v[50:65], v[240:243], v[224:227], v[50:65]
	v_mfma_f32_32x32x16_f16 v[34:49], v[244:247], v[224:227], v[34:49]
	s_waitcnt lgkmcnt(14)
	v_mfma_f32_32x32x16_f16 v[18:33], v[240:243], v[228:231], v[18:33]
	v_mfma_f32_32x32x16_f16 v[2:17], v[244:247], v[228:231], v[2:17]
	ds_read_b128 v[240:243], v213 offset:96
	ds_read_b128 v[216:219], v199 offset:96
	ds_read_b128 v[244:247], v213 offset:4704
	ds_read_b128 v[220:223], v199 offset:4704
	ds_read_b128 v[224:227], v199 offset:9312
	ds_read_b128 v[228:231], v199 offset:13920
	s_waitcnt lgkmcnt(14)
	v_mfma_f32_32x32x16_f16 v[114:129], v[232:235], v[188:191], v[114:129]
	s_waitcnt lgkmcnt(13)
	v_mfma_f32_32x32x16_f16 v[98:113], v[236:239], v[188:191], v[98:113]
	s_waitcnt lgkmcnt(12)
	v_mfma_f32_32x32x16_f16 v[82:97], v[232:235], v[200:203], v[82:97]
	v_mfma_f32_32x32x16_f16 v[66:81], v[236:239], v[200:203], v[66:81]
	s_waitcnt lgkmcnt(11)
	v_mfma_f32_32x32x16_f16 v[50:65], v[232:235], v[204:207], v[50:65]
	v_mfma_f32_32x32x16_f16 v[34:49], v[236:239], v[204:207], v[34:49]
	s_waitcnt lgkmcnt(10)
	v_mfma_f32_32x32x16_f16 v[18:33], v[232:235], v[208:211], v[18:33]
	v_mfma_f32_32x32x16_f16 v[2:17], v[236:239], v[208:211], v[2:17]
	s_waitcnt lgkmcnt(0)
	s_barrier
; DI f16v mfma32(h8v a, h8v b, f16v c) { return __builtin_amdgcn_mfma_f32_32x32x16_f16(a, b, c, 0, 0, 0); }
; template <bool GATHER>
; DI void gemm256_main(const h16* __restrict__ A, int lda, const int* __restrict__ idx, int m0,
;                      const h16* __restrict__ B, int ldb, int n0, int K, h16* lds, f16v (&acc)[4][2]) {
;     ...
;   for (int kt = 0; kt < nk; ++kt) {
;     const h16* As = lds + (kt & 1) * (512 * LDH);
;     const h16* Bs = As + 256 * LDH;
;     h16* Wn = lds + ((kt & 1) ^ 1) * (512 * LDH);
;     if (kt + 1 < nk) {
; #pragma unroll
;       for (int i = 0; i < 4; ++i) { *(u4v*)&Wn[lr * LDH + lc + 8 * i] = ra[i]; *(u4v*)&Wn[(256 + lr) * LDH + lc + 8 * i] = rb[i]; }
;     }
;     if (kt + 2 < nk) {
; #pragma unroll
;       for (int i = 0; i < 4; ++i) { ra[i] = *(const u4v*)(AP_ + 8 * i); rb[i] = *(const u4v*)(BP_ + 8 * i); }
;       ao += 64; bo += 64;
;     }
; #pragma unroll
;     for (int ks = 0; ks < 4; ++ks) {
;       h8v af[4], bf[2];
; #pragma unroll
;       for (int i = 0; i < 4; ++i) af[i] = *(const h8v*)&As[(wm * 128 + i * 32 + (lane & 31)) * LDH + ks * 16 + 8 * (lane >> 5)];
; #pragma unroll
;       for (int j = 0; j < 2; ++j) bf[j] = *(const h8v*)&Bs[(wn * 64 + j * 32 + (lane & 31)) * LDH + ks * 16 + 8 * (lane >> 5)];
; #pragma unroll
;       for (int i = 0; i < 4; ++i)
; #pragma unroll
;         for (int j = 0; j < 2; ++j) acc[i][j] = mfma32(bf[j], af[i], acc[i][j]);
;     }
;     __syncthreads();
;   }
	ds_read_b128 v[232:235], v212
	ds_read_b128 v[188:191], v194
	ds_read_b128 v[236:239], v212 offset:4608
	ds_read_b128 v[200:203], v194 offset:4608
	ds_read_b128 v[204:207], v194 offset:9216
	ds_read_b128 v[208:211], v194 offset:13824
	v_mfma_f32_32x32x16_f16 v[114:129], v[240:243], v[216:219], v[114:129]
	v_mfma_f32_32x32x16_f16 v[98:113], v[244:247], v[216:219], v[98:113]
	v_mfma_f32_32x32x16_f16 v[82:97], v[240:243], v[220:223], v[82:97]
	v_mfma_f32_32x32x16_f16 v[66:81], v[244:247], v[220:223], v[66:81]
	v_mfma_f32_32x32x16_f16 v[50:65], v[240:243], v[224:227], v[50:65]
	v_mfma_f32_32x32x16_f16 v[34:49], v[244:247], v[224:227], v[34:49]
	v_mfma_f32_32x32x16_f16 v[18:33], v[240:243], v[228:231], v[18:33]
	v_mfma_f32_32x32x16_f16 v[2:17], v[244:247], v[228:231], v[2:17]
	ds_read_b128 v[240:243], v212 offset:32
	ds_read_b128 v[216:219], v194 offset:32
	ds_read_b128 v[244:247], v212 offset:4640
	ds_read_b128 v[220:223], v194 offset:4640
	ds_read_b128 v[224:227], v194 offset:9248
	ds_read_b128 v[228:231], v194 offset:13856
	s_waitcnt vmcnt(4)
	ds_write_b128 v175, v[130:133]
	ds_write_b128 v175, v[134:137] offset:16
	ds_write_b128 v175, v[138:141] offset:32
	ds_write_b128 v175, v[142:145] offset:48
	global_load_dwordx4 v[130:133], v[164:165], off offset:512
	global_load_dwordx4 v[134:137], v[164:165], off offset:528
	global_load_dwordx4 v[138:141], v[164:165], off offset:544
	global_load_dwordx4 v[142:145], v[164:165], off offset:560
	s_waitcnt lgkmcnt(14)
	v_mfma_f32_32x32x16_f16 v[114:129], v[232:235], v[188:191], v[114:129]
	s_waitcnt lgkmcnt(13)
	v_mfma_f32_32x32x16_f16 v[98:113], v[236:239], v[188:191], v[98:113]
	s_waitcnt lgkmcnt(12)
	v_mfma_f32_32x32x16_f16 v[82:97], v[232:235], v[200:203], v[82:97]
	v_mfma_f32_32x32x16_f16 v[66:81], v[236:239], v[200:203], v[66:81]
	s_waitcnt lgkmcnt(11)
	v_mfma_f32_32x32x16_f16 v[50:65], v[232:235], v[204:207], v[50:65]
	v_mfma_f32_32x32x16_f16 v[34:49], v[236:239], v[204:207], v[34:49]
	s_waitcnt lgkmcnt(10)
	v_mfma_f32_32x32x16_f16 v[18:33], v[232:235], v[208:211], v[18:33]
	v_mfma_f32_32x32x16_f16 v[2:17], v[236:239], v[208:211], v[2:17]
	ds_read_b128 v[232:235], v212 offset:64
	ds_read_b128 v[188:191], v194 offset:64
	ds_read_b128 v[236:239], v212 offset:4672
	ds_read_b128 v[200:203], v194 offset:4672
	ds_read_b128 v[204:207], v194 offset:9280
	ds_read_b128 v[208:211], v194 offset:13888
	s_waitcnt vmcnt(4)
	ds_write_b128 v175, v[146:149] offset:36864
	ds_write_b128 v175, v[150:153] offset:36880
	ds_write_b128 v175, v[154:157] offset:36896
	ds_write_b128 v175, v[158:161] offset:36912
	global_load_dwordx4 v[146:149], v[192:193], off offset:512
	global_load_dwordx4 v[150:153], v[192:193], off offset:528
	global_load_dwordx4 v[154:157], v[192:193], off offset:544
	global_load_dwordx4 v[158:161], v[192:193], off offset:560
	s_waitcnt lgkmcnt(15)
	v_mfma_f32_32x32x16_f16 v[114:129], v[240:243], v[216:219], v[114:129]
	s_waitcnt lgkmcnt(15)
	v_mfma_f32_32x32x16_f16 v[98:113], v[244:247], v[216:219], v[98:113]
	s_waitcnt lgkmcnt(15)
	v_mfma_f32_32x32x16_f16 v[82:97], v[240:243], v[220:223], v[82:97]
	v_mfma_f32_32x32x16_f16 v[66:81], v[244:247], v[220:223], v[66:81]
	s_waitcnt lgkmcnt(15)
	v_mfma_f32_32x32x16_f16 v[50:65], v[240:243], v[224:227], v[50:65]
	v_mfma_f32_32x32x16_f16 v[34:49], v[244:247], v[224:227], v[34:49]
	s_waitcnt lgkmcnt(14)
	v_mfma_f32_32x32x16_f16 v[18:33], v[240:243], v[228:231], v[18:33]
	v_mfma_f32_32x32x16_f16 v[2:17], v[244:247], v[228:231], v[2:17]
	ds_read_b128 v[240:243], v212 offset:96
	ds_read_b128 v[216:219], v194 offset:96
	ds_read_b128 v[244:247], v212 offset:4704
	ds_read_b128 v[220:223], v194 offset:4704
	ds_read_b128 v[224:227], v194 offset:9312
	ds_read_b128 v[228:231], v194 offset:13920
	s_waitcnt lgkmcnt(14)
	v_mfma_f32_32x32x16_f16 v[114:129], v[232:235], v[188:191], v[114:129]
	s_waitcnt lgkmcnt(13)
	v_mfma_f32_32x32x16_f16 v[98:113], v[236:239], v[188:191], v[98:113]
	s_waitcnt lgkmcnt(12)
	v_mfma_f32_32x32x16_f16 v[82:97], v[232:235], v[200:203], v[82:97]
	v_mfma_f32_32x32x16_f16 v[66:81], v[236:239], v[200:203], v[66:81]
	s_waitcnt lgkmcnt(11)
	v_mfma_f32_32x32x16_f16 v[50:65], v[232:235], v[204:207], v[50:65]
	v_mfma_f32_32x32x16_f16 v[34:49], v[236:239], v[204:207], v[34:49]
	s_waitcnt lgkmcnt(10)
	v_mfma_f32_32x32x16_f16 v[18:33], v[232:235], v[208:211], v[18:33]
	v_mfma_f32_32x32x16_f16 v[2:17], v[236:239], v[208:211], v[2:17]
	s_waitcnt lgkmcnt(0)
	s_barrier
; DI f16v mfma32(h8v a, h8v b, f16v c) { return __builtin_amdgcn_mfma_f32_32x32x16_f16(a, b, c, 0, 0, 0); }
; template <bool GATHER>
; DI void gemm256_main(const h16* __restrict__ A, int lda, const int* __restrict__ idx, int m0,
;                      const h16* __restrict__ B, int ldb, int n0, int K, h16* lds, f16v (&acc)[4][2]) {
;     ...
;   for (int kt = 0; kt < nk; ++kt) {
;     const h16* As = lds + (kt & 1) * (512 * LDH);
;     const h16* Bs = As + 256 * LDH;
;     h16* Wn = lds + ((kt & 1) ^ 1) * (512 * LDH);
;     if (kt + 1 < nk) {
; #pragma unroll
;       for (int i = 0; i < 4; ++i) { *(u4v*)&Wn[lr * LDH + lc + 8 * i] = ra[i]; *(u4v*)&Wn[(256 + lr) * LDH + lc + 8 * i] = rb[i]; }
;     }
;     if (kt + 2 < nk) {
; #pragma unroll
;       for (int i = 0; i < 4; ++i) { ra[i] = *(const u4v*)(AP_ + 8 * i); rb[i] = *(const u4v*)(BP_ + 8 * i); }
;       ao += 64; bo += 64;
;     }
; #pragma unroll
;     for (int ks = 0; ks < 4; ++ks) {
;       h8v af[4], bf[2];
; #pragma unroll
;       for (int i = 0; i < 4; ++i) af[i] = *(const h8v*)&As[(wm * 128 + i * 32 + (lane & 31)) * LDH + ks * 16 + 8 * (lane >> 5)];
; #pragma unroll
;       for (int j = 0; j < 2; ++j) bf[j] = *(const h8v*)&Bs[(wn * 64 + j * 32 + (lane & 31)) * LDH + ks * 16 + 8 * (lane >> 5)];
; #pragma unroll
;       for (int i = 0; i < 4; ++i)
; #pragma unroll
;         for (int j = 0; j < 2; ++j) acc[i][j] = mfma32(bf[j], af[i], acc[i][j]);
;     }
;     __syncthreads();
;   }
	ds_read_b128 v[232:235], v213
	ds_read_b128 v[188:191], v199
	ds_read_b128 v[236:239], v213 offset:4608
	ds_read_b128 v[200:203], v199 offset:4608
	ds_read_b128 v[204:207], v199 offset:9216
	ds_read_b128 v[208:211], v199 offset:13824
	v_mfma_f32_32x32x16_f16 v[114:129], v[240:243], v[216:219], v[114:129]
	v_mfma_f32_32x32x16_f16 v[98:113], v[244:247], v[216:219], v[98:113]
	v_mfma_f32_32x32x16_f16 v[82:97], v[240:243], v[220:223], v[82:97]
	v_mfma_f32_32x32x16_f16 v[66:81], v[244:247], v[220:223], v[66:81]
	v_mfma_f32_32x32x16_f16 v[50:65], v[240:243], v[224:227], v[50:65]
	v_mfma_f32_32x32x16_f16 v[34:49], v[244:247], v[224:227], v[34:49]
	v_mfma_f32_32x32x16_f16 v[18:33], v[240:243], v[228:231], v[18:33]
	v_mfma_f32_32x32x16_f16 v[2:17], v[244:247], v[228:231], v[2:17]
	ds_read_b128 v[240:243], v213 offset:32
	ds_read_b128 v[216:219], v199 offset:32
	ds_read_b128 v[244:247], v213 offset:4640
	ds_read_b128 v[220:223], v199 offset:4640
	ds_read_b128 v[224:227], v199 offset:9248
	ds_read_b128 v[228:231], v199 offset:13856
	s_waitcnt vmcnt(4)
	ds_write_b128 v163, v[130:133]
	ds_write_b128 v163, v[134:137] offset:16
	ds_write_b128 v163, v[138:141] offset:32
	ds_write_b128 v163, v[142:145] offset:48
	global_load_dwordx4 v[130:133], v[164:165], off offset:640
	global_load_dwordx4 v[134:137], v[164:165], off offset:656
	global_load_dwordx4 v[138:141], v[164:165], off offset:672
	global_load_dwordx4 v[142:145], v[164:165], off offset:688
	s_waitcnt lgkmcnt(14)
	v_mfma_f32_32x32x16_f16 v[114:129], v[232:235], v[188:191], v[114:129]
	s_waitcnt lgkmcnt(13)
	v_mfma_f32_32x32x16_f16 v[98:113], v[236:239], v[188:191], v[98:113]
	s_waitcnt lgkmcnt(12)
	v_mfma_f32_32x32x16_f16 v[82:97], v[232:235], v[200:203], v[82:97]
	v_mfma_f32_32x32x16_f16 v[66:81], v[236:239], v[200:203], v[66:81]
	s_waitcnt lgkmcnt(11)
	v_mfma_f32_32x32x16_f16 v[50:65], v[232:235], v[204:207], v[50:65]
	v_mfma_f32_32x32x16_f16 v[34:49], v[236:239], v[204:207], v[34:49]
	s_waitcnt lgkmcnt(10)
	v_mfma_f32_32x32x16_f16 v[18:33], v[232:235], v[208:211], v[18:33]
	v_mfma_f32_32x32x16_f16 v[2:17], v[236:239], v[208:211], v[2:17]
	ds_read_b128 v[232:235], v213 offset:64
	ds_read_b128 v[188:191], v199 offset:64
	ds_read_b128 v[236:239], v213 offset:4672
	ds_read_b128 v[200:203], v199 offset:4672
	ds_read_b128 v[204:207], v199 offset:9280
	ds_read_b128 v[208:211], v199 offset:13888
	s_waitcnt vmcnt(4)
	ds_write_b128 v163, v[146:149] offset:36864
	ds_write_b128 v163, v[150:153] offset:36880
	ds_write_b128 v163, v[154:157] offset:36896
	ds_write_b128 v163, v[158:161] offset:36912
	global_load_dwordx4 v[146:149], v[192:193], off offset:640
	global_load_dwordx4 v[150:153], v[192:193], off offset:656
	global_load_dwordx4 v[154:157], v[192:193], off offset:672
	global_load_dwordx4 v[158:161], v[192:193], off offset:688
	s_waitcnt lgkmcnt(15)
	v_mfma_f32_32x32x16_f16 v[114:129], v[240:243], v[216:219], v[114:129]
	s_waitcnt lgkmcnt(15)
	v_mfma_f32_32x32x16_f16 v[98:113], v[244:247], v[216:219], v[98:113]
	s_waitcnt lgkmcnt(15)
	v_mfma_f32_32x32x16_f16 v[82:97], v[240:243], v[220:223], v[82:97]
	v_mfma_f32_32x32x16_f16 v[66:81], v[244:247], v[220:223], v[66:81]
	s_waitcnt lgkmcnt(15)
	v_mfma_f32_32x32x16_f16 v[50:65], v[240:243], v[224:227], v[50:65]
	v_mfma_f32_32x32x16_f16 v[34:49], v[244:247], v[224:227], v[34:49]
	s_waitcnt lgkmcnt(14)
	v_mfma_f32_32x32x16_f16 v[18:33], v[240:243], v[228:231], v[18:33]
	v_mfma_f32_32x32x16_f16 v[2:17], v[244:247], v[228:231], v[2:17]
	ds_read_b128 v[240:243], v213 offset:96
	ds_read_b128 v[216:219], v199 offset:96
	ds_read_b128 v[244:247], v213 offset:4704
	ds_read_b128 v[220:223], v199 offset:4704
	ds_read_b128 v[224:227], v199 offset:9312
	ds_read_b128 v[228:231], v199 offset:13920
	s_waitcnt lgkmcnt(14)
	v_mfma_f32_32x32x16_f16 v[114:129], v[232:235], v[188:191], v[114:129]
	s_waitcnt lgkmcnt(13)
	v_mfma_f32_32x32x16_f16 v[98:113], v[236:239], v[188:191], v[98:113]
	s_waitcnt lgkmcnt(12)
	v_mfma_f32_32x32x16_f16 v[82:97], v[232:235], v[200:203], v[82:97]
	v_mfma_f32_32x32x16_f16 v[66:81], v[236:239], v[200:203], v[66:81]
	s_waitcnt lgkmcnt(11)
	v_mfma_f32_32x32x16_f16 v[50:65], v[232:235], v[204:207], v[50:65]
	v_mfma_f32_32x32x16_f16 v[34:49], v[236:239], v[204:207], v[34:49]
	s_waitcnt lgkmcnt(10)
	v_mfma_f32_32x32x16_f16 v[18:33], v[232:235], v[208:211], v[18:33]
	v_mfma_f32_32x32x16_f16 v[2:17], v[236:239], v[208:211], v[2:17]
	s_waitcnt lgkmcnt(0)
	s_barrier
; DI f16v mfma32(h8v a, h8v b, f16v c) { return __builtin_amdgcn_mfma_f32_32x32x16_f16(a, b, c, 0, 0, 0); }
; template <bool GATHER>
; DI void gemm256_main(const h16* __restrict__ A, int lda, const int* __restrict__ idx, int m0,
;                      const h16* __restrict__ B, int ldb, int n0, int K, h16* lds, f16v (&acc)[4][2]) {
;     ...
;   for (int kt = 0; kt < nk; ++kt) {
;     const h16* As = lds + (kt & 1) * (512 * LDH);
;     const h16* Bs = As + 256 * LDH;
;     h16* Wn = lds + ((kt & 1) ^ 1) * (512 * LDH);
;     if (kt + 1 < nk) {
; #pragma unroll
;       for (int i = 0; i < 4; ++i) { *(u4v*)&Wn[lr * LDH + lc + 8 * i] = ra[i]; *(u4v*)&Wn[(256 + lr) * LDH + lc + 8 * i] = rb[i]; }
;     }
;     if (kt + 2 < nk) {
; #pragma unroll
;       for (int i = 0; i < 4; ++i) { ra[i] = *(const u4v*)(AP_ + 8 * i); rb[i] = *(const u4v*)(BP_ + 8 * i); }
;       ao += 64; bo += 64;
;     }
; #pragma unroll
;     for (int ks = 0; ks < 4; ++ks) {
;       h8v af[4], bf[2];
; #pragma unroll
;       for (int i = 0; i < 4; ++i) af[i] = *(const h8v*)&As[(wm * 128 + i * 32 + (lane & 31)) * LDH + ks * 16 + 8 * (lane >> 5)];
; #pragma unroll
;       for (int j = 0; j < 2; ++j) bf[j] = *(const h8v*)&Bs[(wn * 64 + j * 32 + (lane & 31)) * LDH + ks * 16 + 8 * (lane >> 5)];
; #pragma unroll
;       for (int i = 0; i < 4; ++i)
; #pragma unroll
;         for (int j = 0; j < 2; ++j) acc[i][j] = mfma32(bf[j], af[i], acc[i][j]);
;     }
;     __syncthreads();
;   }
	ds_read_b128 v[232:235], v212
	ds_read_b128 v[188:191], v194
	ds_read_b128 v[236:239], v212 offset:4608
	ds_read_b128 v[200:203], v194 offset:4608
	ds_read_b128 v[204:207], v194 offset:9216
	ds_read_b128 v[208:211], v194 offset:13824
	v_mfma_f32_32x32x16_f16 v[114:129], v[240:243], v[216:219], v[114:129]
	v_mfma_f32_32x32x16_f16 v[98:113], v[244:247], v[216:219], v[98:113]
	v_mfma_f32_32x32x16_f16 v[82:97], v[240:243], v[220:223], v[82:97]
	v_mfma_f32_32x32x16_f16 v[66:81], v[244:247], v[220:223], v[66:81]
	v_mfma_f32_32x32x16_f16 v[50:65], v[240:243], v[224:227], v[50:65]
	v_mfma_f32_32x32x16_f16 v[34:49], v[244:247], v[224:227], v[34:49]
	v_mfma_f32_32x32x16_f16 v[18:33], v[240:243], v[228:231], v[18:33]
	v_mfma_f32_32x32x16_f16 v[2:17], v[244:247], v[228:231], v[2:17]
	ds_read_b128 v[240:243], v212 offset:32
	ds_read_b128 v[216:219], v194 offset:32
	ds_read_b128 v[244:247], v212 offset:4640
	ds_read_b128 v[220:223], v194 offset:4640
	ds_read_b128 v[224:227], v194 offset:9248
	ds_read_b128 v[228:231], v194 offset:13856
	s_waitcnt vmcnt(4)
	ds_write_b128 v175, v[130:133]
	ds_write_b128 v175, v[134:137] offset:16
	ds_write_b128 v175, v[138:141] offset:32
	ds_write_b128 v175, v[142:145] offset:48
	global_load_dwordx4 v[130:133], v[164:165], off offset:768
	global_load_dwordx4 v[134:137], v[164:165], off offset:784
	global_load_dwordx4 v[138:141], v[164:165], off offset:800
	global_load_dwordx4 v[142:145], v[164:165], off offset:816
	s_waitcnt lgkmcnt(14)
	v_mfma_f32_32x32x16_f16 v[114:129], v[232:235], v[188:191], v[114:129]
	s_waitcnt lgkmcnt(13)
	v_mfma_f32_32x32x16_f16 v[98:113], v[236:239], v[188:191], v[98:113]
	s_waitcnt lgkmcnt(12)
	v_mfma_f32_32x32x16_f16 v[82:97], v[232:235], v[200:203], v[82:97]
	v_mfma_f32_32x32x16_f16 v[66:81], v[236:239], v[200:203], v[66:81]
	s_waitcnt lgkmcnt(11)
	v_mfma_f32_32x32x16_f16 v[50:65], v[232:235], v[204:207], v[50:65]
	v_mfma_f32_32x32x16_f16 v[34:49], v[236:239], v[204:207], v[34:49]
	s_waitcnt lgkmcnt(10)
	v_mfma_f32_32x32x16_f16 v[18:33], v[232:235], v[208:211], v[18:33]
	v_mfma_f32_32x32x16_f16 v[2:17], v[236:239], v[208:211], v[2:17]
	ds_read_b128 v[232:235], v212 offset:64
	ds_read_b128 v[188:191], v194 offset:64
	ds_read_b128 v[236:239], v212 offset:4672
	ds_read_b128 v[200:203], v194 offset:4672
	ds_read_b128 v[204:207], v194 offset:9280
	ds_read_b128 v[208:211], v194 offset:13888
	s_waitcnt vmcnt(4)
	ds_write_b128 v175, v[146:149] offset:36864
	ds_write_b128 v175, v[150:153] offset:36880
	ds_write_b128 v175, v[154:157] offset:36896
	ds_write_b128 v175, v[158:161] offset:36912
	global_load_dwordx4 v[146:149], v[192:193], off offset:768
	global_load_dwordx4 v[150:153], v[192:193], off offset:784
	global_load_dwordx4 v[154:157], v[192:193], off offset:800
	global_load_dwordx4 v[158:161], v[192:193], off offset:816
	s_waitcnt lgkmcnt(15)
	v_mfma_f32_32x32x16_f16 v[114:129], v[240:243], v[216:219], v[114:129]
	s_waitcnt lgkmcnt(15)
	v_mfma_f32_32x32x16_f16 v[98:113], v[244:247], v[216:219], v[98:113]
	s_waitcnt lgkmcnt(15)
	v_mfma_f32_32x32x16_f16 v[82:97], v[240:243], v[220:223], v[82:97]
	v_mfma_f32_32x32x16_f16 v[66:81], v[244:247], v[220:223], v[66:81]
	s_waitcnt lgkmcnt(15)
	v_mfma_f32_32x32x16_f16 v[50:65], v[240:243], v[224:227], v[50:65]
	v_mfma_f32_32x32x16_f16 v[34:49], v[244:247], v[224:227], v[34:49]
	s_waitcnt lgkmcnt(14)
	v_mfma_f32_32x32x16_f16 v[18:33], v[240:243], v[228:231], v[18:33]
	v_mfma_f32_32x32x16_f16 v[2:17], v[244:247], v[228:231], v[2:17]
	ds_read_b128 v[240:243], v212 offset:96
	ds_read_b128 v[216:219], v194 offset:96
	ds_read_b128 v[244:247], v212 offset:4704
	ds_read_b128 v[220:223], v194 offset:4704
	ds_read_b128 v[224:227], v194 offset:9312
	ds_read_b128 v[228:231], v194 offset:13920
	s_waitcnt lgkmcnt(14)
	v_mfma_f32_32x32x16_f16 v[114:129], v[232:235], v[188:191], v[114:129]
	s_waitcnt lgkmcnt(13)
	v_mfma_f32_32x32x16_f16 v[98:113], v[236:239], v[188:191], v[98:113]
	s_waitcnt lgkmcnt(12)
	v_mfma_f32_32x32x16_f16 v[82:97], v[232:235], v[200:203], v[82:97]
	v_mfma_f32_32x32x16_f16 v[66:81], v[236:239], v[200:203], v[66:81]
	s_waitcnt lgkmcnt(11)
	v_mfma_f32_32x32x16_f16 v[50:65], v[232:235], v[204:207], v[50:65]
	v_mfma_f32_32x32x16_f16 v[34:49], v[236:239], v[204:207], v[34:49]
	s_waitcnt lgkmcnt(10)
	v_mfma_f32_32x32x16_f16 v[18:33], v[232:235], v[208:211], v[18:33]
	v_mfma_f32_32x32x16_f16 v[2:17], v[236:239], v[208:211], v[2:17]
	s_waitcnt lgkmcnt(0)
	s_barrier
; DI f16v mfma32(h8v a, h8v b, f16v c) { return __builtin_amdgcn_mfma_f32_32x32x16_f16(a, b, c, 0, 0, 0); }
; template <bool GATHER>
; DI void gemm256_main(const h16* __restrict__ A, int lda, const int* __restrict__ idx, int m0,
;                      const h16* __restrict__ B, int ldb, int n0, int K, h16* lds, f16v (&acc)[4][2]) {
;     ...
;   for (int kt = 0; kt < nk; ++kt) {
;     const h16* As = lds + (kt & 1) * (512 * LDH);
;     const h16* Bs = As + 256 * LDH;
;     h16* Wn = lds + ((kt & 1) ^ 1) * (512 * LDH);
;     if (kt + 1 < nk) {
; #pragma unroll
;       for (int i = 0; i < 4; ++i) { *(u4v*)&Wn[lr * LDH + lc + 8 * i] = ra[i]; *(u4v*)&Wn[(256 + lr) * LDH + lc + 8 * i] = rb[i]; }
;     }
;     if (kt + 2 < nk) {
; #pragma unroll
;       for (int i = 0; i < 4; ++i) { ra[i] = *(const u4v*)(AP_ + 8 * i); rb[i] = *(const u4v*)(BP_ + 8 * i); }
;       ao += 64; bo += 64;
;     }
; #pragma unroll
;     for (int ks = 0; ks < 4; ++ks) {
;       h8v af[4], bf[2];
; #pragma unroll
;       for (int i = 0; i < 4; ++i) af[i] = *(const h8v*)&As[(wm * 128 + i * 32 + (lane & 31)) * LDH + ks * 16 + 8 * (lane >> 5)];
; #pragma unroll
;       for (int j = 0; j < 2; ++j) bf[j] = *(const h8v*)&Bs[(wn * 64 + j * 32 + (lane & 31)) * LDH + ks * 16 + 8 * (lane >> 5)];
; #pragma unroll
;       for (int i = 0; i < 4; ++i)
; #pragma unroll
;         for (int j = 0; j < 2; ++j) acc[i][j] = mfma32(bf[j], af[i], acc[i][j]);
;     }
;     __syncthreads();
;   }
	ds_read_b128 v[232:235], v213
	ds_read_b128 v[188:191], v199
	ds_read_b128 v[236:239], v213 offset:4608
	ds_read_b128 v[200:203], v199 offset:4608
	ds_read_b128 v[204:207], v199 offset:9216
	ds_read_b128 v[208:211], v199 offset:13824
	v_mfma_f32_32x32x16_f16 v[114:129], v[240:243], v[216:219], v[114:129]
	v_mfma_f32_32x32x16_f16 v[98:113], v[244:247], v[216:219], v[98:113]
	v_mfma_f32_32x32x16_f16 v[82:97], v[240:243], v[220:223], v[82:97]
	v_mfma_f32_32x32x16_f16 v[66:81], v[244:247], v[220:223], v[66:81]
	v_mfma_f32_32x32x16_f16 v[50:65], v[240:243], v[224:227], v[50:65]
	v_mfma_f32_32x32x16_f16 v[34:49], v[244:247], v[224:227], v[34:49]
	v_mfma_f32_32x32x16_f16 v[18:33], v[240:243], v[228:231], v[18:33]
	v_mfma_f32_32x32x16_f16 v[2:17], v[244:247], v[228:231], v[2:17]
	ds_read_b128 v[240:243], v213 offset:32
	ds_read_b128 v[216:219], v199 offset:32
	ds_read_b128 v[244:247], v213 offset:4640
	ds_read_b128 v[220:223], v199 offset:4640
	ds_read_b128 v[224:227], v199 offset:9248
	ds_read_b128 v[228:231], v199 offset:13856
	s_waitcnt vmcnt(4)
	ds_write_b128 v163, v[130:133]
	ds_write_b128 v163, v[134:137] offset:16
	ds_write_b128 v163, v[138:141] offset:32
	ds_write_b128 v163, v[142:145] offset:48
	global_load_dwordx4 v[130:133], v[164:165], off offset:896
	global_load_dwordx4 v[134:137], v[164:165], off offset:912
	global_load_dwordx4 v[138:141], v[164:165], off offset:928
	global_load_dwordx4 v[142:145], v[164:165], off offset:944
	s_waitcnt lgkmcnt(14)
	v_mfma_f32_32x32x16_f16 v[114:129], v[232:235], v[188:191], v[114:129]
	s_waitcnt lgkmcnt(13)
	v_mfma_f32_32x32x16_f16 v[98:113], v[236:239], v[188:191], v[98:113]
	s_waitcnt lgkmcnt(12)
	v_mfma_f32_32x32x16_f16 v[82:97], v[232:235], v[200:203], v[82:97]
	v_mfma_f32_32x32x16_f16 v[66:81], v[236:239], v[200:203], v[66:81]
	s_waitcnt lgkmcnt(11)
	v_mfma_f32_32x32x16_f16 v[50:65], v[232:235], v[204:207], v[50:65]
	v_mfma_f32_32x32x16_f16 v[34:49], v[236:239], v[204:207], v[34:49]
	s_waitcnt lgkmcnt(10)
	v_mfma_f32_32x32x16_f16 v[18:33], v[232:235], v[208:211], v[18:33]
	v_mfma_f32_32x32x16_f16 v[2:17], v[236:239], v[208:211], v[2:17]
	ds_read_b128 v[232:235], v213 offset:64
	ds_read_b128 v[188:191], v199 offset:64
	ds_read_b128 v[236:239], v213 offset:4672
	ds_read_b128 v[200:203], v199 offset:4672
	ds_read_b128 v[204:207], v199 offset:9280
	ds_read_b128 v[208:211], v199 offset:13888
	s_waitcnt vmcnt(4)
	ds_write_b128 v163, v[146:149] offset:36864
	ds_write_b128 v163, v[150:153] offset:36880
	ds_write_b128 v163, v[154:157] offset:36896
	ds_write_b128 v163, v[158:161] offset:36912
	global_load_dwordx4 v[146:149], v[192:193], off offset:896
	global_load_dwordx4 v[150:153], v[192:193], off offset:912
	global_load_dwordx4 v[154:157], v[192:193], off offset:928
	global_load_dwordx4 v[158:161], v[192:193], off offset:944
	s_waitcnt lgkmcnt(15)
	v_mfma_f32_32x32x16_f16 v[114:129], v[240:243], v[216:219], v[114:129]
	s_waitcnt lgkmcnt(15)
	v_mfma_f32_32x32x16_f16 v[98:113], v[244:247], v[216:219], v[98:113]
	s_waitcnt lgkmcnt(15)
	v_mfma_f32_32x32x16_f16 v[82:97], v[240:243], v[220:223], v[82:97]
	v_mfma_f32_32x32x16_f16 v[66:81], v[244:247], v[220:223], v[66:81]
	s_waitcnt lgkmcnt(15)
	v_mfma_f32_32x32x16_f16 v[50:65], v[240:243], v[224:227], v[50:65]
	v_mfma_f32_32x32x16_f16 v[34:49], v[244:247], v[224:227], v[34:49]
	s_waitcnt lgkmcnt(14)
	v_mfma_f32_32x32x16_f16 v[18:33], v[240:243], v[228:231], v[18:33]
	v_mfma_f32_32x32x16_f16 v[2:17], v[244:247], v[228:231], v[2:17]
	ds_read_b128 v[240:243], v213 offset:96
	ds_read_b128 v[216:219], v199 offset:96
	ds_read_b128 v[244:247], v213 offset:4704
	ds_read_b128 v[220:223], v199 offset:4704
	ds_read_b128 v[224:227], v199 offset:9312
	ds_read_b128 v[228:231], v199 offset:13920
	s_waitcnt lgkmcnt(14)
	v_mfma_f32_32x32x16_f16 v[114:129], v[232:235], v[188:191], v[114:129]
	s_waitcnt lgkmcnt(13)
	v_mfma_f32_32x32x16_f16 v[98:113], v[236:239], v[188:191], v[98:113]
	s_waitcnt lgkmcnt(12)
	v_mfma_f32_32x32x16_f16 v[82:97], v[232:235], v[200:203], v[82:97]
	v_mfma_f32_32x32x16_f16 v[66:81], v[236:239], v[200:203], v[66:81]
	s_waitcnt lgkmcnt(11)
	v_mfma_f32_32x32x16_f16 v[50:65], v[232:235], v[204:207], v[50:65]
	v_mfma_f32_32x32x16_f16 v[34:49], v[236:239], v[204:207], v[34:49]
	s_waitcnt lgkmcnt(10)
	v_mfma_f32_32x32x16_f16 v[18:33], v[232:235], v[208:211], v[18:33]
	v_mfma_f32_32x32x16_f16 v[2:17], v[236:239], v[208:211], v[2:17]
	s_waitcnt lgkmcnt(0)
	s_barrier
; DI f16v mfma32(h8v a, h8v b, f16v c) { return __builtin_amdgcn_mfma_f32_32x32x16_f16(a, b, c, 0, 0, 0); }
; template <bool GATHER>
; DI void gemm256_main(const h16* __restrict__ A, int lda, const int* __restrict__ idx, int m0,
;                      const h16* __restrict__ B, int ldb, int n0, int K, h16* lds, f16v (&acc)[4][2]) {
;     ...
;   for (int kt = 0; kt < nk; ++kt) {
;     const h16* As = lds + (kt & 1) * (512 * LDH);
;     const h16* Bs = As + 256 * LDH;
;     h16* Wn = lds + ((kt & 1) ^ 1) * (512 * LDH);
;     if (kt + 1 < nk) {
; #pragma unroll
;       for (int i = 0; i < 4; ++i) { *(u4v*)&Wn[lr * LDH + lc + 8 * i] = ra[i]; *(u4v*)&Wn[(256 + lr) * LDH + lc + 8 * i] = rb[i]; }
;     }
;     if (kt + 2 < nk) {
; #pragma unroll
;       for (int i = 0; i < 4; ++i) { ra[i] = *(const u4v*)(AP_ + 8 * i); rb[i] = *(const u4v*)(BP_ + 8 * i); }
;       ao += 64; bo += 64;
;     }
; #pragma unroll
;     for (int ks = 0; ks < 4; ++ks) {
;       h8v af[4], bf[2];
; #pragma unroll
;       for (int i = 0; i < 4; ++i) af[i] = *(const h8v*)&As[(wm * 128 + i * 32 + (lane & 31)) * LDH + ks * 16 + 8 * (lane >> 5)];
; #pragma unroll
;       for (int j = 0; j < 2; ++j) bf[j] = *(const h8v*)&Bs[(wn * 64 + j * 32 + (lane & 31)) * LDH + ks * 16 + 8 * (lane >> 5)];
; #pragma unroll
;       for (int i = 0; i < 4; ++i)
; #pragma unroll
;         for (int j = 0; j < 2; ++j) acc[i][j] = mfma32(bf[j], af[i], acc[i][j]);
;     }
;     __syncthreads();
;   }
	ds_read_b128 v[232:235], v212
	ds_read_b128 v[188:191], v194
	ds_read_b128 v[236:239], v212 offset:4608
	ds_read_b128 v[200:203], v194 offset:4608
	ds_read_b128 v[204:207], v194 offset:9216
	ds_read_b128 v[208:211], v194 offset:13824
	v_mfma_f32_32x32x16_f16 v[114:129], v[240:243], v[216:219], v[114:129]
	v_mfma_f32_32x32x16_f16 v[98:113], v[244:247], v[216:219], v[98:113]
	v_mfma_f32_32x32x16_f16 v[82:97], v[240:243], v[220:223], v[82:97]
	v_mfma_f32_32x32x16_f16 v[66:81], v[244:247], v[220:223], v[66:81]
	v_mfma_f32_32x32x16_f16 v[50:65], v[240:243], v[224:227], v[50:65]
	v_mfma_f32_32x32x16_f16 v[34:49], v[244:247], v[224:227], v[34:49]
	v_mfma_f32_32x32x16_f16 v[18:33], v[240:243], v[228:231], v[18:33]
	v_mfma_f32_32x32x16_f16 v[2:17], v[244:247], v[228:231], v[2:17]
	ds_read_b128 v[240:243], v212 offset:32
	ds_read_b128 v[216:219], v194 offset:32
	ds_read_b128 v[244:247], v212 offset:4640
	ds_read_b128 v[220:223], v194 offset:4640
	ds_read_b128 v[224:227], v194 offset:9248
	ds_read_b128 v[228:231], v194 offset:13856
	s_waitcnt vmcnt(4)
	ds_write_b128 v175, v[130:133]
	ds_write_b128 v175, v[134:137] offset:16
	ds_write_b128 v175, v[138:141] offset:32
	ds_write_b128 v175, v[142:145] offset:48
	global_load_dwordx4 v[130:133], v[164:165], off offset:1024
	global_load_dwordx4 v[134:137], v[164:165], off offset:1040
	global_load_dwordx4 v[138:141], v[164:165], off offset:1056
	global_load_dwordx4 v[142:145], v[164:165], off offset:1072
	s_waitcnt lgkmcnt(14)
	v_mfma_f32_32x32x16_f16 v[114:129], v[232:235], v[188:191], v[114:129]
	s_waitcnt lgkmcnt(13)
	v_mfma_f32_32x32x16_f16 v[98:113], v[236:239], v[188:191], v[98:113]
	s_waitcnt lgkmcnt(12)
	v_mfma_f32_32x32x16_f16 v[82:97], v[232:235], v[200:203], v[82:97]
	v_mfma_f32_32x32x16_f16 v[66:81], v[236:239], v[200:203], v[66:81]
	s_waitcnt lgkmcnt(11)
	v_mfma_f32_32x32x16_f16 v[50:65], v[232:235], v[204:207], v[50:65]
	v_mfma_f32_32x32x16_f16 v[34:49], v[236:239], v[204:207], v[34:49]
	s_waitcnt lgkmcnt(10)
	v_mfma_f32_32x32x16_f16 v[18:33], v[232:235], v[208:211], v[18:33]
	v_mfma_f32_32x32x16_f16 v[2:17], v[236:239], v[208:211], v[2:17]
	ds_read_b128 v[232:235], v212 offset:64
	ds_read_b128 v[188:191], v194 offset:64
	ds_read_b128 v[236:239], v212 offset:4672
	ds_read_b128 v[200:203], v194 offset:4672
	ds_read_b128 v[204:207], v194 offset:9280
	ds_read_b128 v[208:211], v194 offset:13888
	s_waitcnt vmcnt(4)
	ds_write_b128 v175, v[146:149] offset:36864
	ds_write_b128 v175, v[150:153] offset:36880
	ds_write_b128 v175, v[154:157] offset:36896
	ds_write_b128 v175, v[158:161] offset:36912
	global_load_dwordx4 v[146:149], v[192:193], off offset:1024
	global_load_dwordx4 v[150:153], v[192:193], off offset:1040
	global_load_dwordx4 v[154:157], v[192:193], off offset:1056
	global_load_dwordx4 v[158:161], v[192:193], off offset:1072
	s_waitcnt lgkmcnt(15)
	v_mfma_f32_32x32x16_f16 v[114:129], v[240:243], v[216:219], v[114:129]
	s_waitcnt lgkmcnt(15)
	v_mfma_f32_32x32x16_f16 v[98:113], v[244:247], v[216:219], v[98:113]
	s_waitcnt lgkmcnt(15)
	v_mfma_f32_32x32x16_f16 v[82:97], v[240:243], v[220:223], v[82:97]
	v_mfma_f32_32x32x16_f16 v[66:81], v[244:247], v[220:223], v[66:81]
	s_waitcnt lgkmcnt(15)
	v_mfma_f32_32x32x16_f16 v[50:65], v[240:243], v[224:227], v[50:65]
	v_mfma_f32_32x32x16_f16 v[34:49], v[244:247], v[224:227], v[34:49]
	s_waitcnt lgkmcnt(14)
	v_mfma_f32_32x32x16_f16 v[18:33], v[240:243], v[228:231], v[18:33]
	v_mfma_f32_32x32x16_f16 v[2:17], v[244:247], v[228:231], v[2:17]
	ds_read_b128 v[240:243], v212 offset:96
	ds_read_b128 v[216:219], v194 offset:96
	ds_read_b128 v[244:247], v212 offset:4704
	ds_read_b128 v[220:223], v194 offset:4704
	ds_read_b128 v[224:227], v194 offset:9312
	ds_read_b128 v[228:231], v194 offset:13920
	s_waitcnt lgkmcnt(14)
	v_mfma_f32_32x32x16_f16 v[114:129], v[232:235], v[188:191], v[114:129]
	s_waitcnt lgkmcnt(13)
	v_mfma_f32_32x32x16_f16 v[98:113], v[236:239], v[188:191], v[98:113]
	s_waitcnt lgkmcnt(12)
	v_mfma_f32_32x32x16_f16 v[82:97], v[232:235], v[200:203], v[82:97]
	v_mfma_f32_32x32x16_f16 v[66:81], v[236:239], v[200:203], v[66:81]
	s_waitcnt lgkmcnt(11)
	v_mfma_f32_32x32x16_f16 v[50:65], v[232:235], v[204:207], v[50:65]
	v_mfma_f32_32x32x16_f16 v[34:49], v[236:239], v[204:207], v[34:49]
	s_waitcnt lgkmcnt(10)
	v_mfma_f32_32x32x16_f16 v[18:33], v[232:235], v[208:211], v[18:33]
	v_mfma_f32_32x32x16_f16 v[2:17], v[236:239], v[208:211], v[2:17]
	s_waitcnt lgkmcnt(0)
	s_barrier
; DI f16v mfma32(h8v a, h8v b, f16v c) { return __builtin_amdgcn_mfma_f32_32x32x16_f16(a, b, c, 0, 0, 0); }
; template <bool GATHER>
; DI void gemm256_main(const h16* __restrict__ A, int lda, const int* __restrict__ idx, int m0,
;                      const h16* __restrict__ B, int ldb, int n0, int K, h16* lds, f16v (&acc)[4][2]) {
;     ...
;   for (int kt = 0; kt < nk; ++kt) {
;     const h16* As = lds + (kt & 1) * (512 * LDH);
;     const h16* Bs = As + 256 * LDH;
;     h16* Wn = lds + ((kt & 1) ^ 1) * (512 * LDH);
;     if (kt + 1 < nk) {
; #pragma unroll
;       for (int i = 0; i < 4; ++i) { *(u4v*)&Wn[lr * LDH + lc + 8 * i] = ra[i]; *(u4v*)&Wn[(256 + lr) * LDH + lc + 8 * i] = rb[i]; }
;     }
;     if (kt + 2 < nk) {
; #pragma unroll
;       for (int i = 0; i < 4; ++i) { ra[i] = *(const u4v*)(AP_ + 8 * i); rb[i] = *(const u4v*)(BP_ + 8 * i); }
;       ao += 64; bo += 64;
;     }
; #pragma unroll
;     for (int ks = 0; ks < 4; ++ks) {
;       h8v af[4], bf[2];
; #pragma unroll
;       for (int i = 0; i < 4; ++i) af[i] = *(const h8v*)&As[(wm * 128 + i * 32 + (lane & 31)) * LDH + ks * 16 + 8 * (lane >> 5)];
; #pragma unroll
;       for (int j = 0; j < 2; ++j) bf[j] = *(const h8v*)&Bs[(wn * 64 + j * 32 + (lane & 31)) * LDH + ks * 16 + 8 * (lane >> 5)];
; #pragma unroll
;       for (int i = 0; i < 4; ++i)
; #pragma unroll
;         for (int j = 0; j < 2; ++j) acc[i][j] = mfma32(bf[j], af[i], acc[i][j]);
;     }
;     __syncthreads();
;   }
	ds_read_b128 v[232:235], v213
	ds_read_b128 v[188:191], v199
	ds_read_b128 v[236:239], v213 offset:4608
	ds_read_b128 v[200:203], v199 offset:4608
	ds_read_b128 v[204:207], v199 offset:9216
	ds_read_b128 v[208:211], v199 offset:13824
	v_mfma_f32_32x32x16_f16 v[114:129], v[240:243], v[216:219], v[114:129]
	v_mfma_f32_32x32x16_f16 v[98:113], v[244:247], v[216:219], v[98:113]
	v_mfma_f32_32x32x16_f16 v[82:97], v[240:243], v[220:223], v[82:97]
	v_mfma_f32_32x32x16_f16 v[66:81], v[244:247], v[220:223], v[66:81]
	v_mfma_f32_32x32x16_f16 v[50:65], v[240:243], v[224:227], v[50:65]
	v_mfma_f32_32x32x16_f16 v[34:49], v[244:247], v[224:227], v[34:49]
	v_mfma_f32_32x32x16_f16 v[18:33], v[240:243], v[228:231], v[18:33]
	v_mfma_f32_32x32x16_f16 v[2:17], v[244:247], v[228:231], v[2:17]
	ds_read_b128 v[240:243], v213 offset:32
	ds_read_b128 v[216:219], v199 offset:32
	ds_read_b128 v[244:247], v213 offset:4640
	ds_read_b128 v[220:223], v199 offset:4640
	ds_read_b128 v[224:227], v199 offset:9248
	ds_read_b128 v[228:231], v199 offset:13856
	s_waitcnt vmcnt(4)
	ds_write_b128 v163, v[130:133]
	ds_write_b128 v163, v[134:137] offset:16
	ds_write_b128 v163, v[138:141] offset:32
	ds_write_b128 v163, v[142:145] offset:48
	global_load_dwordx4 v[130:133], v[164:165], off offset:1152
	global_load_dwordx4 v[134:137], v[164:165], off offset:1168
	global_load_dwordx4 v[138:141], v[164:165], off offset:1184
	global_load_dwordx4 v[142:145], v[164:165], off offset:1200
	s_waitcnt lgkmcnt(14)
	v_mfma_f32_32x32x16_f16 v[114:129], v[232:235], v[188:191], v[114:129]
	s_waitcnt lgkmcnt(13)
	v_mfma_f32_32x32x16_f16 v[98:113], v[236:239], v[188:191], v[98:113]
	s_waitcnt lgkmcnt(12)
	v_mfma_f32_32x32x16_f16 v[82:97], v[232:235], v[200:203], v[82:97]
	v_mfma_f32_32x32x16_f16 v[66:81], v[236:239], v[200:203], v[66:81]
	s_waitcnt lgkmcnt(11)
	v_mfma_f32_32x32x16_f16 v[50:65], v[232:235], v[204:207], v[50:65]
	v_mfma_f32_32x32x16_f16 v[34:49], v[236:239], v[204:207], v[34:49]
	s_waitcnt lgkmcnt(10)
	v_mfma_f32_32x32x16_f16 v[18:33], v[232:235], v[208:211], v[18:33]
	v_mfma_f32_32x32x16_f16 v[2:17], v[236:239], v[208:211], v[2:17]
	ds_read_b128 v[232:235], v213 offset:64
	ds_read_b128 v[188:191], v199 offset:64
	ds_read_b128 v[236:239], v213 offset:4672
	ds_read_b128 v[200:203], v199 offset:4672
	ds_read_b128 v[204:207], v199 offset:9280
	ds_read_b128 v[208:211], v199 offset:13888
	s_waitcnt vmcnt(4)
	ds_write_b128 v163, v[146:149] offset:36864
	ds_write_b128 v163, v[150:153] offset:36880
	ds_write_b128 v163, v[154:157] offset:36896
	ds_write_b128 v163, v[158:161] offset:36912
	global_load_dwordx4 v[146:149], v[192:193], off offset:1152
	global_load_dwordx4 v[150:153], v[192:193], off offset:1168
	global_load_dwordx4 v[154:157], v[192:193], off offset:1184
	global_load_dwordx4 v[158:161], v[192:193], off offset:1200
	s_waitcnt lgkmcnt(15)
	v_mfma_f32_32x32x16_f16 v[114:129], v[240:243], v[216:219], v[114:129]
	s_waitcnt lgkmcnt(15)
	v_mfma_f32_32x32x16_f16 v[98:113], v[244:247], v[216:219], v[98:113]
	s_waitcnt lgkmcnt(15)
	v_mfma_f32_32x32x16_f16 v[82:97], v[240:243], v[220:223], v[82:97]
	v_mfma_f32_32x32x16_f16 v[66:81], v[244:247], v[220:223], v[66:81]
	s_waitcnt lgkmcnt(15)
	v_mfma_f32_32x32x16_f16 v[50:65], v[240:243], v[224:227], v[50:65]
	v_mfma_f32_32x32x16_f16 v[34:49], v[244:247], v[224:227], v[34:49]
	s_waitcnt lgkmcnt(14)
	v_mfma_f32_32x32x16_f16 v[18:33], v[240:243], v[228:231], v[18:33]
	v_mfma_f32_32x32x16_f16 v[2:17], v[244:247], v[228:231], v[2:17]
	ds_read_b128 v[240:243], v213 offset:96
	ds_read_b128 v[216:219], v199 offset:96
	ds_read_b128 v[244:247], v213 offset:4704
	ds_read_b128 v[220:223], v199 offset:4704
	ds_read_b128 v[224:227], v199 offset:9312
	ds_read_b128 v[228:231], v199 offset:13920
	s_waitcnt lgkmcnt(14)
	v_mfma_f32_32x32x16_f16 v[114:129], v[232:235], v[188:191], v[114:129]
	s_waitcnt lgkmcnt(13)
	v_mfma_f32_32x32x16_f16 v[98:113], v[236:239], v[188:191], v[98:113]
	s_waitcnt lgkmcnt(12)
	v_mfma_f32_32x32x16_f16 v[82:97], v[232:235], v[200:203], v[82:97]
	v_mfma_f32_32x32x16_f16 v[66:81], v[236:239], v[200:203], v[66:81]
	s_waitcnt lgkmcnt(11)
	v_mfma_f32_32x32x16_f16 v[50:65], v[232:235], v[204:207], v[50:65]
	v_mfma_f32_32x32x16_f16 v[34:49], v[236:239], v[204:207], v[34:49]
	s_waitcnt lgkmcnt(10)
	v_mfma_f32_32x32x16_f16 v[18:33], v[232:235], v[208:211], v[18:33]
	v_mfma_f32_32x32x16_f16 v[2:17], v[236:239], v[208:211], v[2:17]
	s_waitcnt lgkmcnt(0)
	s_barrier
; DI f16v mfma32(h8v a, h8v b, f16v c) { return __builtin_amdgcn_mfma_f32_32x32x16_f16(a, b, c, 0, 0, 0); }
; template <bool GATHER>
; DI void gemm256_main(const h16* __restrict__ A, int lda, const int* __restrict__ idx, int m0,
;                      const h16* __restrict__ B, int ldb, int n0, int K, h16* lds, f16v (&acc)[4][2]) {
;     ...
;   for (int kt = 0; kt < nk; ++kt) {
;     const h16* As = lds + (kt & 1) * (512 * LDH);
;     const h16* Bs = As + 256 * LDH;
;     h16* Wn = lds + ((kt & 1) ^ 1) * (512 * LDH);
;     if (kt + 1 < nk) {
; #pragma unroll
;       for (int i = 0; i < 4; ++i) { *(u4v*)&Wn[lr * LDH + lc + 8 * i] = ra[i]; *(u4v*)&Wn[(256 + lr) * LDH + lc + 8 * i] = rb[i]; }
;     }
;     if (kt + 2 < nk) {
; #pragma unroll
;       for (int i = 0; i < 4; ++i) { ra[i] = *(const u4v*)(AP_ + 8 * i); rb[i] = *(const u4v*)(BP_ + 8 * i); }
;       ao += 64; bo += 64;
;     }
; #pragma unroll
;     for (int ks = 0; ks < 4; ++ks) {
;       h8v af[4], bf[2];
; #pragma unroll
;       for (int i = 0; i < 4; ++i) af[i] = *(const h8v*)&As[(wm * 128 + i * 32 + (lane & 31)) * LDH + ks * 16 + 8 * (lane >> 5)];
; #pragma unroll
;       for (int j = 0; j < 2; ++j) bf[j] = *(const h8v*)&Bs[(wn * 64 + j * 32 + (lane & 31)) * LDH + ks * 16 + 8 * (lane >> 5)];
; #pragma unroll
;       for (int i = 0; i < 4; ++i)
; #pragma unroll
;         for (int j = 0; j < 2; ++j) acc[i][j] = mfma32(bf[j], af[i], acc[i][j]);
;     }
;     __syncthreads();
;   }
	ds_read_b128 v[232:235], v212
	ds_read_b128 v[188:191], v194
	ds_read_b128 v[236:239], v212 offset:4608
	ds_read_b128 v[200:203], v194 offset:4608
	ds_read_b128 v[204:207], v194 offset:9216
	ds_read_b128 v[208:211], v194 offset:13824
	v_mfma_f32_32x32x16_f16 v[114:129], v[240:243], v[216:219], v[114:129]
	v_mfma_f32_32x32x16_f16 v[98:113], v[244:247], v[216:219], v[98:113]
	v_mfma_f32_32x32x16_f16 v[82:97], v[240:243], v[220:223], v[82:97]
	v_mfma_f32_32x32x16_f16 v[66:81], v[244:247], v[220:223], v[66:81]
	v_mfma_f32_32x32x16_f16 v[50:65], v[240:243], v[224:227], v[50:65]
	v_mfma_f32_32x32x16_f16 v[34:49], v[244:247], v[224:227], v[34:49]
	v_mfma_f32_32x32x16_f16 v[18:33], v[240:243], v[228:231], v[18:33]
	v_mfma_f32_32x32x16_f16 v[2:17], v[244:247], v[228:231], v[2:17]
	ds_read_b128 v[240:243], v212 offset:32
	ds_read_b128 v[216:219], v194 offset:32
	ds_read_b128 v[244:247], v212 offset:4640
	ds_read_b128 v[220:223], v194 offset:4640
	ds_read_b128 v[224:227], v194 offset:9248
	ds_read_b128 v[228:231], v194 offset:13856
	s_waitcnt vmcnt(4)
	ds_write_b128 v175, v[130:133]
	ds_write_b128 v175, v[134:137] offset:16
	ds_write_b128 v175, v[138:141] offset:32
	ds_write_b128 v175, v[142:145] offset:48
	global_load_dwordx4 v[130:133], v[164:165], off offset:1280
	global_load_dwordx4 v[134:137], v[164:165], off offset:1296
	global_load_dwordx4 v[138:141], v[164:165], off offset:1312
	global_load_dwordx4 v[142:145], v[164:165], off offset:1328
	s_waitcnt lgkmcnt(14)
	v_mfma_f32_32x32x16_f16 v[114:129], v[232:235], v[188:191], v[114:129]
	s_waitcnt lgkmcnt(13)
	v_mfma_f32_32x32x16_f16 v[98:113], v[236:239], v[188:191], v[98:113]
	s_waitcnt lgkmcnt(12)
	v_mfma_f32_32x32x16_f16 v[82:97], v[232:235], v[200:203], v[82:97]
	v_mfma_f32_32x32x16_f16 v[66:81], v[236:239], v[200:203], v[66:81]
	s_waitcnt lgkmcnt(11)
	v_mfma_f32_32x32x16_f16 v[50:65], v[232:235], v[204:207], v[50:65]
	v_mfma_f32_32x32x16_f16 v[34:49], v[236:239], v[204:207], v[34:49]
	s_waitcnt lgkmcnt(10)
	v_mfma_f32_32x32x16_f16 v[18:33], v[232:235], v[208:211], v[18:33]
	v_mfma_f32_32x32x16_f16 v[2:17], v[236:239], v[208:211], v[2:17]
	ds_read_b128 v[232:235], v212 offset:64
	ds_read_b128 v[188:191], v194 offset:64
	ds_read_b128 v[236:239], v212 offset:4672
	ds_read_b128 v[200:203], v194 offset:4672
	ds_read_b128 v[204:207], v194 offset:9280
	ds_read_b128 v[208:211], v194 offset:13888
	s_waitcnt vmcnt(4)
	ds_write_b128 v175, v[146:149] offset:36864
	ds_write_b128 v175, v[150:153] offset:36880
	ds_write_b128 v175, v[154:157] offset:36896
	ds_write_b128 v175, v[158:161] offset:36912
	global_load_dwordx4 v[146:149], v[192:193], off offset:1280
	global_load_dwordx4 v[150:153], v[192:193], off offset:1296
	global_load_dwordx4 v[154:157], v[192:193], off offset:1312
	global_load_dwordx4 v[158:161], v[192:193], off offset:1328
	s_waitcnt lgkmcnt(15)
	v_mfma_f32_32x32x16_f16 v[114:129], v[240:243], v[216:219], v[114:129]
	s_waitcnt lgkmcnt(15)
	v_mfma_f32_32x32x16_f16 v[98:113], v[244:247], v[216:219], v[98:113]
	s_waitcnt lgkmcnt(15)
	v_mfma_f32_32x32x16_f16 v[82:97], v[240:243], v[220:223], v[82:97]
	v_mfma_f32_32x32x16_f16 v[66:81], v[244:247], v[220:223], v[66:81]
	s_waitcnt lgkmcnt(15)
	v_mfma_f32_32x32x16_f16 v[50:65], v[240:243], v[224:227], v[50:65]
	v_mfma_f32_32x32x16_f16 v[34:49], v[244:247], v[224:227], v[34:49]
	s_waitcnt lgkmcnt(14)
	v_mfma_f32_32x32x16_f16 v[18:33], v[240:243], v[228:231], v[18:33]
	v_mfma_f32_32x32x16_f16 v[2:17], v[244:247], v[228:231], v[2:17]
	ds_read_b128 v[240:243], v212 offset:96
	ds_read_b128 v[216:219], v194 offset:96
	ds_read_b128 v[244:247], v212 offset:4704
	ds_read_b128 v[220:223], v194 offset:4704
	ds_read_b128 v[224:227], v194 offset:9312
	ds_read_b128 v[228:231], v194 offset:13920
	s_waitcnt lgkmcnt(14)
	v_mfma_f32_32x32x16_f16 v[114:129], v[232:235], v[188:191], v[114:129]
	s_waitcnt lgkmcnt(13)
	v_mfma_f32_32x32x16_f16 v[98:113], v[236:239], v[188:191], v[98:113]
	s_waitcnt lgkmcnt(12)
	v_mfma_f32_32x32x16_f16 v[82:97], v[232:235], v[200:203], v[82:97]
	v_mfma_f32_32x32x16_f16 v[66:81], v[236:239], v[200:203], v[66:81]
	s_waitcnt lgkmcnt(11)
	v_mfma_f32_32x32x16_f16 v[50:65], v[232:235], v[204:207], v[50:65]
	v_mfma_f32_32x32x16_f16 v[34:49], v[236:239], v[204:207], v[34:49]
	s_waitcnt lgkmcnt(10)
	v_mfma_f32_32x32x16_f16 v[18:33], v[232:235], v[208:211], v[18:33]
	v_mfma_f32_32x32x16_f16 v[2:17], v[236:239], v[208:211], v[2:17]
	s_waitcnt lgkmcnt(0)
	s_barrier
; DI f16v mfma32(h8v a, h8v b, f16v c) { return __builtin_amdgcn_mfma_f32_32x32x16_f16(a, b, c, 0, 0, 0); }
; template <bool GATHER>
; DI void gemm256_main(const h16* __restrict__ A, int lda, const int* __restrict__ idx, int m0,
;                      const h16* __restrict__ B, int ldb, int n0, int K, h16* lds, f16v (&acc)[4][2]) {
;     ...
;   for (int kt = 0; kt < nk; ++kt) {
;     const h16* As = lds + (kt & 1) * (512 * LDH);
;     const h16* Bs = As + 256 * LDH;
;     h16* Wn = lds + ((kt & 1) ^ 1) * (512 * LDH);
;     if (kt + 1 < nk) {
; #pragma unroll
;       for (int i = 0; i < 4; ++i) { *(u4v*)&Wn[lr * LDH + lc + 8 * i] = ra[i]; *(u4v*)&Wn[(256 + lr) * LDH + lc + 8 * i] = rb[i]; }
;     }
;     if (kt + 2 < nk) {
; #pragma unroll
;       for (int i = 0; i < 4; ++i) { ra[i] = *(const u4v*)(AP_ + 8 * i); rb[i] = *(const u4v*)(BP_ + 8 * i); }
;       ao += 64; bo += 64;
;     }
; #pragma unroll
;     for (int ks = 0; ks < 4; ++ks) {
;       h8v af[4], bf[2];
; #pragma unroll
;       for (int i = 0; i < 4; ++i) af[i] = *(const h8v*)&As[(wm * 128 + i * 32 + (lane & 31)) * LDH + ks * 16 + 8 * (lane >> 5)];
; #pragma unroll
;       for (int j = 0; j < 2; ++j) bf[j] = *(const h8v*)&Bs[(wn * 64 + j * 32 + (lane & 31)) * LDH + ks * 16 + 8 * (lane >> 5)];
; #pragma unroll
;       for (int i = 0; i < 4; ++i)
; #pragma unroll
;         for (int j = 0; j < 2; ++j) acc[i][j] = mfma32(bf[j], af[i], acc[i][j]);
;     }
;     __syncthreads();
;   }
	ds_read_b128 v[232:235], v213
	ds_read_b128 v[188:191], v199
	ds_read_b128 v[236:239], v213 offset:4608
	ds_read_b128 v[200:203], v199 offset:4608
	ds_read_b128 v[204:207], v199 offset:9216
	ds_read_b128 v[208:211], v199 offset:13824
	v_mfma_f32_32x32x16_f16 v[114:129], v[240:243], v[216:219], v[114:129]
	v_mfma_f32_32x32x16_f16 v[98:113], v[244:247], v[216:219], v[98:113]
	v_mfma_f32_32x32x16_f16 v[82:97], v[240:243], v[220:223], v[82:97]
	v_mfma_f32_32x32x16_f16 v[66:81], v[244:247], v[220:223], v[66:81]
	v_mfma_f32_32x32x16_f16 v[50:65], v[240:243], v[224:227], v[50:65]
	v_mfma_f32_32x32x16_f16 v[34:49], v[244:247], v[224:227], v[34:49]
	v_mfma_f32_32x32x16_f16 v[18:33], v[240:243], v[228:231], v[18:33]
	v_mfma_f32_32x32x16_f16 v[2:17], v[244:247], v[228:231], v[2:17]
	ds_read_b128 v[240:243], v213 offset:32
	ds_read_b128 v[216:219], v199 offset:32
	ds_read_b128 v[244:247], v213 offset:4640
	ds_read_b128 v[220:223], v199 offset:4640
	ds_read_b128 v[224:227], v199 offset:9248
	ds_read_b128 v[228:231], v199 offset:13856
	s_waitcnt vmcnt(4)
	ds_write_b128 v163, v[130:133]
	ds_write_b128 v163, v[134:137] offset:16
	ds_write_b128 v163, v[138:141] offset:32
	ds_write_b128 v163, v[142:145] offset:48
	global_load_dwordx4 v[130:133], v[164:165], off offset:1408
	global_load_dwordx4 v[134:137], v[164:165], off offset:1424
	global_load_dwordx4 v[138:141], v[164:165], off offset:1440
	global_load_dwordx4 v[142:145], v[164:165], off offset:1456
	s_waitcnt lgkmcnt(14)
	v_mfma_f32_32x32x16_f16 v[114:129], v[232:235], v[188:191], v[114:129]
	s_waitcnt lgkmcnt(13)
	v_mfma_f32_32x32x16_f16 v[98:113], v[236:239], v[188:191], v[98:113]
	s_waitcnt lgkmcnt(12)
	v_mfma_f32_32x32x16_f16 v[82:97], v[232:235], v[200:203], v[82:97]
	v_mfma_f32_32x32x16_f16 v[66:81], v[236:239], v[200:203], v[66:81]
	s_waitcnt lgkmcnt(11)
	v_mfma_f32_32x32x16_f16 v[50:65], v[232:235], v[204:207], v[50:65]
	v_mfma_f32_32x32x16_f16 v[34:49], v[236:239], v[204:207], v[34:49]
	s_waitcnt lgkmcnt(10)
	v_mfma_f32_32x32x16_f16 v[18:33], v[232:235], v[208:211], v[18:33]
	v_mfma_f32_32x32x16_f16 v[2:17], v[236:239], v[208:211], v[2:17]
	ds_read_b128 v[232:235], v213 offset:64
	ds_read_b128 v[188:191], v199 offset:64
	ds_read_b128 v[236:239], v213 offset:4672
	ds_read_b128 v[200:203], v199 offset:4672
	ds_read_b128 v[204:207], v199 offset:9280
	ds_read_b128 v[208:211], v199 offset:13888
	s_waitcnt vmcnt(4)
	ds_write_b128 v163, v[146:149] offset:36864
	ds_write_b128 v163, v[150:153] offset:36880
	ds_write_b128 v163, v[154:157] offset:36896
	ds_write_b128 v163, v[158:161] offset:36912
	global_load_dwordx4 v[146:149], v[192:193], off offset:1408
	global_load_dwordx4 v[150:153], v[192:193], off offset:1424
	global_load_dwordx4 v[154:157], v[192:193], off offset:1440
	global_load_dwordx4 v[158:161], v[192:193], off offset:1456
	s_waitcnt lgkmcnt(15)
	v_mfma_f32_32x32x16_f16 v[114:129], v[240:243], v[216:219], v[114:129]
	s_waitcnt lgkmcnt(15)
	v_mfma_f32_32x32x16_f16 v[98:113], v[244:247], v[216:219], v[98:113]
	s_waitcnt lgkmcnt(15)
	v_mfma_f32_32x32x16_f16 v[82:97], v[240:243], v[220:223], v[82:97]
	v_mfma_f32_32x32x16_f16 v[66:81], v[244:247], v[220:223], v[66:81]
	s_waitcnt lgkmcnt(15)
	v_mfma_f32_32x32x16_f16 v[50:65], v[240:243], v[224:227], v[50:65]
	v_mfma_f32_32x32x16_f16 v[34:49], v[244:247], v[224:227], v[34:49]
	s_waitcnt lgkmcnt(14)
	v_mfma_f32_32x32x16_f16 v[18:33], v[240:243], v[228:231], v[18:33]
	v_mfma_f32_32x32x16_f16 v[2:17], v[244:247], v[228:231], v[2:17]
	ds_read_b128 v[240:243], v213 offset:96
	ds_read_b128 v[216:219], v199 offset:96
	ds_read_b128 v[244:247], v213 offset:4704
	ds_read_b128 v[220:223], v199 offset:4704
	ds_read_b128 v[224:227], v199 offset:9312
	ds_read_b128 v[228:231], v199 offset:13920
	s_waitcnt lgkmcnt(14)
	v_mfma_f32_32x32x16_f16 v[114:129], v[232:235], v[188:191], v[114:129]
	s_waitcnt lgkmcnt(13)
	v_mfma_f32_32x32x16_f16 v[98:113], v[236:239], v[188:191], v[98:113]
	s_waitcnt lgkmcnt(12)
	v_mfma_f32_32x32x16_f16 v[82:97], v[232:235], v[200:203], v[82:97]
	v_mfma_f32_32x32x16_f16 v[66:81], v[236:239], v[200:203], v[66:81]
	s_waitcnt lgkmcnt(11)
	v_mfma_f32_32x32x16_f16 v[50:65], v[232:235], v[204:207], v[50:65]
	v_mfma_f32_32x32x16_f16 v[34:49], v[236:239], v[204:207], v[34:49]
	s_waitcnt lgkmcnt(10)
	v_mfma_f32_32x32x16_f16 v[18:33], v[232:235], v[208:211], v[18:33]
	v_mfma_f32_32x32x16_f16 v[2:17], v[236:239], v[208:211], v[2:17]
	s_waitcnt lgkmcnt(0)
	s_barrier
; DI f16v mfma32(h8v a, h8v b, f16v c) { return __builtin_amdgcn_mfma_f32_32x32x16_f16(a, b, c, 0, 0, 0); }
; template <bool GATHER>
; DI void gemm256_main(const h16* __restrict__ A, int lda, const int* __restrict__ idx, int m0,
;                      const h16* __restrict__ B, int ldb, int n0, int K, h16* lds, f16v (&acc)[4][2]) {
;     ...
;   for (int kt = 0; kt < nk; ++kt) {
;     const h16* As = lds + (kt & 1) * (512 * LDH);
;     const h16* Bs = As + 256 * LDH;
;     h16* Wn = lds + ((kt & 1) ^ 1) * (512 * LDH);
;     if (kt + 1 < nk) {
; #pragma unroll
;       for (int i = 0; i < 4; ++i) { *(u4v*)&Wn[lr * LDH + lc + 8 * i] = ra[i]; *(u4v*)&Wn[(256 + lr) * LDH + lc + 8 * i] = rb[i]; }
;     }
;     if (kt + 2 < nk) {
; #pragma unroll
;       for (int i = 0; i < 4; ++i) { ra[i] = *(const u4v*)(AP_ + 8 * i); rb[i] = *(const u4v*)(BP_ + 8 * i); }
;       ao += 64; bo += 64;
;     }
; #pragma unroll
;     for (int ks = 0; ks < 4; ++ks) {
;       h8v af[4], bf[2];
; #pragma unroll
;       for (int i = 0; i < 4; ++i) af[i] = *(const h8v*)&As[(wm * 128 + i * 32 + (lane & 31)) * LDH + ks * 16 + 8 * (lane >> 5)];
; #pragma unroll
;       for (int j = 0; j < 2; ++j) bf[j] = *(const h8v*)&Bs[(wn * 64 + j * 32 + (lane & 31)) * LDH + ks * 16 + 8 * (lane >> 5)];
; #pragma unroll
;       for (int i = 0; i < 4; ++i)
; #pragma unroll
;         for (int j = 0; j < 2; ++j) acc[i][j] = mfma32(bf[j], af[i], acc[i][j]);
;     }
;     __syncthreads();
;   }
	ds_read_b128 v[232:235], v212
	ds_read_b128 v[188:191], v194
	ds_read_b128 v[236:239], v212 offset:4608
	ds_read_b128 v[200:203], v194 offset:4608
	ds_read_b128 v[204:207], v194 offset:9216
	ds_read_b128 v[208:211], v194 offset:13824
	v_mfma_f32_32x32x16_f16 v[114:129], v[240:243], v[216:219], v[114:129]
	v_mfma_f32_32x32x16_f16 v[98:113], v[244:247], v[216:219], v[98:113]
	v_mfma_f32_32x32x16_f16 v[82:97], v[240:243], v[220:223], v[82:97]
	v_mfma_f32_32x32x16_f16 v[66:81], v[244:247], v[220:223], v[66:81]
	v_mfma_f32_32x32x16_f16 v[50:65], v[240:243], v[224:227], v[50:65]
	v_mfma_f32_32x32x16_f16 v[34:49], v[244:247], v[224:227], v[34:49]
	v_mfma_f32_32x32x16_f16 v[18:33], v[240:243], v[228:231], v[18:33]
	v_mfma_f32_32x32x16_f16 v[2:17], v[244:247], v[228:231], v[2:17]
	ds_read_b128 v[240:243], v212 offset:32
	ds_read_b128 v[216:219], v194 offset:32
	ds_read_b128 v[244:247], v212 offset:4640
	ds_read_b128 v[220:223], v194 offset:4640
	ds_read_b128 v[224:227], v194 offset:9248
	ds_read_b128 v[228:231], v194 offset:13856
	s_waitcnt vmcnt(4)
	ds_write_b128 v175, v[130:133]
	ds_write_b128 v175, v[134:137] offset:16
	ds_write_b128 v175, v[138:141] offset:32
	ds_write_b128 v175, v[142:145] offset:48
	global_load_dwordx4 v[130:133], v[164:165], off offset:1536
	global_load_dwordx4 v[134:137], v[164:165], off offset:1552
	global_load_dwordx4 v[138:141], v[164:165], off offset:1568
	global_load_dwordx4 v[142:145], v[164:165], off offset:1584
	s_waitcnt lgkmcnt(14)
	v_mfma_f32_32x32x16_f16 v[114:129], v[232:235], v[188:191], v[114:129]
	s_waitcnt lgkmcnt(13)
	v_mfma_f32_32x32x16_f16 v[98:113], v[236:239], v[188:191], v[98:113]
	s_waitcnt lgkmcnt(12)
	v_mfma_f32_32x32x16_f16 v[82:97], v[232:235], v[200:203], v[82:97]
	v_mfma_f32_32x32x16_f16 v[66:81], v[236:239], v[200:203], v[66:81]
	s_waitcnt lgkmcnt(11)
	v_mfma_f32_32x32x16_f16 v[50:65], v[232:235], v[204:207], v[50:65]
	v_mfma_f32_32x32x16_f16 v[34:49], v[236:239], v[204:207], v[34:49]
	s_waitcnt lgkmcnt(10)
	v_mfma_f32_32x32x16_f16 v[18:33], v[232:235], v[208:211], v[18:33]
	v_mfma_f32_32x32x16_f16 v[2:17], v[236:239], v[208:211], v[2:17]
	ds_read_b128 v[232:235], v212 offset:64
	ds_read_b128 v[188:191], v194 offset:64
	ds_read_b128 v[236:239], v212 offset:4672
	ds_read_b128 v[200:203], v194 offset:4672
	ds_read_b128 v[204:207], v194 offset:9280
	ds_read_b128 v[208:211], v194 offset:13888
	s_waitcnt vmcnt(4)
	ds_write_b128 v175, v[146:149] offset:36864
	ds_write_b128 v175, v[150:153] offset:36880
	ds_write_b128 v175, v[154:157] offset:36896
	ds_write_b128 v175, v[158:161] offset:36912
	global_load_dwordx4 v[146:149], v[192:193], off offset:1536
	global_load_dwordx4 v[150:153], v[192:193], off offset:1552
	global_load_dwordx4 v[154:157], v[192:193], off offset:1568
	global_load_dwordx4 v[158:161], v[192:193], off offset:1584
	s_waitcnt lgkmcnt(15)
	v_mfma_f32_32x32x16_f16 v[114:129], v[240:243], v[216:219], v[114:129]
	s_waitcnt lgkmcnt(15)
	v_mfma_f32_32x32x16_f16 v[98:113], v[244:247], v[216:219], v[98:113]
	s_waitcnt lgkmcnt(15)
	v_mfma_f32_32x32x16_f16 v[82:97], v[240:243], v[220:223], v[82:97]
	v_mfma_f32_32x32x16_f16 v[66:81], v[244:247], v[220:223], v[66:81]
	s_waitcnt lgkmcnt(15)
	v_mfma_f32_32x32x16_f16 v[50:65], v[240:243], v[224:227], v[50:65]
	v_mfma_f32_32x32x16_f16 v[34:49], v[244:247], v[224:227], v[34:49]
	s_waitcnt lgkmcnt(14)
	v_mfma_f32_32x32x16_f16 v[18:33], v[240:243], v[228:231], v[18:33]
	v_mfma_f32_32x32x16_f16 v[2:17], v[244:247], v[228:231], v[2:17]
	ds_read_b128 v[240:243], v212 offset:96
	ds_read_b128 v[216:219], v194 offset:96
	ds_read_b128 v[244:247], v212 offset:4704
	ds_read_b128 v[220:223], v194 offset:4704
	ds_read_b128 v[224:227], v194 offset:9312
	ds_read_b128 v[228:231], v194 offset:13920
	s_waitcnt lgkmcnt(14)
	v_mfma_f32_32x32x16_f16 v[114:129], v[232:235], v[188:191], v[114:129]
	s_waitcnt lgkmcnt(13)
	v_mfma_f32_32x32x16_f16 v[98:113], v[236:239], v[188:191], v[98:113]
	s_waitcnt lgkmcnt(12)
	v_mfma_f32_32x32x16_f16 v[82:97], v[232:235], v[200:203], v[82:97]
	v_mfma_f32_32x32x16_f16 v[66:81], v[236:239], v[200:203], v[66:81]
	s_waitcnt lgkmcnt(11)
	v_mfma_f32_32x32x16_f16 v[50:65], v[232:235], v[204:207], v[50:65]
	v_mfma_f32_32x32x16_f16 v[34:49], v[236:239], v[204:207], v[34:49]
	s_waitcnt lgkmcnt(10)
	v_mfma_f32_32x32x16_f16 v[18:33], v[232:235], v[208:211], v[18:33]
	v_mfma_f32_32x32x16_f16 v[2:17], v[236:239], v[208:211], v[2:17]
	s_waitcnt lgkmcnt(0)
	s_barrier
; DI f16v mfma32(h8v a, h8v b, f16v c) { return __builtin_amdgcn_mfma_f32_32x32x16_f16(a, b, c, 0, 0, 0); }
; template <bool GATHER>
; DI void gemm256_main(const h16* __restrict__ A, int lda, const int* __restrict__ idx, int m0,
;                      const h16* __restrict__ B, int ldb, int n0, int K, h16* lds, f16v (&acc)[4][2]) {
;     ...
;   for (int kt = 0; kt < nk; ++kt) {
;     const h16* As = lds + (kt & 1) * (512 * LDH);
;     const h16* Bs = As + 256 * LDH;
;     h16* Wn = lds + ((kt & 1) ^ 1) * (512 * LDH);
;     if (kt + 1 < nk) {
; #pragma unroll
;       for (int i = 0; i < 4; ++i) { *(u4v*)&Wn[lr * LDH + lc + 8 * i] = ra[i]; *(u4v*)&Wn[(256 + lr) * LDH + lc + 8 * i] = rb[i]; }
;     }
;     if (kt + 2 < nk) {
; #pragma unroll
;       for (int i = 0; i < 4; ++i) { ra[i] = *(const u4v*)(AP_ + 8 * i); rb[i] = *(const u4v*)(BP_ + 8 * i); }
;       ao += 64; bo += 64;
;     }
; #pragma unroll
;     for (int ks = 0; ks < 4; ++ks) {
;       h8v af[4], bf[2];
; #pragma unroll
;       for (int i = 0; i < 4; ++i) af[i] = *(const h8v*)&As[(wm * 128 + i * 32 + (lane & 31)) * LDH + ks * 16 + 8 * (lane >> 5)];
; #pragma unroll
;       for (int j = 0; j < 2; ++j) bf[j] = *(const h8v*)&Bs[(wn * 64 + j * 32 + (lane & 31)) * LDH + ks * 16 + 8 * (lane >> 5)];
; #pragma unroll
;       for (int i = 0; i < 4; ++i)
; #pragma unroll
;         for (int j = 0; j < 2; ++j) acc[i][j] = mfma32(bf[j], af[i], acc[i][j]);
;     }
;     __syncthreads();
;   }
	ds_read_b128 v[232:235], v213
	ds_read_b128 v[188:191], v199
	ds_read_b128 v[236:239], v213 offset:4608
	ds_read_b128 v[200:203], v199 offset:4608
	ds_read_b128 v[204:207], v199 offset:9216
	ds_read_b128 v[208:211], v199 offset:13824
	v_mfma_f32_32x32x16_f16 v[114:129], v[240:243], v[216:219], v[114:129]
	v_mfma_f32_32x32x16_f16 v[98:113], v[244:247], v[216:219], v[98:113]
	v_mfma_f32_32x32x16_f16 v[82:97], v[240:243], v[220:223], v[82:97]
	v_mfma_f32_32x32x16_f16 v[66:81], v[244:247], v[220:223], v[66:81]
	v_mfma_f32_32x32x16_f16 v[50:65], v[240:243], v[224:227], v[50:65]
	v_mfma_f32_32x32x16_f16 v[34:49], v[244:247], v[224:227], v[34:49]
	v_mfma_f32_32x32x16_f16 v[18:33], v[240:243], v[228:231], v[18:33]
	v_mfma_f32_32x32x16_f16 v[2:17], v[244:247], v[228:231], v[2:17]
	ds_read_b128 v[240:243], v213 offset:32
	ds_read_b128 v[216:219], v199 offset:32
	ds_read_b128 v[244:247], v213 offset:4640
	ds_read_b128 v[220:223], v199 offset:4640
	ds_read_b128 v[224:227], v199 offset:9248
	ds_read_b128 v[228:231], v199 offset:13856
	s_waitcnt vmcnt(4)
	ds_write_b128 v163, v[130:133]
	ds_write_b128 v163, v[134:137] offset:16
	ds_write_b128 v163, v[138:141] offset:32
	ds_write_b128 v163, v[142:145] offset:48
	global_load_dwordx4 v[130:133], v[164:165], off offset:1664
	global_load_dwordx4 v[134:137], v[164:165], off offset:1680
	global_load_dwordx4 v[138:141], v[164:165], off offset:1696
	global_load_dwordx4 v[142:145], v[164:165], off offset:1712
	s_waitcnt lgkmcnt(14)
	v_mfma_f32_32x32x16_f16 v[114:129], v[232:235], v[188:191], v[114:129]
	s_waitcnt lgkmcnt(13)
	v_mfma_f32_32x32x16_f16 v[98:113], v[236:239], v[188:191], v[98:113]
	s_waitcnt lgkmcnt(12)
	v_mfma_f32_32x32x16_f16 v[82:97], v[232:235], v[200:203], v[82:97]
	v_mfma_f32_32x32x16_f16 v[66:81], v[236:239], v[200:203], v[66:81]
	s_waitcnt lgkmcnt(11)
	v_mfma_f32_32x32x16_f16 v[50:65], v[232:235], v[204:207], v[50:65]
	v_mfma_f32_32x32x16_f16 v[34:49], v[236:239], v[204:207], v[34:49]
	s_waitcnt lgkmcnt(10)
	v_mfma_f32_32x32x16_f16 v[18:33], v[232:235], v[208:211], v[18:33]
	v_mfma_f32_32x32x16_f16 v[2:17], v[236:239], v[208:211], v[2:17]
	ds_read_b128 v[232:235], v213 offset:64
	ds_read_b128 v[188:191], v199 offset:64
	ds_read_b128 v[236:239], v213 offset:4672
	ds_read_b128 v[200:203], v199 offset:4672
	ds_read_b128 v[204:207], v199 offset:9280
	ds_read_b128 v[208:211], v199 offset:13888
	s_waitcnt vmcnt(4)
	ds_write_b128 v163, v[146:149] offset:36864
	ds_write_b128 v163, v[150:153] offset:36880
	ds_write_b128 v163, v[154:157] offset:36896
	ds_write_b128 v163, v[158:161] offset:36912
	global_load_dwordx4 v[146:149], v[192:193], off offset:1664
	global_load_dwordx4 v[150:153], v[192:193], off offset:1680
	global_load_dwordx4 v[154:157], v[192:193], off offset:1696
	global_load_dwordx4 v[158:161], v[192:193], off offset:1712
	s_waitcnt lgkmcnt(15)
	v_mfma_f32_32x32x16_f16 v[114:129], v[240:243], v[216:219], v[114:129]
	s_waitcnt lgkmcnt(15)
	v_mfma_f32_32x32x16_f16 v[98:113], v[244:247], v[216:219], v[98:113]
	s_waitcnt lgkmcnt(15)
	v_mfma_f32_32x32x16_f16 v[82:97], v[240:243], v[220:223], v[82:97]
	v_mfma_f32_32x32x16_f16 v[66:81], v[244:247], v[220:223], v[66:81]
	s_waitcnt lgkmcnt(15)
	v_mfma_f32_32x32x16_f16 v[50:65], v[240:243], v[224:227], v[50:65]
	v_mfma_f32_32x32x16_f16 v[34:49], v[244:247], v[224:227], v[34:49]
	s_waitcnt lgkmcnt(14)
	v_mfma_f32_32x32x16_f16 v[18:33], v[240:243], v[228:231], v[18:33]
	v_mfma_f32_32x32x16_f16 v[2:17], v[244:247], v[228:231], v[2:17]
	ds_read_b128 v[240:243], v213 offset:96
	ds_read_b128 v[216:219], v199 offset:96
	ds_read_b128 v[244:247], v213 offset:4704
	ds_read_b128 v[220:223], v199 offset:4704
	ds_read_b128 v[224:227], v199 offset:9312
	ds_read_b128 v[228:231], v199 offset:13920
	s_waitcnt lgkmcnt(14)
	v_mfma_f32_32x32x16_f16 v[114:129], v[232:235], v[188:191], v[114:129]
	s_waitcnt lgkmcnt(13)
	v_mfma_f32_32x32x16_f16 v[98:113], v[236:239], v[188:191], v[98:113]
	s_waitcnt lgkmcnt(12)
	v_mfma_f32_32x32x16_f16 v[82:97], v[232:235], v[200:203], v[82:97]
	v_mfma_f32_32x32x16_f16 v[66:81], v[236:239], v[200:203], v[66:81]
	s_waitcnt lgkmcnt(11)
	v_mfma_f32_32x32x16_f16 v[50:65], v[232:235], v[204:207], v[50:65]
	v_mfma_f32_32x32x16_f16 v[34:49], v[236:239], v[204:207], v[34:49]
	s_waitcnt lgkmcnt(10)
	v_mfma_f32_32x32x16_f16 v[18:33], v[232:235], v[208:211], v[18:33]
	v_mfma_f32_32x32x16_f16 v[2:17], v[236:239], v[208:211], v[2:17]
	s_waitcnt lgkmcnt(0)
	s_barrier
; DI f16v mfma32(h8v a, h8v b, f16v c) { return __builtin_amdgcn_mfma_f32_32x32x16_f16(a, b, c, 0, 0, 0); }
; template <bool GATHER>
; DI void gemm256_main(const h16* __restrict__ A, int lda, const int* __restrict__ idx, int m0,
;                      const h16* __restrict__ B, int ldb, int n0, int K, h16* lds, f16v (&acc)[4][2]) {
;     ...
;   for (int kt = 0; kt < nk; ++kt) {
;     const h16* As = lds + (kt & 1) * (512 * LDH);
;     const h16* Bs = As + 256 * LDH;
;     h16* Wn = lds + ((kt & 1) ^ 1) * (512 * LDH);
;     if (kt + 1 < nk) {
; #pragma unroll
;       for (int i = 0; i < 4; ++i) { *(u4v*)&Wn[lr * LDH + lc + 8 * i] = ra[i]; *(u4v*)&Wn[(256 + lr) * LDH + lc + 8 * i] = rb[i]; }
;     }
;     if (kt + 2 < nk) {
; #pragma unroll
;       for (int i = 0; i < 4; ++i) { ra[i] = *(const u4v*)(AP_ + 8 * i); rb[i] = *(const u4v*)(BP_ + 8 * i); }
;       ao += 64; bo += 64;
;     }
; #pragma unroll
;     for (int ks = 0; ks < 4; ++ks) {
;       h8v af[4], bf[2];
; #pragma unroll
;       for (int i = 0; i < 4; ++i) af[i] = *(const h8v*)&As[(wm * 128 + i * 32 + (lane & 31)) * LDH + ks * 16 + 8 * (lane >> 5)];
; #pragma unroll
;       for (int j = 0; j < 2; ++j) bf[j] = *(const h8v*)&Bs[(wn * 64 + j * 32 + (lane & 31)) * LDH + ks * 16 + 8 * (lane >> 5)];
; #pragma unroll
;       for (int i = 0; i < 4; ++i)
; #pragma unroll
;         for (int j = 0; j < 2; ++j) acc[i][j] = mfma32(bf[j], af[i], acc[i][j]);
;     }
;     __syncthreads();
;   }
	ds_read_b128 v[232:235], v212
	ds_read_b128 v[188:191], v194
	ds_read_b128 v[236:239], v212 offset:4608
	ds_read_b128 v[200:203], v194 offset:4608
	ds_read_b128 v[204:207], v194 offset:9216
	ds_read_b128 v[208:211], v194 offset:13824
	v_mfma_f32_32x32x16_f16 v[114:129], v[240:243], v[216:219], v[114:129]
	v_mfma_f32_32x32x16_f16 v[98:113], v[244:247], v[216:219], v[98:113]
	v_mfma_f32_32x32x16_f16 v[82:97], v[240:243], v[220:223], v[82:97]
	v_mfma_f32_32x32x16_f16 v[66:81], v[244:247], v[220:223], v[66:81]
	v_mfma_f32_32x32x16_f16 v[50:65], v[240:243], v[224:227], v[50:65]
	v_mfma_f32_32x32x16_f16 v[34:49], v[244:247], v[224:227], v[34:49]
	v_mfma_f32_32x32x16_f16 v[18:33], v[240:243], v[228:231], v[18:33]
	v_mfma_f32_32x32x16_f16 v[2:17], v[244:247], v[228:231], v[2:17]
	ds_read_b128 v[240:243], v212 offset:32
	ds_read_b128 v[216:219], v194 offset:32
	ds_read_b128 v[244:247], v212 offset:4640
	ds_read_b128 v[220:223], v194 offset:4640
	ds_read_b128 v[224:227], v194 offset:9248
	ds_read_b128 v[228:231], v194 offset:13856
	s_waitcnt vmcnt(4)
	ds_write_b128 v175, v[130:133]
	ds_write_b128 v175, v[134:137] offset:16
	ds_write_b128 v175, v[138:141] offset:32
	ds_write_b128 v175, v[142:145] offset:48
	global_load_dwordx4 v[130:133], v[164:165], off offset:1792
	global_load_dwordx4 v[134:137], v[164:165], off offset:1808
	global_load_dwordx4 v[138:141], v[164:165], off offset:1824
	global_load_dwordx4 v[142:145], v[164:165], off offset:1840
	s_waitcnt lgkmcnt(14)
	v_mfma_f32_32x32x16_f16 v[114:129], v[232:235], v[188:191], v[114:129]
	s_waitcnt lgkmcnt(13)
	v_mfma_f32_32x32x16_f16 v[98:113], v[236:239], v[188:191], v[98:113]
	s_waitcnt lgkmcnt(12)
	v_mfma_f32_32x32x16_f16 v[82:97], v[232:235], v[200:203], v[82:97]
	v_mfma_f32_32x32x16_f16 v[66:81], v[236:239], v[200:203], v[66:81]
	s_waitcnt lgkmcnt(11)
	v_mfma_f32_32x32x16_f16 v[50:65], v[232:235], v[204:207], v[50:65]
	v_mfma_f32_32x32x16_f16 v[34:49], v[236:239], v[204:207], v[34:49]
	s_waitcnt lgkmcnt(10)
	v_mfma_f32_32x32x16_f16 v[18:33], v[232:235], v[208:211], v[18:33]
	v_mfma_f32_32x32x16_f16 v[2:17], v[236:239], v[208:211], v[2:17]
	ds_read_b128 v[232:235], v212 offset:64
	ds_read_b128 v[188:191], v194 offset:64
	ds_read_b128 v[236:239], v212 offset:4672
	ds_read_b128 v[200:203], v194 offset:4672
	ds_read_b128 v[204:207], v194 offset:9280
	ds_read_b128 v[208:211], v194 offset:13888
	s_waitcnt vmcnt(4)
	ds_write_b128 v175, v[146:149] offset:36864
	ds_write_b128 v175, v[150:153] offset:36880
	ds_write_b128 v175, v[154:157] offset:36896
	ds_write_b128 v175, v[158:161] offset:36912
	global_load_dwordx4 v[146:149], v[192:193], off offset:1792
	global_load_dwordx4 v[150:153], v[192:193], off offset:1808
	global_load_dwordx4 v[154:157], v[192:193], off offset:1824
	global_load_dwordx4 v[158:161], v[192:193], off offset:1840
	s_waitcnt lgkmcnt(15)
	v_mfma_f32_32x32x16_f16 v[114:129], v[240:243], v[216:219], v[114:129]
	s_waitcnt lgkmcnt(15)
	v_mfma_f32_32x32x16_f16 v[98:113], v[244:247], v[216:219], v[98:113]
	s_waitcnt lgkmcnt(15)
	v_mfma_f32_32x32x16_f16 v[82:97], v[240:243], v[220:223], v[82:97]
	v_mfma_f32_32x32x16_f16 v[66:81], v[244:247], v[220:223], v[66:81]
	s_waitcnt lgkmcnt(15)
	v_mfma_f32_32x32x16_f16 v[50:65], v[240:243], v[224:227], v[50:65]
	v_mfma_f32_32x32x16_f16 v[34:49], v[244:247], v[224:227], v[34:49]
	s_waitcnt lgkmcnt(14)
	v_mfma_f32_32x32x16_f16 v[18:33], v[240:243], v[228:231], v[18:33]
	v_mfma_f32_32x32x16_f16 v[2:17], v[244:247], v[228:231], v[2:17]
	ds_read_b128 v[240:243], v212 offset:96
	ds_read_b128 v[216:219], v194 offset:96
	ds_read_b128 v[244:247], v212 offset:4704
	ds_read_b128 v[220:223], v194 offset:4704
	ds_read_b128 v[224:227], v194 offset:9312
	ds_read_b128 v[228:231], v194 offset:13920
	s_waitcnt lgkmcnt(14)
	v_mfma_f32_32x32x16_f16 v[114:129], v[232:235], v[188:191], v[114:129]
	s_waitcnt lgkmcnt(13)
	v_mfma_f32_32x32x16_f16 v[98:113], v[236:239], v[188:191], v[98:113]
	s_waitcnt lgkmcnt(12)
	v_mfma_f32_32x32x16_f16 v[82:97], v[232:235], v[200:203], v[82:97]
	v_mfma_f32_32x32x16_f16 v[66:81], v[236:239], v[200:203], v[66:81]
	s_waitcnt lgkmcnt(11)
	v_mfma_f32_32x32x16_f16 v[50:65], v[232:235], v[204:207], v[50:65]
	v_mfma_f32_32x32x16_f16 v[34:49], v[236:239], v[204:207], v[34:49]
	s_waitcnt lgkmcnt(10)
	v_mfma_f32_32x32x16_f16 v[18:33], v[232:235], v[208:211], v[18:33]
	v_mfma_f32_32x32x16_f16 v[2:17], v[236:239], v[208:211], v[2:17]
	s_waitcnt lgkmcnt(0)
	s_barrier
; DI f16v mfma32(h8v a, h8v b, f16v c) { return __builtin_amdgcn_mfma_f32_32x32x16_f16(a, b, c, 0, 0, 0); }
; template <bool GATHER>
; DI void gemm256_main(const h16* __restrict__ A, int lda, const int* __restrict__ idx, int m0,
;                      const h16* __restrict__ B, int ldb, int n0, int K, h16* lds, f16v (&acc)[4][2]) {
;     ...
;   for (int kt = 0; kt < nk; ++kt) {
;     const h16* As = lds + (kt & 1) * (512 * LDH);
;     const h16* Bs = As + 256 * LDH;
;     h16* Wn = lds + ((kt & 1) ^ 1) * (512 * LDH);
;     if (kt + 1 < nk) {
; #pragma unroll
;       for (int i = 0; i < 4; ++i) { *(u4v*)&Wn[lr * LDH + lc + 8 * i] = ra[i]; *(u4v*)&Wn[(256 + lr) * LDH + lc + 8 * i] = rb[i]; }
;     }
;     if (kt + 2 < nk) {
; #pragma unroll
;       for (int i = 0; i < 4; ++i) { ra[i] = *(const u4v*)(AP_ + 8 * i); rb[i] = *(const u4v*)(BP_ + 8 * i); }
;       ao += 64; bo += 64;
;     }
; #pragma unroll
;     for (int ks = 0; ks < 4; ++ks) {
;       h8v af[4], bf[2];
; #pragma unroll
;       for (int i = 0; i < 4; ++i) af[i] = *(const h8v*)&As[(wm * 128 + i * 32 + (lane & 31)) * LDH + ks * 16 + 8 * (lane >> 5)];
; #pragma unroll
;       for (int j = 0; j < 2; ++j) bf[j] = *(const h8v*)&Bs[(wn * 64 + j * 32 + (lane & 31)) * LDH + ks * 16 + 8 * (lane >> 5)];
; #pragma unroll
;       for (int i = 0; i < 4; ++i)
; #pragma unroll
;         for (int j = 0; j < 2; ++j) acc[i][j] = mfma32(bf[j], af[i], acc[i][j]);
;     }
;     __syncthreads();
;   }
	ds_read_b128 v[232:235], v213
	ds_read_b128 v[188:191], v199
	ds_read_b128 v[236:239], v213 offset:4608
	ds_read_b128 v[200:203], v199 offset:4608
	ds_read_b128 v[204:207], v199 offset:9216
	ds_read_b128 v[208:211], v199 offset:13824
	v_mfma_f32_32x32x16_f16 v[114:129], v[240:243], v[216:219], v[114:129]
	v_mfma_f32_32x32x16_f16 v[98:113], v[244:247], v[216:219], v[98:113]
	v_mfma_f32_32x32x16_f16 v[82:97], v[240:243], v[220:223], v[82:97]
	v_mfma_f32_32x32x16_f16 v[66:81], v[244:247], v[220:223], v[66:81]
	v_mfma_f32_32x32x16_f16 v[50:65], v[240:243], v[224:227], v[50:65]
	v_mfma_f32_32x32x16_f16 v[34:49], v[244:247], v[224:227], v[34:49]
	v_mfma_f32_32x32x16_f16 v[18:33], v[240:243], v[228:231], v[18:33]
	v_mfma_f32_32x32x16_f16 v[2:17], v[244:247], v[228:231], v[2:17]
	ds_read_b128 v[240:243], v213 offset:32
	ds_read_b128 v[216:219], v199 offset:32
	ds_read_b128 v[244:247], v213 offset:4640
	ds_read_b128 v[220:223], v199 offset:4640
	ds_read_b128 v[224:227], v199 offset:9248
	ds_read_b128 v[228:231], v199 offset:13856
	s_waitcnt vmcnt(4)
	ds_write_b128 v163, v[130:133]
	ds_write_b128 v163, v[134:137] offset:16
	ds_write_b128 v163, v[138:141] offset:32
	ds_write_b128 v163, v[142:145] offset:48
	global_load_dwordx4 v[130:133], v[164:165], off offset:1920
	global_load_dwordx4 v[134:137], v[164:165], off offset:1936
	global_load_dwordx4 v[138:141], v[164:165], off offset:1952
	global_load_dwordx4 v[142:145], v[164:165], off offset:1968
	s_waitcnt lgkmcnt(14)
	v_mfma_f32_32x32x16_f16 v[114:129], v[232:235], v[188:191], v[114:129]
	s_waitcnt lgkmcnt(13)
	v_mfma_f32_32x32x16_f16 v[98:113], v[236:239], v[188:191], v[98:113]
	s_waitcnt lgkmcnt(12)
	v_mfma_f32_32x32x16_f16 v[82:97], v[232:235], v[200:203], v[82:97]
	v_mfma_f32_32x32x16_f16 v[66:81], v[236:239], v[200:203], v[66:81]
	s_waitcnt lgkmcnt(11)
	v_mfma_f32_32x32x16_f16 v[50:65], v[232:235], v[204:207], v[50:65]
	v_mfma_f32_32x32x16_f16 v[34:49], v[236:239], v[204:207], v[34:49]
	s_waitcnt lgkmcnt(10)
	v_mfma_f32_32x32x16_f16 v[18:33], v[232:235], v[208:211], v[18:33]
	v_mfma_f32_32x32x16_f16 v[2:17], v[236:239], v[208:211], v[2:17]
	ds_read_b128 v[232:235], v213 offset:64
	ds_read_b128 v[188:191], v199 offset:64
	ds_read_b128 v[236:239], v213 offset:4672
	ds_read_b128 v[200:203], v199 offset:4672
	ds_read_b128 v[204:207], v199 offset:9280
	ds_read_b128 v[208:211], v199 offset:13888
	s_waitcnt vmcnt(4)
	ds_write_b128 v163, v[146:149] offset:36864
	ds_write_b128 v163, v[150:153] offset:36880
	ds_write_b128 v163, v[154:157] offset:36896
	ds_write_b128 v163, v[158:161] offset:36912
	global_load_dwordx4 v[146:149], v[192:193], off offset:1920
	global_load_dwordx4 v[150:153], v[192:193], off offset:1936
	global_load_dwordx4 v[154:157], v[192:193], off offset:1952
	global_load_dwordx4 v[158:161], v[192:193], off offset:1968
	s_waitcnt lgkmcnt(15)
	v_mfma_f32_32x32x16_f16 v[114:129], v[240:243], v[216:219], v[114:129]
	s_waitcnt lgkmcnt(15)
	v_mfma_f32_32x32x16_f16 v[98:113], v[244:247], v[216:219], v[98:113]
	s_waitcnt lgkmcnt(15)
	v_mfma_f32_32x32x16_f16 v[82:97], v[240:243], v[220:223], v[82:97]
	v_mfma_f32_32x32x16_f16 v[66:81], v[244:247], v[220:223], v[66:81]
	s_waitcnt lgkmcnt(15)
	v_mfma_f32_32x32x16_f16 v[50:65], v[240:243], v[224:227], v[50:65]
	v_mfma_f32_32x32x16_f16 v[34:49], v[244:247], v[224:227], v[34:49]
	s_waitcnt lgkmcnt(14)
	v_mfma_f32_32x32x16_f16 v[18:33], v[240:243], v[228:231], v[18:33]
	v_mfma_f32_32x32x16_f16 v[2:17], v[244:247], v[228:231], v[2:17]
	ds_read_b128 v[240:243], v213 offset:96
	ds_read_b128 v[216:219], v199 offset:96
	ds_read_b128 v[244:247], v213 offset:4704
	ds_read_b128 v[220:223], v199 offset:4704
	ds_read_b128 v[224:227], v199 offset:9312
	ds_read_b128 v[228:231], v199 offset:13920
	s_waitcnt lgkmcnt(14)
	v_mfma_f32_32x32x16_f16 v[114:129], v[232:235], v[188:191], v[114:129]
	s_waitcnt lgkmcnt(13)
	v_mfma_f32_32x32x16_f16 v[98:113], v[236:239], v[188:191], v[98:113]
	s_waitcnt lgkmcnt(12)
	v_mfma_f32_32x32x16_f16 v[82:97], v[232:235], v[200:203], v[82:97]
	v_mfma_f32_32x32x16_f16 v[66:81], v[236:239], v[200:203], v[66:81]
	s_waitcnt lgkmcnt(11)
	v_mfma_f32_32x32x16_f16 v[50:65], v[232:235], v[204:207], v[50:65]
	v_mfma_f32_32x32x16_f16 v[34:49], v[236:239], v[204:207], v[34:49]
	s_waitcnt lgkmcnt(10)
	v_mfma_f32_32x32x16_f16 v[18:33], v[232:235], v[208:211], v[18:33]
	v_mfma_f32_32x32x16_f16 v[2:17], v[236:239], v[208:211], v[2:17]
	s_waitcnt lgkmcnt(0)
	s_barrier
; DI f16v mfma32(h8v a, h8v b, f16v c) { return __builtin_amdgcn_mfma_f32_32x32x16_f16(a, b, c, 0, 0, 0); }
; template <bool GATHER>
; DI void gemm256_main(const h16* __restrict__ A, int lda, const int* __restrict__ idx, int m0,
;                      const h16* __restrict__ B, int ldb, int n0, int K, h16* lds, f16v (&acc)[4][2]) {
;     ...
;   for (int kt = 0; kt < nk; ++kt) {
;     const h16* As = lds + (kt & 1) * (512 * LDH);
;     const h16* Bs = As + 256 * LDH;
;     h16* Wn = lds + ((kt & 1) ^ 1) * (512 * LDH);
;     if (kt + 1 < nk) {
; #pragma unroll
;       for (int i = 0; i < 4; ++i) { *(u4v*)&Wn[lr * LDH + lc + 8 * i] = ra[i]; *(u4v*)&Wn[(256 + lr) * LDH + lc + 8 * i] = rb[i]; }
;     }
;     if (kt + 2 < nk) {
; #pragma unroll
;       for (int i = 0; i < 4; ++i) { ra[i] = *(const u4v*)(AP_ + 8 * i); rb[i] = *(const u4v*)(BP_ + 8 * i); }
;       ao += 64; bo += 64;
;     }
; #pragma unroll
;     for (int ks = 0; ks < 4; ++ks) {
;       h8v af[4], bf[2];
; #pragma unroll
;       for (int i = 0; i < 4; ++i) af[i] = *(const h8v*)&As[(wm * 128 + i * 32 + (lane & 31)) * LDH + ks * 16 + 8 * (lane >> 5)];
; #pragma unroll
;       for (int j = 0; j < 2; ++j) bf[j] = *(const h8v*)&Bs[(wn * 64 + j * 32 + (lane & 31)) * LDH + ks * 16 + 8 * (lane >> 5)];
; #pragma unroll
;       for (int i = 0; i < 4; ++i)
; #pragma unroll
;         for (int j = 0; j < 2; ++j) acc[i][j] = mfma32(bf[j], af[i], acc[i][j]);
;     }
;     __syncthreads();
;   }
	ds_read_b128 v[232:235], v212
	ds_read_b128 v[188:191], v194
	ds_read_b128 v[236:239], v212 offset:4608
	ds_read_b128 v[200:203], v194 offset:4608
	ds_read_b128 v[204:207], v194 offset:9216
	ds_read_b128 v[208:211], v194 offset:13824
	v_mfma_f32_32x32x16_f16 v[114:129], v[240:243], v[216:219], v[114:129]
	v_mfma_f32_32x32x16_f16 v[98:113], v[244:247], v[216:219], v[98:113]
	v_mfma_f32_32x32x16_f16 v[82:97], v[240:243], v[220:223], v[82:97]
	v_mfma_f32_32x32x16_f16 v[66:81], v[244:247], v[220:223], v[66:81]
	v_mfma_f32_32x32x16_f16 v[50:65], v[240:243], v[224:227], v[50:65]
	v_mfma_f32_32x32x16_f16 v[34:49], v[244:247], v[224:227], v[34:49]
	v_mfma_f32_32x32x16_f16 v[18:33], v[240:243], v[228:231], v[18:33]
	v_mfma_f32_32x32x16_f16 v[2:17], v[244:247], v[228:231], v[2:17]
	ds_read_b128 v[240:243], v212 offset:32
	ds_read_b128 v[216:219], v194 offset:32
	ds_read_b128 v[244:247], v212 offset:4640
	ds_read_b128 v[220:223], v194 offset:4640
	ds_read_b128 v[224:227], v194 offset:9248
	ds_read_b128 v[228:231], v194 offset:13856
	s_waitcnt vmcnt(4)
	ds_write_b128 v175, v[130:133]
	ds_write_b128 v175, v[134:137] offset:16
	ds_write_b128 v175, v[138:141] offset:32
	ds_write_b128 v175, v[142:145] offset:48
	global_load_dwordx4 v[130:133], v[164:165], off offset:2048
	global_load_dwordx4 v[134:137], v[164:165], off offset:2064
	global_load_dwordx4 v[138:141], v[164:165], off offset:2080
	global_load_dwordx4 v[142:145], v[164:165], off offset:2096
	s_waitcnt lgkmcnt(14)
	v_mfma_f32_32x32x16_f16 v[114:129], v[232:235], v[188:191], v[114:129]
	s_waitcnt lgkmcnt(13)
	v_mfma_f32_32x32x16_f16 v[98:113], v[236:239], v[188:191], v[98:113]
	s_waitcnt lgkmcnt(12)
	v_mfma_f32_32x32x16_f16 v[82:97], v[232:235], v[200:203], v[82:97]
	v_mfma_f32_32x32x16_f16 v[66:81], v[236:239], v[200:203], v[66:81]
	s_waitcnt lgkmcnt(11)
	v_mfma_f32_32x32x16_f16 v[50:65], v[232:235], v[204:207], v[50:65]
	v_mfma_f32_32x32x16_f16 v[34:49], v[236:239], v[204:207], v[34:49]
	s_waitcnt lgkmcnt(10)
	v_mfma_f32_32x32x16_f16 v[18:33], v[232:235], v[208:211], v[18:33]
	v_mfma_f32_32x32x16_f16 v[2:17], v[236:239], v[208:211], v[2:17]
	ds_read_b128 v[232:235], v212 offset:64
	ds_read_b128 v[188:191], v194 offset:64
	ds_read_b128 v[236:239], v212 offset:4672
	ds_read_b128 v[200:203], v194 offset:4672
	ds_read_b128 v[204:207], v194 offset:9280
	ds_read_b128 v[208:211], v194 offset:13888
	s_waitcnt vmcnt(4)
	ds_write_b128 v175, v[146:149] offset:36864
	ds_write_b128 v175, v[150:153] offset:36880
	ds_write_b128 v175, v[154:157] offset:36896
	ds_write_b128 v175, v[158:161] offset:36912
	global_load_dwordx4 v[146:149], v[192:193], off offset:2048
	global_load_dwordx4 v[150:153], v[192:193], off offset:2064
	global_load_dwordx4 v[154:157], v[192:193], off offset:2080
	global_load_dwordx4 v[158:161], v[192:193], off offset:2096
	s_waitcnt lgkmcnt(15)
	v_mfma_f32_32x32x16_f16 v[114:129], v[240:243], v[216:219], v[114:129]
	s_waitcnt lgkmcnt(15)
	v_mfma_f32_32x32x16_f16 v[98:113], v[244:247], v[216:219], v[98:113]
	s_waitcnt lgkmcnt(15)
	v_mfma_f32_32x32x16_f16 v[82:97], v[240:243], v[220:223], v[82:97]
	v_mfma_f32_32x32x16_f16 v[66:81], v[244:247], v[220:223], v[66:81]
	s_waitcnt lgkmcnt(15)
	v_mfma_f32_32x32x16_f16 v[50:65], v[240:243], v[224:227], v[50:65]
	v_mfma_f32_32x32x16_f16 v[34:49], v[244:247], v[224:227], v[34:49]
	s_waitcnt lgkmcnt(14)
	v_mfma_f32_32x32x16_f16 v[18:33], v[240:243], v[228:231], v[18:33]
	v_mfma_f32_32x32x16_f16 v[2:17], v[244:247], v[228:231], v[2:17]
	ds_read_b128 v[240:243], v212 offset:96
	ds_read_b128 v[216:219], v194 offset:96
	ds_read_b128 v[244:247], v212 offset:4704
	ds_read_b128 v[220:223], v194 offset:4704
	ds_read_b128 v[224:227], v194 offset:9312
	ds_read_b128 v[228:231], v194 offset:13920
	s_waitcnt lgkmcnt(14)
	v_mfma_f32_32x32x16_f16 v[114:129], v[232:235], v[188:191], v[114:129]
	s_waitcnt lgkmcnt(13)
	v_mfma_f32_32x32x16_f16 v[98:113], v[236:239], v[188:191], v[98:113]
	s_waitcnt lgkmcnt(12)
	v_mfma_f32_32x32x16_f16 v[82:97], v[232:235], v[200:203], v[82:97]
	v_mfma_f32_32x32x16_f16 v[66:81], v[236:239], v[200:203], v[66:81]
	s_waitcnt lgkmcnt(11)
	v_mfma_f32_32x32x16_f16 v[50:65], v[232:235], v[204:207], v[50:65]
	v_mfma_f32_32x32x16_f16 v[34:49], v[236:239], v[204:207], v[34:49]
	s_waitcnt lgkmcnt(10)
	v_mfma_f32_32x32x16_f16 v[18:33], v[232:235], v[208:211], v[18:33]
	v_mfma_f32_32x32x16_f16 v[2:17], v[236:239], v[208:211], v[2:17]
	s_waitcnt lgkmcnt(0)
	s_barrier
; DI f16v mfma32(h8v a, h8v b, f16v c) { return __builtin_amdgcn_mfma_f32_32x32x16_f16(a, b, c, 0, 0, 0); }
; template <bool GATHER>
; DI void gemm256_main(const h16* __restrict__ A, int lda, const int* __restrict__ idx, int m0,
;                      const h16* __restrict__ B, int ldb, int n0, int K, h16* lds, f16v (&acc)[4][2]) {
;     ...
;   for (int kt = 0; kt < nk; ++kt) {
;     const h16* As = lds + (kt & 1) * (512 * LDH);
;     const h16* Bs = As + 256 * LDH;
;     h16* Wn = lds + ((kt & 1) ^ 1) * (512 * LDH);
;     if (kt + 1 < nk) {
; #pragma unroll
;       for (int i = 0; i < 4; ++i) { *(u4v*)&Wn[lr * LDH + lc + 8 * i] = ra[i]; *(u4v*)&Wn[(256 + lr) * LDH + lc + 8 * i] = rb[i]; }
;     }
;     if (kt + 2 < nk) {
; #pragma unroll
;       for (int i = 0; i < 4; ++i) { ra[i] = *(const u4v*)(AP_ + 8 * i); rb[i] = *(const u4v*)(BP_ + 8 * i); }
;       ao += 64; bo += 64;
;     }
; #pragma unroll
;     for (int ks = 0; ks < 4; ++ks) {
;       h8v af[4], bf[2];
; #pragma unroll
;       for (int i = 0; i < 4; ++i) af[i] = *(const h8v*)&As[(wm * 128 + i * 32 + (lane & 31)) * LDH + ks * 16 + 8 * (lane >> 5)];
; #pragma unroll
;       for (int j = 0; j < 2; ++j) bf[j] = *(const h8v*)&Bs[(wn * 64 + j * 32 + (lane & 31)) * LDH + ks * 16 + 8 * (lane >> 5)];
; #pragma unroll
;       for (int i = 0; i < 4; ++i)
; #pragma unroll
;         for (int j = 0; j < 2; ++j) acc[i][j] = mfma32(bf[j], af[i], acc[i][j]);
;     }
;     __syncthreads();
;   }
	ds_read_b128 v[232:235], v213
	ds_read_b128 v[188:191], v199
	ds_read_b128 v[236:239], v213 offset:4608
	ds_read_b128 v[200:203], v199 offset:4608
	ds_read_b128 v[204:207], v199 offset:9216
	ds_read_b128 v[208:211], v199 offset:13824
	v_mfma_f32_32x32x16_f16 v[114:129], v[240:243], v[216:219], v[114:129]
	v_mfma_f32_32x32x16_f16 v[98:113], v[244:247], v[216:219], v[98:113]
	v_mfma_f32_32x32x16_f16 v[82:97], v[240:243], v[220:223], v[82:97]
	v_mfma_f32_32x32x16_f16 v[66:81], v[244:247], v[220:223], v[66:81]
	v_mfma_f32_32x32x16_f16 v[50:65], v[240:243], v[224:227], v[50:65]
	v_mfma_f32_32x32x16_f16 v[34:49], v[244:247], v[224:227], v[34:49]
	v_mfma_f32_32x32x16_f16 v[18:33], v[240:243], v[228:231], v[18:33]
	v_mfma_f32_32x32x16_f16 v[2:17], v[244:247], v[228:231], v[2:17]
	ds_read_b128 v[240:243], v213 offset:32
	ds_read_b128 v[216:219], v199 offset:32
	ds_read_b128 v[244:247], v213 offset:4640
	ds_read_b128 v[220:223], v199 offset:4640
	ds_read_b128 v[224:227], v199 offset:9248
	ds_read_b128 v[228:231], v199 offset:13856
	s_waitcnt vmcnt(4)
	ds_write_b128 v163, v[130:133]
	ds_write_b128 v163, v[134:137] offset:16
	ds_write_b128 v163, v[138:141] offset:32
	ds_write_b128 v163, v[142:145] offset:48
	global_load_dwordx4 v[130:133], v[164:165], off offset:2176
	global_load_dwordx4 v[134:137], v[164:165], off offset:2192
	global_load_dwordx4 v[138:141], v[164:165], off offset:2208
	global_load_dwordx4 v[142:145], v[164:165], off offset:2224
	s_waitcnt lgkmcnt(14)
	v_mfma_f32_32x32x16_f16 v[114:129], v[232:235], v[188:191], v[114:129]
	s_waitcnt lgkmcnt(13)
	v_mfma_f32_32x32x16_f16 v[98:113], v[236:239], v[188:191], v[98:113]
	s_waitcnt lgkmcnt(12)
	v_mfma_f32_32x32x16_f16 v[82:97], v[232:235], v[200:203], v[82:97]
	v_mfma_f32_32x32x16_f16 v[66:81], v[236:239], v[200:203], v[66:81]
	s_waitcnt lgkmcnt(11)
	v_mfma_f32_32x32x16_f16 v[50:65], v[232:235], v[204:207], v[50:65]
	v_mfma_f32_32x32x16_f16 v[34:49], v[236:239], v[204:207], v[34:49]
	s_waitcnt lgkmcnt(10)
	v_mfma_f32_32x32x16_f16 v[18:33], v[232:235], v[208:211], v[18:33]
	v_mfma_f32_32x32x16_f16 v[2:17], v[236:239], v[208:211], v[2:17]
	ds_read_b128 v[232:235], v213 offset:64
	ds_read_b128 v[188:191], v199 offset:64
	ds_read_b128 v[236:239], v213 offset:4672
	ds_read_b128 v[200:203], v199 offset:4672
	ds_read_b128 v[204:207], v199 offset:9280
	ds_read_b128 v[208:211], v199 offset:13888
	s_waitcnt vmcnt(4)
	ds_write_b128 v163, v[146:149] offset:36864
	ds_write_b128 v163, v[150:153] offset:36880
	ds_write_b128 v163, v[154:157] offset:36896
	ds_write_b128 v163, v[158:161] offset:36912
	global_load_dwordx4 v[146:149], v[192:193], off offset:2176
	global_load_dwordx4 v[150:153], v[192:193], off offset:2192
	global_load_dwordx4 v[154:157], v[192:193], off offset:2208
	global_load_dwordx4 v[158:161], v[192:193], off offset:2224
	s_waitcnt lgkmcnt(15)
	v_mfma_f32_32x32x16_f16 v[114:129], v[240:243], v[216:219], v[114:129]
	s_waitcnt lgkmcnt(15)
	v_mfma_f32_32x32x16_f16 v[98:113], v[244:247], v[216:219], v[98:113]
	s_waitcnt lgkmcnt(15)
	v_mfma_f32_32x32x16_f16 v[82:97], v[240:243], v[220:223], v[82:97]
	v_mfma_f32_32x32x16_f16 v[66:81], v[244:247], v[220:223], v[66:81]
	s_waitcnt lgkmcnt(15)
	v_mfma_f32_32x32x16_f16 v[50:65], v[240:243], v[224:227], v[50:65]
	v_mfma_f32_32x32x16_f16 v[34:49], v[244:247], v[224:227], v[34:49]
	s_waitcnt lgkmcnt(14)
	v_mfma_f32_32x32x16_f16 v[18:33], v[240:243], v[228:231], v[18:33]
	v_mfma_f32_32x32x16_f16 v[2:17], v[244:247], v[228:231], v[2:17]
	ds_read_b128 v[240:243], v213 offset:96
	ds_read_b128 v[216:219], v199 offset:96
	ds_read_b128 v[244:247], v213 offset:4704
	ds_read_b128 v[220:223], v199 offset:4704
	ds_read_b128 v[224:227], v199 offset:9312
	ds_read_b128 v[228:231], v199 offset:13920
	s_waitcnt lgkmcnt(14)
	v_mfma_f32_32x32x16_f16 v[114:129], v[232:235], v[188:191], v[114:129]
	s_waitcnt lgkmcnt(13)
	v_mfma_f32_32x32x16_f16 v[98:113], v[236:239], v[188:191], v[98:113]
	s_waitcnt lgkmcnt(12)
	v_mfma_f32_32x32x16_f16 v[82:97], v[232:235], v[200:203], v[82:97]
	v_mfma_f32_32x32x16_f16 v[66:81], v[236:239], v[200:203], v[66:81]
	s_waitcnt lgkmcnt(11)
	v_mfma_f32_32x32x16_f16 v[50:65], v[232:235], v[204:207], v[50:65]
	v_mfma_f32_32x32x16_f16 v[34:49], v[236:239], v[204:207], v[34:49]
	s_waitcnt lgkmcnt(10)
	v_mfma_f32_32x32x16_f16 v[18:33], v[232:235], v[208:211], v[18:33]
	v_mfma_f32_32x32x16_f16 v[2:17], v[236:239], v[208:211], v[2:17]
	s_waitcnt lgkmcnt(0)
	s_barrier
; DI f16v mfma32(h8v a, h8v b, f16v c) { return __builtin_amdgcn_mfma_f32_32x32x16_f16(a, b, c, 0, 0, 0); }
; template <bool GATHER>
; DI void gemm256_main(const h16* __restrict__ A, int lda, const int* __restrict__ idx, int m0,
;                      const h16* __restrict__ B, int ldb, int n0, int K, h16* lds, f16v (&acc)[4][2]) {
;     ...
;   for (int kt = 0; kt < nk; ++kt) {
;     const h16* As = lds + (kt & 1) * (512 * LDH);
;     const h16* Bs = As + 256 * LDH;
;     h16* Wn = lds + ((kt & 1) ^ 1) * (512 * LDH);
;     if (kt + 1 < nk) {
; #pragma unroll
;       for (int i = 0; i < 4; ++i) { *(u4v*)&Wn[lr * LDH + lc + 8 * i] = ra[i]; *(u4v*)&Wn[(256 + lr) * LDH + lc + 8 * i] = rb[i]; }
;     }
;     if (kt + 2 < nk) {
; #pragma unroll
;       for (int i = 0; i < 4; ++i) { ra[i] = *(const u4v*)(AP_ + 8 * i); rb[i] = *(const u4v*)(BP_ + 8 * i); }
;       ao += 64; bo += 64;
;     }
; #pragma unroll
;     for (int ks = 0; ks < 4; ++ks) {
;       h8v af[4], bf[2];
; #pragma unroll
;       for (int i = 0; i < 4; ++i) af[i] = *(const h8v*)&As[(wm * 128 + i * 32 + (lane & 31)) * LDH + ks * 16 + 8 * (lane >> 5)];
; #pragma unroll
;       for (int j = 0; j < 2; ++j) bf[j] = *(const h8v*)&Bs[(wn * 64 + j * 32 + (lane & 31)) * LDH + ks * 16 + 8 * (lane >> 5)];
; #pragma unroll
;       for (int i = 0; i < 4; ++i)
; #pragma unroll
;         for (int j = 0; j < 2; ++j) acc[i][j] = mfma32(bf[j], af[i], acc[i][j]);
;     }
;     __syncthreads();
;   }
	ds_read_b128 v[232:235], v212
	ds_read_b128 v[188:191], v194
	ds_read_b128 v[236:239], v212 offset:4608
	ds_read_b128 v[200:203], v194 offset:4608
	ds_read_b128 v[204:207], v194 offset:9216
	ds_read_b128 v[208:211], v194 offset:13824
	v_mfma_f32_32x32x16_f16 v[114:129], v[240:243], v[216:219], v[114:129]
	v_mfma_f32_32x32x16_f16 v[98:113], v[244:247], v[216:219], v[98:113]
	v_mfma_f32_32x32x16_f16 v[82:97], v[240:243], v[220:223], v[82:97]
	v_mfma_f32_32x32x16_f16 v[66:81], v[244:247], v[220:223], v[66:81]
	v_mfma_f32_32x32x16_f16 v[50:65], v[240:243], v[224:227], v[50:65]
	v_mfma_f32_32x32x16_f16 v[34:49], v[244:247], v[224:227], v[34:49]
	v_mfma_f32_32x32x16_f16 v[18:33], v[240:243], v[228:231], v[18:33]
	v_mfma_f32_32x32x16_f16 v[2:17], v[244:247], v[228:231], v[2:17]
	ds_read_b128 v[240:243], v212 offset:32
	ds_read_b128 v[216:219], v194 offset:32
	ds_read_b128 v[244:247], v212 offset:4640
	ds_read_b128 v[220:223], v194 offset:4640
	ds_read_b128 v[224:227], v194 offset:9248
	ds_read_b128 v[228:231], v194 offset:13856
	s_waitcnt vmcnt(4)
	ds_write_b128 v175, v[130:133]
	ds_write_b128 v175, v[134:137] offset:16
	ds_write_b128 v175, v[138:141] offset:32
	ds_write_b128 v175, v[142:145] offset:48
	global_load_dwordx4 v[130:133], v[164:165], off offset:2304
	global_load_dwordx4 v[134:137], v[164:165], off offset:2320
	global_load_dwordx4 v[138:141], v[164:165], off offset:2336
	global_load_dwordx4 v[142:145], v[164:165], off offset:2352
	s_waitcnt lgkmcnt(14)
	v_mfma_f32_32x32x16_f16 v[114:129], v[232:235], v[188:191], v[114:129]
	s_waitcnt lgkmcnt(13)
	v_mfma_f32_32x32x16_f16 v[98:113], v[236:239], v[188:191], v[98:113]
	s_waitcnt lgkmcnt(12)
	v_mfma_f32_32x32x16_f16 v[82:97], v[232:235], v[200:203], v[82:97]
	v_mfma_f32_32x32x16_f16 v[66:81], v[236:239], v[200:203], v[66:81]
	s_waitcnt lgkmcnt(11)
	v_mfma_f32_32x32x16_f16 v[50:65], v[232:235], v[204:207], v[50:65]
	v_mfma_f32_32x32x16_f16 v[34:49], v[236:239], v[204:207], v[34:49]
	s_waitcnt lgkmcnt(10)
	v_mfma_f32_32x32x16_f16 v[18:33], v[232:235], v[208:211], v[18:33]
	v_mfma_f32_32x32x16_f16 v[2:17], v[236:239], v[208:211], v[2:17]
	ds_read_b128 v[232:235], v212 offset:64
	ds_read_b128 v[188:191], v194 offset:64
	ds_read_b128 v[236:239], v212 offset:4672
	ds_read_b128 v[200:203], v194 offset:4672
	ds_read_b128 v[204:207], v194 offset:9280
	ds_read_b128 v[208:211], v194 offset:13888
	s_waitcnt vmcnt(4)
	ds_write_b128 v175, v[146:149] offset:36864
	ds_write_b128 v175, v[150:153] offset:36880
	ds_write_b128 v175, v[154:157] offset:36896
	ds_write_b128 v175, v[158:161] offset:36912
	global_load_dwordx4 v[146:149], v[192:193], off offset:2304
	global_load_dwordx4 v[150:153], v[192:193], off offset:2320
	global_load_dwordx4 v[154:157], v[192:193], off offset:2336
	global_load_dwordx4 v[158:161], v[192:193], off offset:2352
	s_waitcnt lgkmcnt(15)
	v_mfma_f32_32x32x16_f16 v[114:129], v[240:243], v[216:219], v[114:129]
	s_waitcnt lgkmcnt(15)
	v_mfma_f32_32x32x16_f16 v[98:113], v[244:247], v[216:219], v[98:113]
	s_waitcnt lgkmcnt(15)
	v_mfma_f32_32x32x16_f16 v[82:97], v[240:243], v[220:223], v[82:97]
	v_mfma_f32_32x32x16_f16 v[66:81], v[244:247], v[220:223], v[66:81]
	s_waitcnt lgkmcnt(15)
	v_mfma_f32_32x32x16_f16 v[50:65], v[240:243], v[224:227], v[50:65]
	v_mfma_f32_32x32x16_f16 v[34:49], v[244:247], v[224:227], v[34:49]
	s_waitcnt lgkmcnt(14)
	v_mfma_f32_32x32x16_f16 v[18:33], v[240:243], v[228:231], v[18:33]
	v_mfma_f32_32x32x16_f16 v[2:17], v[244:247], v[228:231], v[2:17]
	ds_read_b128 v[240:243], v212 offset:96
	ds_read_b128 v[216:219], v194 offset:96
	ds_read_b128 v[244:247], v212 offset:4704
	ds_read_b128 v[220:223], v194 offset:4704
	ds_read_b128 v[224:227], v194 offset:9312
	ds_read_b128 v[228:231], v194 offset:13920
	s_waitcnt lgkmcnt(14)
	v_mfma_f32_32x32x16_f16 v[114:129], v[232:235], v[188:191], v[114:129]
	s_waitcnt lgkmcnt(13)
	v_mfma_f32_32x32x16_f16 v[98:113], v[236:239], v[188:191], v[98:113]
	s_waitcnt lgkmcnt(12)
	v_mfma_f32_32x32x16_f16 v[82:97], v[232:235], v[200:203], v[82:97]
	v_mfma_f32_32x32x16_f16 v[66:81], v[236:239], v[200:203], v[66:81]
	s_waitcnt lgkmcnt(11)
	v_mfma_f32_32x32x16_f16 v[50:65], v[232:235], v[204:207], v[50:65]
	v_mfma_f32_32x32x16_f16 v[34:49], v[236:239], v[204:207], v[34:49]
	s_waitcnt lgkmcnt(10)
	v_mfma_f32_32x32x16_f16 v[18:33], v[232:235], v[208:211], v[18:33]
	v_mfma_f32_32x32x16_f16 v[2:17], v[236:239], v[208:211], v[2:17]
	s_waitcnt lgkmcnt(0)
	s_barrier
; DI f16v mfma32(h8v a, h8v b, f16v c) { return __builtin_amdgcn_mfma_f32_32x32x16_f16(a, b, c, 0, 0, 0); }
; template <bool GATHER>
; DI void gemm256_main(const h16* __restrict__ A, int lda, const int* __restrict__ idx, int m0,
;                      const h16* __restrict__ B, int ldb, int n0, int K, h16* lds, f16v (&acc)[4][2]) {
;     ...
;   for (int kt = 0; kt < nk; ++kt) {
;     const h16* As = lds + (kt & 1) * (512 * LDH);
;     const h16* Bs = As + 256 * LDH;
;     h16* Wn = lds + ((kt & 1) ^ 1) * (512 * LDH);
;     if (kt + 1 < nk) {
; #pragma unroll
;       for (int i = 0; i < 4; ++i) { *(u4v*)&Wn[lr * LDH + lc + 8 * i] = ra[i]; *(u4v*)&Wn[(256 + lr) * LDH + lc + 8 * i] = rb[i]; }
;     }
;     if (kt + 2 < nk) {
; #pragma unroll
;       for (int i = 0; i < 4; ++i) { ra[i] = *(const u4v*)(AP_ + 8 * i); rb[i] = *(const u4v*)(BP_ + 8 * i); }
;       ao += 64; bo += 64;
;     }
; #pragma unroll
;     for (int ks = 0; ks < 4; ++ks) {
;       h8v af[4], bf[2];
; #pragma unroll
;       for (int i = 0; i < 4; ++i) af[i] = *(const h8v*)&As[(wm * 128 + i * 32 + (lane & 31)) * LDH + ks * 16 + 8 * (lane >> 5)];
; #pragma unroll
;       for (int j = 0; j < 2; ++j) bf[j] = *(const h8v*)&Bs[(wn * 64 + j * 32 + (lane & 31)) * LDH + ks * 16 + 8 * (lane >> 5)];
; #pragma unroll
;       for (int i = 0; i < 4; ++i)
; #pragma unroll
;         for (int j = 0; j < 2; ++j) acc[i][j] = mfma32(bf[j], af[i], acc[i][j]);
;     }
;     __syncthreads();
;   }
	ds_read_b128 v[232:235], v213
	ds_read_b128 v[188:191], v199
	ds_read_b128 v[236:239], v213 offset:4608
	ds_read_b128 v[200:203], v199 offset:4608
	ds_read_b128 v[204:207], v199 offset:9216
	ds_read_b128 v[208:211], v199 offset:13824
	v_mfma_f32_32x32x16_f16 v[114:129], v[240:243], v[216:219], v[114:129]
	v_mfma_f32_32x32x16_f16 v[98:113], v[244:247], v[216:219], v[98:113]
	v_mfma_f32_32x32x16_f16 v[82:97], v[240:243], v[220:223], v[82:97]
	v_mfma_f32_32x32x16_f16 v[66:81], v[244:247], v[220:223], v[66:81]
	v_mfma_f32_32x32x16_f16 v[50:65], v[240:243], v[224:227], v[50:65]
	v_mfma_f32_32x32x16_f16 v[34:49], v[244:247], v[224:227], v[34:49]
	v_mfma_f32_32x32x16_f16 v[18:33], v[240:243], v[228:231], v[18:33]
	v_mfma_f32_32x32x16_f16 v[2:17], v[244:247], v[228:231], v[2:17]
	ds_read_b128 v[240:243], v213 offset:32
	ds_read_b128 v[216:219], v199 offset:32
	ds_read_b128 v[244:247], v213 offset:4640
	ds_read_b128 v[220:223], v199 offset:4640
	ds_read_b128 v[224:227], v199 offset:9248
	ds_read_b128 v[228:231], v199 offset:13856
	s_waitcnt vmcnt(4)
	ds_write_b128 v163, v[130:133]
	ds_write_b128 v163, v[134:137] offset:16
	ds_write_b128 v163, v[138:141] offset:32
	ds_write_b128 v163, v[142:145] offset:48
	global_load_dwordx4 v[130:133], v[164:165], off offset:2432
	global_load_dwordx4 v[134:137], v[164:165], off offset:2448
	global_load_dwordx4 v[138:141], v[164:165], off offset:2464
	global_load_dwordx4 v[142:145], v[164:165], off offset:2480
	s_waitcnt lgkmcnt(14)
	v_mfma_f32_32x32x16_f16 v[114:129], v[232:235], v[188:191], v[114:129]
	s_waitcnt lgkmcnt(13)
	v_mfma_f32_32x32x16_f16 v[98:113], v[236:239], v[188:191], v[98:113]
	s_waitcnt lgkmcnt(12)
	v_mfma_f32_32x32x16_f16 v[82:97], v[232:235], v[200:203], v[82:97]
	v_mfma_f32_32x32x16_f16 v[66:81], v[236:239], v[200:203], v[66:81]
	s_waitcnt lgkmcnt(11)
	v_mfma_f32_32x32x16_f16 v[50:65], v[232:235], v[204:207], v[50:65]
	v_mfma_f32_32x32x16_f16 v[34:49], v[236:239], v[204:207], v[34:49]
	s_waitcnt lgkmcnt(10)
	v_mfma_f32_32x32x16_f16 v[18:33], v[232:235], v[208:211], v[18:33]
	v_mfma_f32_32x32x16_f16 v[2:17], v[236:239], v[208:211], v[2:17]
	ds_read_b128 v[232:235], v213 offset:64
	ds_read_b128 v[188:191], v199 offset:64
	ds_read_b128 v[236:239], v213 offset:4672
	ds_read_b128 v[200:203], v199 offset:4672
	ds_read_b128 v[204:207], v199 offset:9280
	ds_read_b128 v[208:211], v199 offset:13888
	s_waitcnt vmcnt(4)
	ds_write_b128 v163, v[146:149] offset:36864
	ds_write_b128 v163, v[150:153] offset:36880
	ds_write_b128 v163, v[154:157] offset:36896
	ds_write_b128 v163, v[158:161] offset:36912
	global_load_dwordx4 v[146:149], v[192:193], off offset:2432
	global_load_dwordx4 v[150:153], v[192:193], off offset:2448
	global_load_dwordx4 v[154:157], v[192:193], off offset:2464
	global_load_dwordx4 v[158:161], v[192:193], off offset:2480
	s_waitcnt lgkmcnt(15)
	v_mfma_f32_32x32x16_f16 v[114:129], v[240:243], v[216:219], v[114:129]
	s_waitcnt lgkmcnt(15)
	v_mfma_f32_32x32x16_f16 v[98:113], v[244:247], v[216:219], v[98:113]
	s_waitcnt lgkmcnt(15)
	v_mfma_f32_32x32x16_f16 v[82:97], v[240:243], v[220:223], v[82:97]
	v_mfma_f32_32x32x16_f16 v[66:81], v[244:247], v[220:223], v[66:81]
	s_waitcnt lgkmcnt(15)
	v_mfma_f32_32x32x16_f16 v[50:65], v[240:243], v[224:227], v[50:65]
	v_mfma_f32_32x32x16_f16 v[34:49], v[244:247], v[224:227], v[34:49]
	s_waitcnt lgkmcnt(14)
	v_mfma_f32_32x32x16_f16 v[18:33], v[240:243], v[228:231], v[18:33]
	v_mfma_f32_32x32x16_f16 v[2:17], v[244:247], v[228:231], v[2:17]
	ds_read_b128 v[240:243], v213 offset:96
	ds_read_b128 v[216:219], v199 offset:96
	ds_read_b128 v[244:247], v213 offset:4704
	ds_read_b128 v[220:223], v199 offset:4704
	ds_read_b128 v[224:227], v199 offset:9312
	ds_read_b128 v[228:231], v199 offset:13920
	s_waitcnt lgkmcnt(14)
	v_mfma_f32_32x32x16_f16 v[114:129], v[232:235], v[188:191], v[114:129]
	s_waitcnt lgkmcnt(13)
	v_mfma_f32_32x32x16_f16 v[98:113], v[236:239], v[188:191], v[98:113]
	s_waitcnt lgkmcnt(12)
	v_mfma_f32_32x32x16_f16 v[82:97], v[232:235], v[200:203], v[82:97]
	v_mfma_f32_32x32x16_f16 v[66:81], v[236:239], v[200:203], v[66:81]
	s_waitcnt lgkmcnt(11)
	v_mfma_f32_32x32x16_f16 v[50:65], v[232:235], v[204:207], v[50:65]
	v_mfma_f32_32x32x16_f16 v[34:49], v[236:239], v[204:207], v[34:49]
	s_waitcnt lgkmcnt(10)
	v_mfma_f32_32x32x16_f16 v[18:33], v[232:235], v[208:211], v[18:33]
	v_mfma_f32_32x32x16_f16 v[2:17], v[236:239], v[208:211], v[2:17]
	s_waitcnt lgkmcnt(0)
	s_barrier
; DI f16v mfma32(h8v a, h8v b, f16v c) { return __builtin_amdgcn_mfma_f32_32x32x16_f16(a, b, c, 0, 0, 0); }
; template <bool GATHER>
; DI void gemm256_main(const h16* __restrict__ A, int lda, const int* __restrict__ idx, int m0,
;                      const h16* __restrict__ B, int ldb, int n0, int K, h16* lds, f16v (&acc)[4][2]) {
;     ...
;   for (int kt = 0; kt < nk; ++kt) {
;     const h16* As = lds + (kt & 1) * (512 * LDH);
;     const h16* Bs = As + 256 * LDH;
;     h16* Wn = lds + ((kt & 1) ^ 1) * (512 * LDH);
;     if (kt + 1 < nk) {
; #pragma unroll
;       for (int i = 0; i < 4; ++i) { *(u4v*)&Wn[lr * LDH + lc + 8 * i] = ra[i]; *(u4v*)&Wn[(256 + lr) * LDH + lc + 8 * i] = rb[i]; }
;     }
;     if (kt + 2 < nk) {
; #pragma unroll
;       for (int i = 0; i < 4; ++i) { ra[i] = *(const u4v*)(AP_ + 8 * i); rb[i] = *(const u4v*)(BP_ + 8 * i); }
;       ao += 64; bo += 64;
;     }
; #pragma unroll
;     for (int ks = 0; ks < 4; ++ks) {
;       h8v af[4], bf[2];
; #pragma unroll
;       for (int i = 0; i < 4; ++i) af[i] = *(const h8v*)&As[(wm * 128 + i * 32 + (lane & 31)) * LDH + ks * 16 + 8 * (lane >> 5)];
; #pragma unroll
;       for (int j = 0; j < 2; ++j) bf[j] = *(const h8v*)&Bs[(wn * 64 + j * 32 + (lane & 31)) * LDH + ks * 16 + 8 * (lane >> 5)];
; #pragma unroll
;       for (int i = 0; i < 4; ++i)
; #pragma unroll
;         for (int j = 0; j < 2; ++j) acc[i][j] = mfma32(bf[j], af[i], acc[i][j]);
;     }
;     __syncthreads();
;   }
	ds_read_b128 v[232:235], v212
	ds_read_b128 v[188:191], v194
	ds_read_b128 v[236:239], v212 offset:4608
	ds_read_b128 v[200:203], v194 offset:4608
	ds_read_b128 v[204:207], v194 offset:9216
	ds_read_b128 v[208:211], v194 offset:13824
	v_mfma_f32_32x32x16_f16 v[114:129], v[240:243], v[216:219], v[114:129]
	v_mfma_f32_32x32x16_f16 v[98:113], v[244:247], v[216:219], v[98:113]
	v_mfma_f32_32x32x16_f16 v[82:97], v[240:243], v[220:223], v[82:97]
	v_mfma_f32_32x32x16_f16 v[66:81], v[244:247], v[220:223], v[66:81]
	v_mfma_f32_32x32x16_f16 v[50:65], v[240:243], v[224:227], v[50:65]
	v_mfma_f32_32x32x16_f16 v[34:49], v[244:247], v[224:227], v[34:49]
	v_mfma_f32_32x32x16_f16 v[18:33], v[240:243], v[228:231], v[18:33]
	v_mfma_f32_32x32x16_f16 v[2:17], v[244:247], v[228:231], v[2:17]
	ds_read_b128 v[240:243], v212 offset:32
	ds_read_b128 v[216:219], v194 offset:32
	ds_read_b128 v[244:247], v212 offset:4640
	ds_read_b128 v[220:223], v194 offset:4640
	ds_read_b128 v[224:227], v194 offset:9248
	ds_read_b128 v[228:231], v194 offset:13856
	s_waitcnt vmcnt(4)
	ds_write_b128 v175, v[130:133]
	ds_write_b128 v175, v[134:137] offset:16
	ds_write_b128 v175, v[138:141] offset:32
	ds_write_b128 v175, v[142:145] offset:48
	global_load_dwordx4 v[130:133], v[164:165], off offset:2560
	global_load_dwordx4 v[134:137], v[164:165], off offset:2576
	global_load_dwordx4 v[138:141], v[164:165], off offset:2592
	global_load_dwordx4 v[142:145], v[164:165], off offset:2608
	s_waitcnt lgkmcnt(14)
	v_mfma_f32_32x32x16_f16 v[114:129], v[232:235], v[188:191], v[114:129]
	s_waitcnt lgkmcnt(13)
	v_mfma_f32_32x32x16_f16 v[98:113], v[236:239], v[188:191], v[98:113]
	s_waitcnt lgkmcnt(12)
	v_mfma_f32_32x32x16_f16 v[82:97], v[232:235], v[200:203], v[82:97]
	v_mfma_f32_32x32x16_f16 v[66:81], v[236:239], v[200:203], v[66:81]
	s_waitcnt lgkmcnt(11)
	v_mfma_f32_32x32x16_f16 v[50:65], v[232:235], v[204:207], v[50:65]
	v_mfma_f32_32x32x16_f16 v[34:49], v[236:239], v[204:207], v[34:49]
	s_waitcnt lgkmcnt(10)
	v_mfma_f32_32x32x16_f16 v[18:33], v[232:235], v[208:211], v[18:33]
	v_mfma_f32_32x32x16_f16 v[2:17], v[236:239], v[208:211], v[2:17]
	ds_read_b128 v[232:235], v212 offset:64
	ds_read_b128 v[188:191], v194 offset:64
	ds_read_b128 v[236:239], v212 offset:4672
	ds_read_b128 v[200:203], v194 offset:4672
	ds_read_b128 v[204:207], v194 offset:9280
	ds_read_b128 v[208:211], v194 offset:13888
	s_waitcnt vmcnt(4)
	ds_write_b128 v175, v[146:149] offset:36864
	ds_write_b128 v175, v[150:153] offset:36880
	ds_write_b128 v175, v[154:157] offset:36896
	ds_write_b128 v175, v[158:161] offset:36912
	global_load_dwordx4 v[146:149], v[192:193], off offset:2560
	global_load_dwordx4 v[150:153], v[192:193], off offset:2576
	global_load_dwordx4 v[154:157], v[192:193], off offset:2592
	global_load_dwordx4 v[158:161], v[192:193], off offset:2608
	s_waitcnt lgkmcnt(15)
	v_mfma_f32_32x32x16_f16 v[114:129], v[240:243], v[216:219], v[114:129]
	s_waitcnt lgkmcnt(15)
	v_mfma_f32_32x32x16_f16 v[98:113], v[244:247], v[216:219], v[98:113]
	s_waitcnt lgkmcnt(15)
	v_mfma_f32_32x32x16_f16 v[82:97], v[240:243], v[220:223], v[82:97]
	v_mfma_f32_32x32x16_f16 v[66:81], v[244:247], v[220:223], v[66:81]
	s_waitcnt lgkmcnt(15)
	v_mfma_f32_32x32x16_f16 v[50:65], v[240:243], v[224:227], v[50:65]
	v_mfma_f32_32x32x16_f16 v[34:49], v[244:247], v[224:227], v[34:49]
	s_waitcnt lgkmcnt(14)
	v_mfma_f32_32x32x16_f16 v[18:33], v[240:243], v[228:231], v[18:33]
	v_mfma_f32_32x32x16_f16 v[2:17], v[244:247], v[228:231], v[2:17]
	ds_read_b128 v[240:243], v212 offset:96
	ds_read_b128 v[216:219], v194 offset:96
	ds_read_b128 v[244:247], v212 offset:4704
	ds_read_b128 v[220:223], v194 offset:4704
	ds_read_b128 v[224:227], v194 offset:9312
	ds_read_b128 v[228:231], v194 offset:13920
	s_waitcnt lgkmcnt(14)
	v_mfma_f32_32x32x16_f16 v[114:129], v[232:235], v[188:191], v[114:129]
	s_waitcnt lgkmcnt(13)
	v_mfma_f32_32x32x16_f16 v[98:113], v[236:239], v[188:191], v[98:113]
	s_waitcnt lgkmcnt(12)
	v_mfma_f32_32x32x16_f16 v[82:97], v[232:235], v[200:203], v[82:97]
	v_mfma_f32_32x32x16_f16 v[66:81], v[236:239], v[200:203], v[66:81]
	s_waitcnt lgkmcnt(11)
	v_mfma_f32_32x32x16_f16 v[50:65], v[232:235], v[204:207], v[50:65]
	v_mfma_f32_32x32x16_f16 v[34:49], v[236:239], v[204:207], v[34:49]
	s_waitcnt lgkmcnt(10)
	v_mfma_f32_32x32x16_f16 v[18:33], v[232:235], v[208:211], v[18:33]
	v_mfma_f32_32x32x16_f16 v[2:17], v[236:239], v[208:211], v[2:17]
	s_waitcnt lgkmcnt(0)
	s_barrier
; DI f16v mfma32(h8v a, h8v b, f16v c) { return __builtin_amdgcn_mfma_f32_32x32x16_f16(a, b, c, 0, 0, 0); }
; template <bool GATHER>
; DI void gemm256_main(const h16* __restrict__ A, int lda, const int* __restrict__ idx, int m0,
;                      const h16* __restrict__ B, int ldb, int n0, int K, h16* lds, f16v (&acc)[4][2]) {
;     ...
;   for (int kt = 0; kt < nk; ++kt) {
;     const h16* As = lds + (kt & 1) * (512 * LDH);
;     const h16* Bs = As + 256 * LDH;
;     h16* Wn = lds + ((kt & 1) ^ 1) * (512 * LDH);
;     if (kt + 1 < nk) {
; #pragma unroll
;       for (int i = 0; i < 4; ++i) { *(u4v*)&Wn[lr * LDH + lc + 8 * i] = ra[i]; *(u4v*)&Wn[(256 + lr) * LDH + lc + 8 * i] = rb[i]; }
;     }
;     if (kt + 2 < nk) {
; #pragma unroll
;       for (int i = 0; i < 4; ++i) { ra[i] = *(const u4v*)(AP_ + 8 * i); rb[i] = *(const u4v*)(BP_ + 8 * i); }
;       ao += 64; bo += 64;
;     }
; #pragma unroll
;     for (int ks = 0; ks < 4; ++ks) {
;       h8v af[4], bf[2];
; #pragma unroll
;       for (int i = 0; i < 4; ++i) af[i] = *(const h8v*)&As[(wm * 128 + i * 32 + (lane & 31)) * LDH + ks * 16 + 8 * (lane >> 5)];
; #pragma unroll
;       for (int j = 0; j < 2; ++j) bf[j] = *(const h8v*)&Bs[(wn * 64 + j * 32 + (lane & 31)) * LDH + ks * 16 + 8 * (lane >> 5)];
; #pragma unroll
;       for (int i = 0; i < 4; ++i)
; #pragma unroll
;         for (int j = 0; j < 2; ++j) acc[i][j] = mfma32(bf[j], af[i], acc[i][j]);
;     }
;     __syncthreads();
;   }
	ds_read_b128 v[232:235], v213
	ds_read_b128 v[188:191], v199
	ds_read_b128 v[236:239], v213 offset:4608
	ds_read_b128 v[200:203], v199 offset:4608
	ds_read_b128 v[204:207], v199 offset:9216
	ds_read_b128 v[208:211], v199 offset:13824
	v_mfma_f32_32x32x16_f16 v[114:129], v[240:243], v[216:219], v[114:129]
	v_mfma_f32_32x32x16_f16 v[98:113], v[244:247], v[216:219], v[98:113]
	v_mfma_f32_32x32x16_f16 v[82:97], v[240:243], v[220:223], v[82:97]
	v_mfma_f32_32x32x16_f16 v[66:81], v[244:247], v[220:223], v[66:81]
	v_mfma_f32_32x32x16_f16 v[50:65], v[240:243], v[224:227], v[50:65]
	v_mfma_f32_32x32x16_f16 v[34:49], v[244:247], v[224:227], v[34:49]
	v_mfma_f32_32x32x16_f16 v[18:33], v[240:243], v[228:231], v[18:33]
	v_mfma_f32_32x32x16_f16 v[2:17], v[244:247], v[228:231], v[2:17]
	ds_read_b128 v[240:243], v213 offset:32
	ds_read_b128 v[216:219], v199 offset:32
	ds_read_b128 v[244:247], v213 offset:4640
	ds_read_b128 v[220:223], v199 offset:4640
	ds_read_b128 v[224:227], v199 offset:9248
	ds_read_b128 v[228:231], v199 offset:13856
	s_waitcnt vmcnt(4)
	ds_write_b128 v163, v[130:133]
	ds_write_b128 v163, v[134:137] offset:16
	ds_write_b128 v163, v[138:141] offset:32
	ds_write_b128 v163, v[142:145] offset:48
	global_load_dwordx4 v[130:133], v[164:165], off offset:2688
	global_load_dwordx4 v[134:137], v[164:165], off offset:2704
	global_load_dwordx4 v[138:141], v[164:165], off offset:2720
	global_load_dwordx4 v[142:145], v[164:165], off offset:2736
	s_waitcnt lgkmcnt(14)
	v_mfma_f32_32x32x16_f16 v[114:129], v[232:235], v[188:191], v[114:129]
	s_waitcnt lgkmcnt(13)
	v_mfma_f32_32x32x16_f16 v[98:113], v[236:239], v[188:191], v[98:113]
	s_waitcnt lgkmcnt(12)
	v_mfma_f32_32x32x16_f16 v[82:97], v[232:235], v[200:203], v[82:97]
	v_mfma_f32_32x32x16_f16 v[66:81], v[236:239], v[200:203], v[66:81]
	s_waitcnt lgkmcnt(11)
	v_mfma_f32_32x32x16_f16 v[50:65], v[232:235], v[204:207], v[50:65]
	v_mfma_f32_32x32x16_f16 v[34:49], v[236:239], v[204:207], v[34:49]
	s_waitcnt lgkmcnt(10)
	v_mfma_f32_32x32x16_f16 v[18:33], v[232:235], v[208:211], v[18:33]
	v_mfma_f32_32x32x16_f16 v[2:17], v[236:239], v[208:211], v[2:17]
	ds_read_b128 v[232:235], v213 offset:64
	ds_read_b128 v[188:191], v199 offset:64
	ds_read_b128 v[236:239], v213 offset:4672
	ds_read_b128 v[200:203], v199 offset:4672
	ds_read_b128 v[204:207], v199 offset:9280
	ds_read_b128 v[208:211], v199 offset:13888
	s_waitcnt vmcnt(4)
	ds_write_b128 v163, v[146:149] offset:36864
	ds_write_b128 v163, v[150:153] offset:36880
	ds_write_b128 v163, v[154:157] offset:36896
	ds_write_b128 v163, v[158:161] offset:36912
	global_load_dwordx4 v[146:149], v[192:193], off offset:2688
	global_load_dwordx4 v[150:153], v[192:193], off offset:2704
	global_load_dwordx4 v[154:157], v[192:193], off offset:2720
	global_load_dwordx4 v[158:161], v[192:193], off offset:2736
	s_waitcnt lgkmcnt(15)
	v_mfma_f32_32x32x16_f16 v[114:129], v[240:243], v[216:219], v[114:129]
	s_waitcnt lgkmcnt(15)
	v_mfma_f32_32x32x16_f16 v[98:113], v[244:247], v[216:219], v[98:113]
	s_waitcnt lgkmcnt(15)
	v_mfma_f32_32x32x16_f16 v[82:97], v[240:243], v[220:223], v[82:97]
	v_mfma_f32_32x32x16_f16 v[66:81], v[244:247], v[220:223], v[66:81]
	s_waitcnt lgkmcnt(15)
	v_mfma_f32_32x32x16_f16 v[50:65], v[240:243], v[224:227], v[50:65]
	v_mfma_f32_32x32x16_f16 v[34:49], v[244:247], v[224:227], v[34:49]
	s_waitcnt lgkmcnt(14)
	v_mfma_f32_32x32x16_f16 v[18:33], v[240:243], v[228:231], v[18:33]
	v_mfma_f32_32x32x16_f16 v[2:17], v[244:247], v[228:231], v[2:17]
	ds_read_b128 v[240:243], v213 offset:96
	ds_read_b128 v[216:219], v199 offset:96
	ds_read_b128 v[244:247], v213 offset:4704
	ds_read_b128 v[220:223], v199 offset:4704
	ds_read_b128 v[224:227], v199 offset:9312
	ds_read_b128 v[228:231], v199 offset:13920
	s_waitcnt lgkmcnt(14)
	v_mfma_f32_32x32x16_f16 v[114:129], v[232:235], v[188:191], v[114:129]
	s_waitcnt lgkmcnt(13)
	v_mfma_f32_32x32x16_f16 v[98:113], v[236:239], v[188:191], v[98:113]
	s_waitcnt lgkmcnt(12)
	v_mfma_f32_32x32x16_f16 v[82:97], v[232:235], v[200:203], v[82:97]
	v_mfma_f32_32x32x16_f16 v[66:81], v[236:239], v[200:203], v[66:81]
	s_waitcnt lgkmcnt(11)
	v_mfma_f32_32x32x16_f16 v[50:65], v[232:235], v[204:207], v[50:65]
	v_mfma_f32_32x32x16_f16 v[34:49], v[236:239], v[204:207], v[34:49]
	s_waitcnt lgkmcnt(10)
	v_mfma_f32_32x32x16_f16 v[18:33], v[232:235], v[208:211], v[18:33]
	v_mfma_f32_32x32x16_f16 v[2:17], v[236:239], v[208:211], v[2:17]
	s_waitcnt lgkmcnt(0)
	s_barrier
; DI f16v mfma32(h8v a, h8v b, f16v c) { return __builtin_amdgcn_mfma_f32_32x32x16_f16(a, b, c, 0, 0, 0); }
; template <bool GATHER>
; DI void gemm256_main(const h16* __restrict__ A, int lda, const int* __restrict__ idx, int m0,
;                      const h16* __restrict__ B, int ldb, int n0, int K, h16* lds, f16v (&acc)[4][2]) {
;     ...
;   for (int kt = 0; kt < nk; ++kt) {
;     const h16* As = lds + (kt & 1) * (512 * LDH);
;     const h16* Bs = As + 256 * LDH;
;     h16* Wn = lds + ((kt & 1) ^ 1) * (512 * LDH);
;     if (kt + 1 < nk) {
; #pragma unroll
;       for (int i = 0; i < 4; ++i) { *(u4v*)&Wn[lr * LDH + lc + 8 * i] = ra[i]; *(u4v*)&Wn[(256 + lr) * LDH + lc + 8 * i] = rb[i]; }
;     }
;     if (kt + 2 < nk) {
; #pragma unroll
;       for (int i = 0; i < 4; ++i) { ra[i] = *(const u4v*)(AP_ + 8 * i); rb[i] = *(const u4v*)(BP_ + 8 * i); }
;       ao += 64; bo += 64;
;     }
; #pragma unroll
;     for (int ks = 0; ks < 4; ++ks) {
;       h8v af[4], bf[2];
; #pragma unroll
;       for (int i = 0; i < 4; ++i) af[i] = *(const h8v*)&As[(wm * 128 + i * 32 + (lane & 31)) * LDH + ks * 16 + 8 * (lane >> 5)];
; #pragma unroll
;       for (int j = 0; j < 2; ++j) bf[j] = *(const h8v*)&Bs[(wn * 64 + j * 32 + (lane & 31)) * LDH + ks * 16 + 8 * (lane >> 5)];
; #pragma unroll
;       for (int i = 0; i < 4; ++i)
; #pragma unroll
;         for (int j = 0; j < 2; ++j) acc[i][j] = mfma32(bf[j], af[i], acc[i][j]);
;     }
;     __syncthreads();
;   }
	ds_read_b128 v[232:235], v212
	ds_read_b128 v[188:191], v194
	ds_read_b128 v[236:239], v212 offset:4608
	ds_read_b128 v[200:203], v194 offset:4608
	ds_read_b128 v[204:207], v194 offset:9216
	ds_read_b128 v[208:211], v194 offset:13824
	v_mfma_f32_32x32x16_f16 v[114:129], v[240:243], v[216:219], v[114:129]
	v_mfma_f32_32x32x16_f16 v[98:113], v[244:247], v[216:219], v[98:113]
	v_mfma_f32_32x32x16_f16 v[82:97], v[240:243], v[220:223], v[82:97]
	v_mfma_f32_32x32x16_f16 v[66:81], v[244:247], v[220:223], v[66:81]
	v_mfma_f32_32x32x16_f16 v[50:65], v[240:243], v[224:227], v[50:65]
	v_mfma_f32_32x32x16_f16 v[34:49], v[244:247], v[224:227], v[34:49]
	v_mfma_f32_32x32x16_f16 v[18:33], v[240:243], v[228:231], v[18:33]
	v_mfma_f32_32x32x16_f16 v[2:17], v[244:247], v[228:231], v[2:17]
	ds_read_b128 v[240:243], v212 offset:32
	ds_read_b128 v[216:219], v194 offset:32
	ds_read_b128 v[244:247], v212 offset:4640
	ds_read_b128 v[220:223], v194 offset:4640
	ds_read_b128 v[224:227], v194 offset:9248
	ds_read_b128 v[228:231], v194 offset:13856
	s_waitcnt vmcnt(4)
	ds_write_b128 v175, v[130:133]
	ds_write_b128 v175, v[134:137] offset:16
	ds_write_b128 v175, v[138:141] offset:32
	ds_write_b128 v175, v[142:145] offset:48
	s_waitcnt lgkmcnt(14)
	v_mfma_f32_32x32x16_f16 v[114:129], v[232:235], v[188:191], v[114:129]
	s_waitcnt lgkmcnt(13)
	v_mfma_f32_32x32x16_f16 v[98:113], v[236:239], v[188:191], v[98:113]
	s_waitcnt lgkmcnt(12)
	v_mfma_f32_32x32x16_f16 v[82:97], v[232:235], v[200:203], v[82:97]
	v_mfma_f32_32x32x16_f16 v[66:81], v[236:239], v[200:203], v[66:81]
	s_waitcnt lgkmcnt(11)
	v_mfma_f32_32x32x16_f16 v[50:65], v[232:235], v[204:207], v[50:65]
	v_mfma_f32_32x32x16_f16 v[34:49], v[236:239], v[204:207], v[34:49]
	s_waitcnt lgkmcnt(10)
	v_mfma_f32_32x32x16_f16 v[18:33], v[232:235], v[208:211], v[18:33]
	v_mfma_f32_32x32x16_f16 v[2:17], v[236:239], v[208:211], v[2:17]
	ds_read_b128 v[232:235], v212 offset:64
	ds_read_b128 v[188:191], v194 offset:64
	ds_read_b128 v[236:239], v212 offset:4672
	ds_read_b128 v[200:203], v194 offset:4672
	ds_read_b128 v[204:207], v194 offset:9280
	ds_read_b128 v[208:211], v194 offset:13888
	s_waitcnt vmcnt(0)
	ds_write_b128 v175, v[146:149] offset:36864
	ds_write_b128 v175, v[150:153] offset:36880
	ds_write_b128 v175, v[154:157] offset:36896
	ds_write_b128 v175, v[158:161] offset:36912
	s_waitcnt lgkmcnt(15)
	v_mfma_f32_32x32x16_f16 v[114:129], v[240:243], v[216:219], v[114:129]
	s_waitcnt lgkmcnt(15)
	v_mfma_f32_32x32x16_f16 v[98:113], v[244:247], v[216:219], v[98:113]
	s_waitcnt lgkmcnt(15)
	v_mfma_f32_32x32x16_f16 v[82:97], v[240:243], v[220:223], v[82:97]
	v_mfma_f32_32x32x16_f16 v[66:81], v[244:247], v[220:223], v[66:81]
	s_waitcnt lgkmcnt(15)
	v_mfma_f32_32x32x16_f16 v[50:65], v[240:243], v[224:227], v[50:65]
	v_mfma_f32_32x32x16_f16 v[34:49], v[244:247], v[224:227], v[34:49]
	s_waitcnt lgkmcnt(14)
	v_mfma_f32_32x32x16_f16 v[18:33], v[240:243], v[228:231], v[18:33]
	v_mfma_f32_32x32x16_f16 v[2:17], v[244:247], v[228:231], v[2:17]
	ds_read_b128 v[240:243], v212 offset:96
	ds_read_b128 v[216:219], v194 offset:96
	ds_read_b128 v[244:247], v212 offset:4704
	ds_read_b128 v[220:223], v194 offset:4704
	ds_read_b128 v[224:227], v194 offset:9312
	ds_read_b128 v[228:231], v194 offset:13920
	s_waitcnt lgkmcnt(14)
	v_mfma_f32_32x32x16_f16 v[114:129], v[232:235], v[188:191], v[114:129]
	s_waitcnt lgkmcnt(13)
	v_mfma_f32_32x32x16_f16 v[98:113], v[236:239], v[188:191], v[98:113]
	s_waitcnt lgkmcnt(12)
	v_mfma_f32_32x32x16_f16 v[82:97], v[232:235], v[200:203], v[82:97]
	v_mfma_f32_32x32x16_f16 v[66:81], v[236:239], v[200:203], v[66:81]
	s_waitcnt lgkmcnt(11)
	v_mfma_f32_32x32x16_f16 v[50:65], v[232:235], v[204:207], v[50:65]
	v_mfma_f32_32x32x16_f16 v[34:49], v[236:239], v[204:207], v[34:49]
	s_waitcnt lgkmcnt(10)
	v_mfma_f32_32x32x16_f16 v[18:33], v[232:235], v[208:211], v[18:33]
	v_mfma_f32_32x32x16_f16 v[2:17], v[236:239], v[208:211], v[2:17]
	s_waitcnt lgkmcnt(0)
	s_barrier
	ds_read_b128 v[232:235], v213
	ds_read_b128 v[188:191], v199
	ds_read_b128 v[236:239], v213 offset:4608
	ds_read_b128 v[200:203], v199 offset:4608
	ds_read_b128 v[204:207], v199 offset:9216
	ds_read_b128 v[208:211], v199 offset:13824
	v_mfma_f32_32x32x16_f16 v[114:129], v[240:243], v[216:219], v[114:129]
	v_mfma_f32_32x32x16_f16 v[98:113], v[244:247], v[216:219], v[98:113]
	v_mfma_f32_32x32x16_f16 v[82:97], v[240:243], v[220:223], v[82:97]
	v_mfma_f32_32x32x16_f16 v[66:81], v[244:247], v[220:223], v[66:81]
	v_mfma_f32_32x32x16_f16 v[50:65], v[240:243], v[224:227], v[50:65]
	v_mfma_f32_32x32x16_f16 v[34:49], v[244:247], v[224:227], v[34:49]
	v_mfma_f32_32x32x16_f16 v[18:33], v[240:243], v[228:231], v[18:33]
	v_mfma_f32_32x32x16_f16 v[2:17], v[244:247], v[228:231], v[2:17]
	ds_read_b128 v[240:243], v213 offset:32
	ds_read_b128 v[216:219], v199 offset:32
	ds_read_b128 v[244:247], v213 offset:4640
	ds_read_b128 v[220:223], v199 offset:4640
	ds_read_b128 v[224:227], v199 offset:9248
	ds_read_b128 v[228:231], v199 offset:13856
	s_waitcnt lgkmcnt(10)
	v_mfma_f32_32x32x16_f16 v[114:129], v[232:235], v[188:191], v[114:129]
	s_waitcnt lgkmcnt(9)
	v_mfma_f32_32x32x16_f16 v[98:113], v[236:239], v[188:191], v[98:113]
	s_waitcnt lgkmcnt(8)
	v_mfma_f32_32x32x16_f16 v[82:97], v[232:235], v[200:203], v[82:97]
	v_mfma_f32_32x32x16_f16 v[66:81], v[236:239], v[200:203], v[66:81]
	s_waitcnt lgkmcnt(7)
	v_mfma_f32_32x32x16_f16 v[50:65], v[232:235], v[204:207], v[50:65]
	v_mfma_f32_32x32x16_f16 v[34:49], v[236:239], v[204:207], v[34:49]
	s_waitcnt lgkmcnt(6)
; DI f16v mfma32(h8v a, h8v b, f16v c) { return __builtin_amdgcn_mfma_f32_32x32x16_f16(a, b, c, 0, 0, 0); }
; template <bool GATHER>
; DI void gemm256_main(const h16* __restrict__ A, int lda, const int* __restrict__ idx, int m0,
;                      const h16* __restrict__ B, int ldb, int n0, int K, h16* lds, f16v (&acc)[4][2]) {
;     ...
; #pragma unroll
;     for (int ks = 0; ks < 4; ++ks) {
;       h8v af[4], bf[2];
; #pragma unroll
;       for (int i = 0; i < 4; ++i) af[i] = *(const h8v*)&As[(wm * 128 + i * 32 + (lane & 31)) * LDH + ks * 16 + 8 * (lane >> 5)];
; #pragma unroll
;       for (int j = 0; j < 2; ++j) bf[j] = *(const h8v*)&Bs[(wn * 64 + j * 32 + (lane & 31)) * LDH + ks * 16 + 8 * (lane >> 5)];
; #pragma unroll
;       for (int i = 0; i < 4; ++i)
; #pragma unroll
;         for (int j = 0; j < 2; ++j) acc[i][j] = mfma32(bf[j], af[i], acc[i][j]);
;     }
; DI void phase_ffn2_moe(const Params& p, int bid, int nb, h16* lds) {
;     ...
;     gemm256_epilogue(acc, m0, n0, [&](int m, int n, f4v v0, f4v v1) {
;       const float g = sg[m];
;       st_h4(&YB[(size_t)m * DM + n], g * v0); st_h4(&YB[(size_t)m * DM + n + 32], g * v1);
;     });
	v_mfma_f32_32x32x16_f16 v[18:33], v[232:235], v[208:211], v[18:33]
	v_mfma_f32_32x32x16_f16 v[2:17], v[236:239], v[208:211], v[2:17]
	ds_read_b128 v[232:235], v213 offset:64
	ds_read_b128 v[188:191], v199 offset:64
	ds_read_b128 v[236:239], v213 offset:4672
	ds_read_b128 v[200:203], v199 offset:4672
	ds_read_b128 v[204:207], v199 offset:9280
	ds_read_b128 v[208:211], v199 offset:13888
	s_waitcnt lgkmcnt(10)
	v_mfma_f32_32x32x16_f16 v[114:129], v[240:243], v[216:219], v[114:129]
	s_waitcnt lgkmcnt(9)
	v_mfma_f32_32x32x16_f16 v[98:113], v[244:247], v[216:219], v[98:113]
	s_waitcnt lgkmcnt(8)
	v_mfma_f32_32x32x16_f16 v[82:97], v[240:243], v[220:223], v[82:97]
	v_mfma_f32_32x32x16_f16 v[66:81], v[244:247], v[220:223], v[66:81]
	s_waitcnt lgkmcnt(7)
	v_mfma_f32_32x32x16_f16 v[50:65], v[240:243], v[224:227], v[50:65]
	v_mfma_f32_32x32x16_f16 v[34:49], v[244:247], v[224:227], v[34:49]
	s_waitcnt lgkmcnt(6)
	v_mfma_f32_32x32x16_f16 v[18:33], v[240:243], v[228:231], v[18:33]
	v_mfma_f32_32x32x16_f16 v[2:17], v[244:247], v[228:231], v[2:17]
	ds_read_b128 v[240:243], v213 offset:96
	ds_read_b128 v[216:219], v199 offset:96
	ds_read_b128 v[244:247], v213 offset:4704
	ds_read_b128 v[220:223], v199 offset:4704
	ds_read_b128 v[224:227], v199 offset:9312
	ds_read_b128 v[228:231], v199 offset:13920
	s_waitcnt lgkmcnt(10)
	v_mfma_f32_32x32x16_f16 v[114:129], v[232:235], v[188:191], v[114:129]
	s_waitcnt lgkmcnt(9)
	v_mfma_f32_32x32x16_f16 v[98:113], v[236:239], v[188:191], v[98:113]
	s_waitcnt lgkmcnt(8)
	v_mfma_f32_32x32x16_f16 v[82:97], v[232:235], v[200:203], v[82:97]
	v_mfma_f32_32x32x16_f16 v[66:81], v[236:239], v[200:203], v[66:81]
	s_waitcnt lgkmcnt(7)
	v_mfma_f32_32x32x16_f16 v[50:65], v[232:235], v[204:207], v[50:65]
	v_mfma_f32_32x32x16_f16 v[34:49], v[236:239], v[204:207], v[34:49]
	s_waitcnt lgkmcnt(6)
	v_mfma_f32_32x32x16_f16 v[18:33], v[232:235], v[208:211], v[18:33]
	v_mfma_f32_32x32x16_f16 v[2:17], v[236:239], v[208:211], v[2:17]
	s_waitcnt lgkmcnt(0)
	v_mfma_f32_32x32x16_f16 v[114:129], v[240:243], v[216:219], v[114:129]
	v_mfma_f32_32x32x16_f16 v[98:113], v[244:247], v[216:219], v[98:113]
	v_mfma_f32_32x32x16_f16 v[82:97], v[240:243], v[220:223], v[82:97]
	v_mfma_f32_32x32x16_f16 v[66:81], v[244:247], v[220:223], v[66:81]
	v_mfma_f32_32x32x16_f16 v[50:65], v[240:243], v[224:227], v[50:65]
	v_mfma_f32_32x32x16_f16 v[34:49], v[244:247], v[224:227], v[34:49]
	v_mfma_f32_32x32x16_f16 v[18:33], v[240:243], v[228:231], v[18:33]
	v_mfma_f32_32x32x16_f16 v[2:17], v[244:247], v[228:231], v[2:17]
	s_nop 15
	v_mov_b32_e32 v188, 0x358637bd
	v_mov_b32_e32 v189, 0x3727c5ac
	v_mov_b32_e32 v190, 0x2100
	v_mov_b32_e32 v191, 0x1400
	v_mov_b32_e32 v192, 0x7f800000
	v_mov_b32_e32 v193, 0x7fc00000
	v_mov_b32_e32 v194, 0xff800000
	v_mov_b32_e32 v199, 0xf149f2ca
	v_mov_b32_e32 v204, 0x7fffec00
	v_mov_b32_e32 v205, 0xff7fc99e
	v_mov_b32_e32 v206, 0x840000
	v_mov_b32_e32 v207, 0xb00000
	v_mov_b32_e32 v208, 0xdc0000
	v_mov_b32_e32 v209, 0x1080000
	v_mov_b32_e32 v210, 0x1340000
	v_mov_b32_e32 v211, 0x420000
	v_mov_b32_e32 v212, 0x580000
	v_mov_b32_e32 v213, 0x6e0000
	v_mov_b32_e32 v214, 0x9a0000
	v_mov_b32_e32 v162, v180
	s_nop 0
	v_ashrrev_i32_e32 v163, 1, v162
	v_and_b32_e32 v163, 0xffffff80, v163
	v_and_or_b32 v164, v162, 31, s6
	v_add_u32_e32 v164, v164, v163
	v_readlane_b32 s6, v255, 4
	v_ashrrev_i32_e32 v165, 31, v164
	v_readlane_b32 s7, v255, 5
	v_and_b32_e32 v163, 0xc0, v162
	v_lshl_add_u64 v[174:175], v[164:165], 2, s[6:7]
	v_lshrrev_b32_e32 v162, 3, v162
	v_and_b32_e32 v162, 4, v162
	v_or3_b32 v215, v163, v162, s5
	v_lshlrev_b64 v[162:163], 11, v[164:165]
	global_load_dword v228, v[174:175], off
	v_lshl_add_u64 v[230:231], s[28:29], 0, v[162:163]
	v_lshlrev_b32_e32 v162, 1, v215
	v_mov_b32_e32 v163, v0
	v_lshl_add_u64 v[230:231], v[230:231], 0, v[162:163]
	s_waitcnt vmcnt(0)
	s_nop 9
	v_mul_f32_e64 v116, v116, v228
	v_mul_f32_e64 v117, v117, v228
	v_mul_f32_e64 v114, v114, v228
	v_mul_f32_e64 v115, v115, v228
	v_pk_mul_f32 v[100:101], v[100:101], v[228:229] op_sel_hi:[1,0]
	v_pk_mul_f32 v[98:99], v[98:99], v[228:229] op_sel_hi:[1,0]
	v_cvt_pk_f16_f32 v117, v116, v117
	v_cvt_pk_f16_f32 v116, v114, v115
	v_cvt_pk_f16_f32 v101, v100, v101
	v_cvt_pk_f16_f32 v100, v98, v99
	global_store_dwordx2 v[230:231], v[116:117], off
	global_store_dwordx2 v[230:231], v[100:101], off offset:64
	global_load_dword v98, v[174:175], off
	s_waitcnt vmcnt(0)
	v_mul_f32_e64 v100, v120, v98
	v_mul_f32_e64 v101, v121, v98
	v_mul_f32_e64 v114, v118, v98
	v_mul_f32_e64 v115, v119, v98
	v_cvt_pk_f16_f32 v101, v100, v101
	v_cvt_pk_f16_f32 v100, v114, v115
	global_store_dwordx2 v[230:231], v[100:101], off offset:16
	v_pk_mul_f32 v[100:101], v[104:105], v[98:99] op_sel_hi:[1,0]
	v_pk_mul_f32 v[98:99], v[102:103], v[98:99] op_sel_hi:[1,0]
	v_cvt_pk_f16_f32 v101, v100, v101
	v_cvt_pk_f16_f32 v100, v98, v99
	global_store_dwordx2 v[230:231], v[100:101], off offset:80
	global_load_dword v98, v[174:175], off
	s_waitcnt vmcnt(0)
	v_mul_f32_e64 v100, v124, v98
	v_mul_f32_e64 v101, v125, v98
	v_mul_f32_e64 v102, v122, v98
	v_mul_f32_e64 v103, v123, v98
	v_cvt_pk_f16_f32 v101, v100, v101
	v_cvt_pk_f16_f32 v100, v102, v103
	global_store_dwordx2 v[230:231], v[100:101], off offset:32
	v_pk_mul_f32 v[100:101], v[108:109], v[98:99] op_sel_hi:[1,0]
	v_pk_mul_f32 v[98:99], v[106:107], v[98:99] op_sel_hi:[1,0]
	v_cvt_pk_f16_f32 v101, v100, v101
	v_cvt_pk_f16_f32 v100, v98, v99
	global_store_dwordx2 v[230:231], v[100:101], off offset:96
	global_load_dword v98, v[174:175], off
	s_waitcnt vmcnt(0)
; template <class Epi>
; DI void gemm256_epilogue(f16v (&acc)[4][2], int m0, int n0, Epi epi) {
;     ...
;   for (int i = 0; i < 4; ++i) {
;     const int m = m0 + wm * 128 + i * 32 + (lane & 31);
; #pragma unroll
;     for (int g = 0; g < 4; ++g) {
;       const int n = n0 + wn * 64 + 8 * g + 4 * h;
;       f4v v0 = {acc[i][0][4 * g], acc[i][0][4 * g + 1], acc[i][0][4 * g + 2], acc[i][0][4 * g + 3]};
;       f4v v1 = {acc[i][1][4 * g], acc[i][1][4 * g + 1], acc[i][1][4 * g + 2], acc[i][1][4 * g + 3]};
;       epi(m, n, v0, v1);
; DI void phase_ffn2_moe(const Params& p, int bid, int nb, h16* lds) {
;     ...
;     gemm256_epilogue(acc, m0, n0, [&](int m, int n, f4v v0, f4v v1) {
;       const float g = sg[m];
;       st_h4(&YB[(size_t)m * DM + n], g * v0); st_h4(&YB[(size_t)m * DM + n + 32], g * v1);
;     });
	v_mul_f32_e64 v100, v128, v98
	v_mul_f32_e64 v101, v129, v98
	v_mul_f32_e64 v102, v126, v98
	v_mul_f32_e64 v103, v127, v98
	v_cvt_pk_f16_f32 v101, v100, v101
	v_cvt_pk_f16_f32 v100, v102, v103
	global_store_dwordx2 v[230:231], v[100:101], off offset:48
	v_pk_mul_f32 v[100:101], v[112:113], v[98:99] op_sel_hi:[1,0]
	v_pk_mul_f32 v[98:99], v[110:111], v[98:99] op_sel_hi:[1,0]
	v_cvt_pk_f16_f32 v101, v100, v101
	v_cvt_pk_f16_f32 v100, v98, v99
	v_or_b32_e32 v98, 32, v164
	v_ashrrev_i32_e32 v99, 31, v98
	global_store_dwordx2 v[230:231], v[100:101], off offset:112
	v_lshl_add_u64 v[100:101], v[98:99], 2, s[6:7]
	global_load_dword v102, v[100:101], off
	v_lshlrev_b64 v[98:99], 11, v[98:99]
	v_lshl_add_u64 v[98:99], s[28:29], 0, v[98:99]
	v_lshl_add_u64 v[98:99], v[98:99], 0, v[162:163]
	s_waitcnt vmcnt(0)
	s_nop 9
	v_mul_f32_e64 v84, v84, v102
	v_mul_f32_e64 v85, v85, v102
	v_mul_f32_e64 v82, v82, v102
	v_mul_f32_e64 v83, v83, v102
	v_pk_mul_f32 v[68:69], v[68:69], v[102:103] op_sel_hi:[1,0]
	v_pk_mul_f32 v[66:67], v[66:67], v[102:103] op_sel_hi:[1,0]
	v_cvt_pk_f16_f32 v85, v84, v85
	v_cvt_pk_f16_f32 v84, v82, v83
	v_cvt_pk_f16_f32 v69, v68, v69
	v_cvt_pk_f16_f32 v68, v66, v67
	global_store_dwordx2 v[98:99], v[84:85], off
	global_store_dwordx2 v[98:99], v[68:69], off offset:64
	global_load_dword v66, v[100:101], off
	s_waitcnt vmcnt(0)
	v_mul_f32_e64 v68, v88, v66
	v_mul_f32_e64 v69, v89, v66
	v_mul_f32_e64 v82, v86, v66
	v_mul_f32_e64 v83, v87, v66
	v_pk_mul_f32 v[72:73], v[72:73], v[66:67] op_sel_hi:[1,0]
	v_pk_mul_f32 v[66:67], v[70:71], v[66:67] op_sel_hi:[1,0]
	v_cvt_pk_f16_f32 v69, v68, v69
	v_cvt_pk_f16_f32 v68, v82, v83
	v_cvt_pk_f16_f32 v71, v72, v73
	v_cvt_pk_f16_f32 v70, v66, v67
	global_store_dwordx2 v[98:99], v[68:69], off offset:16
	global_store_dwordx2 v[98:99], v[70:71], off offset:80
	global_load_dword v66, v[100:101], off
	s_waitcnt vmcnt(0)
	v_mul_f32_e64 v68, v92, v66
	v_mul_f32_e64 v69, v93, v66
	v_mul_f32_e64 v70, v90, v66
	v_mul_f32_e64 v71, v91, v66
	v_pk_mul_f32 v[72:73], v[76:77], v[66:67] op_sel_hi:[1,0]
	v_pk_mul_f32 v[66:67], v[74:75], v[66:67] op_sel_hi:[1,0]
	v_cvt_pk_f16_f32 v69, v68, v69
	v_cvt_pk_f16_f32 v68, v70, v71
	v_cvt_pk_f16_f32 v71, v72, v73
	v_cvt_pk_f16_f32 v70, v66, v67
	global_store_dwordx2 v[98:99], v[68:69], off offset:32
	global_store_dwordx2 v[98:99], v[70:71], off offset:96
	global_load_dword v66, v[100:101], off
	v_or_b32_e32 v68, 64, v164
	v_ashrrev_i32_e32 v69, 31, v68
	v_lshl_add_u64 v[70:71], v[68:69], 2, s[6:7]
	v_lshlrev_b64 v[68:69], 11, v[68:69]
	v_lshl_add_u64 v[68:69], s[28:29], 0, v[68:69]
	v_lshl_add_u64 v[68:69], v[68:69], 0, v[162:163]
	s_waitcnt vmcnt(0)
	v_mul_f32_e64 v72, v96, v66
	v_mul_f32_e64 v73, v97, v66
	v_pk_mul_f32 v[74:75], v[94:95], v[66:67] op_sel_hi:[1,0]
	v_pk_mul_f32 v[76:77], v[80:81], v[66:67] op_sel_hi:[1,0]
	v_pk_mul_f32 v[66:67], v[78:79], v[66:67] op_sel_hi:[1,0]
	v_cvt_pk_f16_f32 v73, v72, v73
	v_cvt_pk_f16_f32 v72, v74, v75
	v_cvt_pk_f16_f32 v75, v76, v77
	v_cvt_pk_f16_f32 v74, v66, v67
	global_store_dwordx2 v[98:99], v[72:73], off offset:48
	global_store_dwordx2 v[98:99], v[74:75], off offset:112
	global_load_dword v66, v[70:71], off
	s_waitcnt vmcnt(0)
	s_nop 9
	v_mul_f32_e64 v52, v52, v66
	v_mul_f32_e64 v53, v53, v66
	v_mul_f32_e64 v50, v50, v66
	v_mul_f32_e64 v51, v51, v66
	v_pk_mul_f32 v[36:37], v[36:37], v[66:67] op_sel_hi:[1,0]
	v_pk_mul_f32 v[34:35], v[34:35], v[66:67] op_sel_hi:[1,0]
	v_cvt_pk_f16_f32 v53, v52, v53
	v_cvt_pk_f16_f32 v52, v50, v51
	v_cvt_pk_f16_f32 v37, v36, v37
	v_cvt_pk_f16_f32 v36, v34, v35
	global_store_dwordx2 v[68:69], v[52:53], off
	global_store_dwordx2 v[68:69], v[36:37], off offset:64
	global_load_dword v34, v[70:71], off
	s_waitcnt vmcnt(0)
; template <class Epi>
; DI void gemm256_epilogue(f16v (&acc)[4][2], int m0, int n0, Epi epi) {
;     ...
;   for (int i = 0; i < 4; ++i) {
;     const int m = m0 + wm * 128 + i * 32 + (lane & 31);
; #pragma unroll
;     for (int g = 0; g < 4; ++g) {
;       const int n = n0 + wn * 64 + 8 * g + 4 * h;
;       f4v v0 = {acc[i][0][4 * g], acc[i][0][4 * g + 1], acc[i][0][4 * g + 2], acc[i][0][4 * g + 3]};
;       f4v v1 = {acc[i][1][4 * g], acc[i][1][4 * g + 1], acc[i][1][4 * g + 2], acc[i][1][4 * g + 3]};
;       epi(m, n, v0, v1);
; DI void phase_ffn2_moe(const Params& p, int bid, int nb, h16* lds) {
;     ...
;     gemm256_epilogue(acc, m0, n0, [&](int m, int n, f4v v0, f4v v1) {
;       const float g = sg[m];
;       st_h4(&YB[(size_t)m * DM + n], g * v0); st_h4(&YB[(size_t)m * DM + n + 32], g * v1);
;     });
	v_mul_f32_e64 v36, v56, v34
	v_mul_f32_e64 v37, v57, v34
	v_mul_f32_e64 v50, v54, v34
	v_mul_f32_e64 v51, v55, v34
	v_pk_mul_f32 v[40:41], v[40:41], v[34:35] op_sel_hi:[1,0]
	v_pk_mul_f32 v[34:35], v[38:39], v[34:35] op_sel_hi:[1,0]
	v_cvt_pk_f16_f32 v37, v36, v37
	v_cvt_pk_f16_f32 v36, v50, v51
	v_cvt_pk_f16_f32 v39, v40, v41
	v_cvt_pk_f16_f32 v38, v34, v35
	global_store_dwordx2 v[68:69], v[36:37], off offset:16
	global_store_dwordx2 v[68:69], v[38:39], off offset:80
	global_load_dword v34, v[70:71], off
	s_waitcnt vmcnt(0)
	v_mul_f32_e64 v36, v60, v34
	v_mul_f32_e64 v37, v61, v34
	v_mul_f32_e64 v38, v58, v34
	v_mul_f32_e64 v39, v59, v34
	v_pk_mul_f32 v[40:41], v[44:45], v[34:35] op_sel_hi:[1,0]
	v_pk_mul_f32 v[34:35], v[42:43], v[34:35] op_sel_hi:[1,0]
	v_cvt_pk_f16_f32 v37, v36, v37
	v_cvt_pk_f16_f32 v36, v38, v39
	v_cvt_pk_f16_f32 v39, v40, v41
	v_cvt_pk_f16_f32 v38, v34, v35
	global_store_dwordx2 v[68:69], v[36:37], off offset:32
	global_store_dwordx2 v[68:69], v[38:39], off offset:96
	global_load_dword v34, v[70:71], off
	v_or_b32_e32 v36, 0x60, v164
	v_ashrrev_i32_e32 v37, 31, v36
	v_lshl_add_u64 v[38:39], v[36:37], 2, s[6:7]
	v_lshlrev_b64 v[36:37], 11, v[36:37]
	v_lshl_add_u64 v[36:37], s[28:29], 0, v[36:37]
	v_lshl_add_u64 v[36:37], v[36:37], 0, v[162:163]
	s_waitcnt vmcnt(0)
	v_mul_f32_e64 v40, v64, v34
	v_mul_f32_e64 v41, v65, v34
	v_pk_mul_f32 v[42:43], v[62:63], v[34:35] op_sel_hi:[1,0]
	v_pk_mul_f32 v[44:45], v[48:49], v[34:35] op_sel_hi:[1,0]
	v_pk_mul_f32 v[34:35], v[46:47], v[34:35] op_sel_hi:[1,0]
	v_cvt_pk_f16_f32 v41, v40, v41
	v_cvt_pk_f16_f32 v40, v42, v43
	v_cvt_pk_f16_f32 v43, v44, v45
	v_cvt_pk_f16_f32 v42, v34, v35
	global_store_dwordx2 v[68:69], v[40:41], off offset:48
	global_store_dwordx2 v[68:69], v[42:43], off offset:112
	global_load_dword v34, v[38:39], off
	s_waitcnt vmcnt(0)
	s_nop 9
	v_mul_f32_e64 v20, v20, v34
	v_mul_f32_e64 v21, v21, v34
	v_mul_f32_e64 v18, v18, v34
	v_mul_f32_e64 v19, v19, v34
	v_pk_mul_f32 v[4:5], v[4:5], v[34:35] op_sel_hi:[1,0]
	v_pk_mul_f32 v[2:3], v[2:3], v[34:35] op_sel_hi:[1,0]
	v_cvt_pk_f16_f32 v21, v20, v21
	v_cvt_pk_f16_f32 v20, v18, v19
	v_cvt_pk_f16_f32 v5, v4, v5
	v_cvt_pk_f16_f32 v4, v2, v3
	global_store_dwordx2 v[36:37], v[20:21], off
	global_store_dwordx2 v[36:37], v[4:5], off offset:64
	global_load_dword v2, v[38:39], off
	s_waitcnt vmcnt(0)
	v_pk_mul_f32 v[4:5], v[24:25], v[2:3] op_sel_hi:[1,0]
	v_pk_mul_f32 v[18:19], v[22:23], v[2:3] op_sel_hi:[1,0]
	v_pk_mul_f32 v[8:9], v[8:9], v[2:3] op_sel_hi:[1,0]
	v_pk_mul_f32 v[2:3], v[6:7], v[2:3] op_sel_hi:[1,0]
	v_cvt_pk_f16_f32 v5, v4, v5
	v_cvt_pk_f16_f32 v4, v18, v19
	v_cvt_pk_f16_f32 v7, v8, v9
	v_cvt_pk_f16_f32 v6, v2, v3
	global_store_dwordx2 v[36:37], v[4:5], off offset:16
	global_store_dwordx2 v[36:37], v[6:7], off offset:80
	global_load_dword v2, v[38:39], off
	s_waitcnt vmcnt(0)
	v_pk_mul_f32 v[4:5], v[28:29], v[2:3] op_sel_hi:[1,0]
	v_pk_mul_f32 v[6:7], v[26:27], v[2:3] op_sel_hi:[1,0]
	v_pk_mul_f32 v[8:9], v[12:13], v[2:3] op_sel_hi:[1,0]
	v_pk_mul_f32 v[2:3], v[10:11], v[2:3] op_sel_hi:[1,0]
	v_cvt_pk_f16_f32 v5, v4, v5
	v_cvt_pk_f16_f32 v4, v6, v7
	v_cvt_pk_f16_f32 v7, v8, v9
	v_cvt_pk_f16_f32 v6, v2, v3
	global_store_dwordx2 v[36:37], v[4:5], off offset:32
	global_store_dwordx2 v[36:37], v[6:7], off offset:96
	global_load_dword v2, v[38:39], off
	s_waitcnt vmcnt(0)
	v_pk_mul_f32 v[4:5], v[32:33], v[2:3] op_sel_hi:[1,0]
	v_pk_mul_f32 v[6:7], v[30:31], v[2:3] op_sel_hi:[1,0]
	v_pk_mul_f32 v[8:9], v[16:17], v[2:3] op_sel_hi:[1,0]
	v_pk_mul_f32 v[2:3], v[14:15], v[2:3] op_sel_hi:[1,0]
	v_cvt_pk_f16_f32 v5, v4, v5
	v_cvt_pk_f16_f32 v4, v6, v7
	v_cvt_pk_f16_f32 v7, v8, v9
	v_cvt_pk_f16_f32 v6, v2, v3
	global_store_dwordx2 v[36:37], v[4:5], off offset:48
	global_store_dwordx2 v[36:37], v[6:7], off offset:112
	s_cbranch_vccnz .LBB0_1571
